# hand-pipelined cast and final-norm loops (2 rows in flight, DPP wave sums), next-unit L2 prefetch in mixer_local, batched gdn rc loads
# speedup vs baseline: 1.0301x; 1.0300x over previous
; __device__ __forceinline__ unsigned pk2(float lo, float hi) { return pg8::cvt_pk_bf16(lo, hi); }
; __device__ __forceinline__ float wave_sum(float v) {
; #pragma unroll
;     for (int o = 1; o < 64; o <<= 1) v += __shfl_xor(v, o);
;     return v;
; __device__ __forceinline__ void cast_phase(const float* x, bf16_t* xb, float* rowsq, int gw, int ngw, int lane) {
;     asm volatile("" : "+v"(lane));
;     for (int m = gw; m < M; m += ngw) {
;         const f32x4* xr = (const f32x4*)(x + (size_t)m * D) + lane; float s = 0.f;
; #pragma unroll
;         for (int j = 0; j < 4; ++j) { const f32x4 v = __builtin_nontemporal_load(xr + 64 * j); s += (v.x * v.x + v.y * v.y) + (v.z * v.z + v.w * v.w); u32x2 p; p.x = pk2(v.x, v.y); p.y = pk2(v.z, v.w); ((u32x2*)(xb + (size_t)m * D) + lane)[64 * j] = p; }
;         s = wave_sum(s); if (lane == 0) rowsq[m] = s;
;     }
; }
.LBB0_51:
	s_waitcnt lgkmcnt(0)
	s_mov_b32 s0, 0
	s_brev_b32 s1, 1
	global_load_dwordx4 v[14:17], v[2:3], off offset:-3072 nt
	global_load_dwordx4 v[18:21], v[2:3], off offset:-2048 nt
	global_load_dwordx4 v[22:25], v[2:3], off offset:-1024 nt
	global_load_dwordx4 v[26:29], v[2:3], off nt
.Lcast_loop:
	s_add_i32 s12, s12, s64
	v_lshl_add_u64 v[2:3], v[2:3], 0, s[10:11]
	s_cmp_lt_i32 s12, 0x8000
	s_cbranch_scc0 .Lcast_lastA
	global_load_dwordx4 v[32:35], v[2:3], off offset:-3072 nt
	global_load_dwordx4 v[36:39], v[2:3], off offset:-2048 nt
	global_load_dwordx4 v[40:43], v[2:3], off offset:-1024 nt
	global_load_dwordx4 v[44:47], v[2:3], off nt
	s_waitcnt vmcnt(4)
	v_cvt_pk_bf16_f32 v48, v14, v15
	v_cvt_pk_bf16_f32 v49, v16, v17
	v_cvt_pk_bf16_f32 v50, v18, v19
	v_cvt_pk_bf16_f32 v51, v20, v21
	v_cvt_pk_bf16_f32 v52, v22, v23
	v_cvt_pk_bf16_f32 v53, v24, v25
	v_cvt_pk_bf16_f32 v54, v26, v27
	v_cvt_pk_bf16_f32 v55, v28, v29
	global_store_dwordx2 v[0:1], v[48:49], off offset:-1024
	global_store_dwordx2 v[0:1], v[50:51], off offset:-512
	global_store_dwordx2 v[0:1], v[52:53], off
	global_store_dwordx2 v[0:1], v[54:55], off offset:512
	v_mul_f32_e32 v15, v15, v15
	v_mul_f32_e32 v17, v17, v17
	v_fmac_f32_e32 v15, v14, v14
	v_fmac_f32_e32 v17, v16, v16
	v_add_f32_e32 v14, v15, v17
	v_mul_f32_e32 v19, v19, v19
	v_mul_f32_e32 v21, v21, v21
	v_fmac_f32_e32 v19, v18, v18
	v_fmac_f32_e32 v21, v20, v20
	v_add_f32_e32 v18, v19, v21
	v_mul_f32_e32 v23, v23, v23
	v_mul_f32_e32 v25, v25, v25
	v_fmac_f32_e32 v23, v22, v22
	v_fmac_f32_e32 v25, v24, v24
	v_add_f32_e32 v22, v23, v25
	v_mul_f32_e32 v27, v27, v27
	v_mul_f32_e32 v29, v29, v29
	v_fmac_f32_e32 v27, v26, v26
	v_fmac_f32_e32 v29, v28, v28
	v_add_f32_e32 v26, v27, v29
	v_add_f32_e32 v14, v14, v18
	v_add_f32_e32 v14, v14, v22
	v_add_f32_e32 v14, v14, v26
	s_nop 1
	v_add_f32_dpp v14, v14, v14 quad_perm:[1,0,3,2] row_mask:0xf bank_mask:0xf
	s_nop 1
	v_add_f32_dpp v14, v14, v14 quad_perm:[2,3,0,1] row_mask:0xf bank_mask:0xf
	s_nop 1
	v_add_f32_dpp v14, v14, v14 row_half_mirror row_mask:0xf bank_mask:0xf
	s_nop 1
	v_add_f32_dpp v14, v14, v14 row_mirror row_mask:0xf bank_mask:0xf
	s_nop 1
	v_add_f32_dpp v14, v14, v14 row_bcast:15 row_mask:0xa bank_mask:0xf
	s_nop 1
	v_add_f32_dpp v14, v14, v14 row_bcast:31 row_mask:0xc bank_mask:0xf
	s_mov_b64 exec, s[0:1]
	global_store_dword v13, v14, s[4:5]
	s_mov_b64 exec, -1
	v_lshl_add_u64 v[0:1], v[0:1], 0, s[8:9]
	s_add_u32 s4, s4, s6
	s_addc_u32 s5, s5, s7
	s_add_i32 s12, s12, s64
	v_lshl_add_u64 v[2:3], v[2:3], 0, s[10:11]
	s_cmp_lt_i32 s12, 0x8000
	s_cbranch_scc0 .Lcast_lastB
	global_load_dwordx4 v[14:17], v[2:3], off offset:-3072 nt
	global_load_dwordx4 v[18:21], v[2:3], off offset:-2048 nt
	global_load_dwordx4 v[22:25], v[2:3], off offset:-1024 nt
	global_load_dwordx4 v[26:29], v[2:3], off nt
	s_waitcnt vmcnt(4)
	v_cvt_pk_bf16_f32 v48, v32, v33
	v_cvt_pk_bf16_f32 v49, v34, v35
	v_cvt_pk_bf16_f32 v50, v36, v37
	v_cvt_pk_bf16_f32 v51, v38, v39
	v_cvt_pk_bf16_f32 v52, v40, v41
	v_cvt_pk_bf16_f32 v53, v42, v43
	v_cvt_pk_bf16_f32 v54, v44, v45
	v_cvt_pk_bf16_f32 v55, v46, v47
	global_store_dwordx2 v[0:1], v[48:49], off offset:-1024
	global_store_dwordx2 v[0:1], v[50:51], off offset:-512
	global_store_dwordx2 v[0:1], v[52:53], off
	global_store_dwordx2 v[0:1], v[54:55], off offset:512
	v_mul_f32_e32 v33, v33, v33
	v_mul_f32_e32 v35, v35, v35
	v_fmac_f32_e32 v33, v32, v32
	v_fmac_f32_e32 v35, v34, v34
	v_add_f32_e32 v32, v33, v35
	v_mul_f32_e32 v37, v37, v37
	v_mul_f32_e32 v39, v39, v39
	v_fmac_f32_e32 v37, v36, v36
	v_fmac_f32_e32 v39, v38, v38
	v_add_f32_e32 v36, v37, v39
	v_mul_f32_e32 v41, v41, v41
	v_mul_f32_e32 v43, v43, v43
	v_fmac_f32_e32 v41, v40, v40
	v_fmac_f32_e32 v43, v42, v42
	v_add_f32_e32 v40, v41, v43
	v_mul_f32_e32 v45, v45, v45
	v_mul_f32_e32 v47, v47, v47
	v_fmac_f32_e32 v45, v44, v44
	v_fmac_f32_e32 v47, v46, v46
	v_add_f32_e32 v44, v45, v47
	v_add_f32_e32 v32, v32, v36
	v_add_f32_e32 v32, v32, v40
	v_add_f32_e32 v32, v32, v44
	s_nop 1
	v_add_f32_dpp v32, v32, v32 quad_perm:[1,0,3,2] row_mask:0xf bank_mask:0xf
	s_nop 1
	v_add_f32_dpp v32, v32, v32 quad_perm:[2,3,0,1] row_mask:0xf bank_mask:0xf
	s_nop 1
	v_add_f32_dpp v32, v32, v32 row_half_mirror row_mask:0xf bank_mask:0xf
	s_nop 1
	v_add_f32_dpp v32, v32, v32 row_mirror row_mask:0xf bank_mask:0xf
	s_nop 1
	v_add_f32_dpp v32, v32, v32 row_bcast:15 row_mask:0xa bank_mask:0xf
	s_nop 1
	v_add_f32_dpp v32, v32, v32 row_bcast:31 row_mask:0xc bank_mask:0xf
	s_mov_b64 exec, s[0:1]
	global_store_dword v13, v32, s[4:5]
	s_mov_b64 exec, -1
	v_lshl_add_u64 v[0:1], v[0:1], 0, s[8:9]
	s_add_u32 s4, s4, s6
	s_addc_u32 s5, s5, s7
	s_branch .Lcast_loop
; __device__ __forceinline__ unsigned pk2(float lo, float hi) { return pg8::cvt_pk_bf16(lo, hi); }
; __device__ __forceinline__ void cast_phase(const float* x, bf16_t* xb, float* rowsq, int gw, int ngw, int lane) {
;     ...
;     for (int m = gw; m < M; m += ngw) {
;         const f32x4* xr = (const f32x4*)(x + (size_t)m * D) + lane; float s = 0.f;
; #pragma unroll
;         for (int j = 0; j < 4; ++j) { const f32x4 v = __builtin_nontemporal_load(xr + 64 * j); s += (v.x * v.x + v.y * v.y) + (v.z * v.z + v.w * v.w); u32x2 p; p.x = pk2(v.x, v.y); p.y = pk2(v.z, v.w); ((u32x2*)(xb + (size_t)m * D) + lane)[64 * j] = p; }
;         s = wave_sum(s); if (lane == 0) rowsq[m] = s;
.Lcast_lastA:
	s_waitcnt vmcnt(0)
	v_cvt_pk_bf16_f32 v48, v14, v15
	v_cvt_pk_bf16_f32 v49, v16, v17
	v_cvt_pk_bf16_f32 v50, v18, v19
	v_cvt_pk_bf16_f32 v51, v20, v21
	v_cvt_pk_bf16_f32 v52, v22, v23
	v_cvt_pk_bf16_f32 v53, v24, v25
	v_cvt_pk_bf16_f32 v54, v26, v27
	v_cvt_pk_bf16_f32 v55, v28, v29
	global_store_dwordx2 v[0:1], v[48:49], off offset:-1024
	global_store_dwordx2 v[0:1], v[50:51], off offset:-512
	global_store_dwordx2 v[0:1], v[52:53], off
	global_store_dwordx2 v[0:1], v[54:55], off offset:512
	v_mul_f32_e32 v15, v15, v15
	v_mul_f32_e32 v17, v17, v17
	v_fmac_f32_e32 v15, v14, v14
	v_fmac_f32_e32 v17, v16, v16
	v_add_f32_e32 v14, v15, v17
	v_mul_f32_e32 v19, v19, v19
	v_mul_f32_e32 v21, v21, v21
	v_fmac_f32_e32 v19, v18, v18
	v_fmac_f32_e32 v21, v20, v20
	v_add_f32_e32 v18, v19, v21
	v_mul_f32_e32 v23, v23, v23
	v_mul_f32_e32 v25, v25, v25
	v_fmac_f32_e32 v23, v22, v22
	v_fmac_f32_e32 v25, v24, v24
	v_add_f32_e32 v22, v23, v25
	v_mul_f32_e32 v27, v27, v27
	v_mul_f32_e32 v29, v29, v29
	v_fmac_f32_e32 v27, v26, v26
	v_fmac_f32_e32 v29, v28, v28
	v_add_f32_e32 v26, v27, v29
	v_add_f32_e32 v14, v14, v18
	v_add_f32_e32 v14, v14, v22
	v_add_f32_e32 v14, v14, v26
	s_nop 1
	v_add_f32_dpp v14, v14, v14 quad_perm:[1,0,3,2] row_mask:0xf bank_mask:0xf
	s_nop 1
	v_add_f32_dpp v14, v14, v14 quad_perm:[2,3,0,1] row_mask:0xf bank_mask:0xf
	s_nop 1
	v_add_f32_dpp v14, v14, v14 row_half_mirror row_mask:0xf bank_mask:0xf
	s_nop 1
	v_add_f32_dpp v14, v14, v14 row_mirror row_mask:0xf bank_mask:0xf
	s_nop 1
	v_add_f32_dpp v14, v14, v14 row_bcast:15 row_mask:0xa bank_mask:0xf
	s_nop 1
	v_add_f32_dpp v14, v14, v14 row_bcast:31 row_mask:0xc bank_mask:0xf
	s_mov_b64 exec, s[0:1]
	global_store_dword v13, v14, s[4:5]
	s_mov_b64 exec, -1
	v_lshl_add_u64 v[0:1], v[0:1], 0, s[8:9]
	s_add_u32 s4, s4, s6
	s_addc_u32 s5, s5, s7
	s_branch .LBB0_53
.Lcast_lastB:
	s_waitcnt vmcnt(0)
	v_cvt_pk_bf16_f32 v48, v32, v33
	v_cvt_pk_bf16_f32 v49, v34, v35
	v_cvt_pk_bf16_f32 v50, v36, v37
	v_cvt_pk_bf16_f32 v51, v38, v39
	v_cvt_pk_bf16_f32 v52, v40, v41
	v_cvt_pk_bf16_f32 v53, v42, v43
	v_cvt_pk_bf16_f32 v54, v44, v45
	v_cvt_pk_bf16_f32 v55, v46, v47
	global_store_dwordx2 v[0:1], v[48:49], off offset:-1024
	global_store_dwordx2 v[0:1], v[50:51], off offset:-512
	global_store_dwordx2 v[0:1], v[52:53], off
	global_store_dwordx2 v[0:1], v[54:55], off offset:512
	v_mul_f32_e32 v33, v33, v33
	v_mul_f32_e32 v35, v35, v35
	v_fmac_f32_e32 v33, v32, v32
	v_fmac_f32_e32 v35, v34, v34
	v_add_f32_e32 v32, v33, v35
	v_mul_f32_e32 v37, v37, v37
	v_mul_f32_e32 v39, v39, v39
	v_fmac_f32_e32 v37, v36, v36
	v_fmac_f32_e32 v39, v38, v38
	v_add_f32_e32 v36, v37, v39
	v_mul_f32_e32 v41, v41, v41
	v_mul_f32_e32 v43, v43, v43
	v_fmac_f32_e32 v41, v40, v40
	v_fmac_f32_e32 v43, v42, v42
	v_add_f32_e32 v40, v41, v43
	v_mul_f32_e32 v45, v45, v45
	v_mul_f32_e32 v47, v47, v47
	v_fmac_f32_e32 v45, v44, v44
	v_fmac_f32_e32 v47, v46, v46
	v_add_f32_e32 v44, v45, v47
	v_add_f32_e32 v32, v32, v36
	v_add_f32_e32 v32, v32, v40
	v_add_f32_e32 v32, v32, v44
	s_nop 1
	v_add_f32_dpp v32, v32, v32 quad_perm:[1,0,3,2] row_mask:0xf bank_mask:0xf
	s_nop 1
	v_add_f32_dpp v32, v32, v32 quad_perm:[2,3,0,1] row_mask:0xf bank_mask:0xf
	s_nop 1
	v_add_f32_dpp v32, v32, v32 row_half_mirror row_mask:0xf bank_mask:0xf
	s_nop 1
	v_add_f32_dpp v32, v32, v32 row_mirror row_mask:0xf bank_mask:0xf
	s_nop 1
	v_add_f32_dpp v32, v32, v32 row_bcast:15 row_mask:0xa bank_mask:0xf
	s_nop 1
	v_add_f32_dpp v32, v32, v32 row_bcast:31 row_mask:0xc bank_mask:0xf
	s_mov_b64 exec, s[0:1]
	global_store_dword v13, v32, s[4:5]
	s_mov_b64 exec, -1
	v_lshl_add_u64 v[0:1], v[0:1], 0, s[8:9]
	s_add_u32 s4, s4, s6
	s_addc_u32 s5, s5, s7

; __device__ __forceinline__ unsigned cvt_pk_bf16(float lo, float hi) { unsigned r; asm volatile("v_cvt_pk_bf16_f32 %0, %1, %2" : "=v"(r) : "v"(lo), "v"(hi)); return r; }
;     __device__ __forceinline__ void operator()(const f32x4 (&acc)[2][2][4][2], const Unit& u, int wr, int wc, int fr, int fq, const float (&rsv)[8]) const {
;     ...
;                 const float rs = __builtin_amdgcn_rsqf(rsv[ai * 4 + m] * (1.0f / 1024.0f) + 1e-6f);
; #pragma unroll
;                 for (int bj = 0; bj < 2; ++bj) { const int col = col0 + bj * HALF;
;                     if (col < ncols) { const f32x4 v0 = acc[ai][bj][m][0] * rs, v1 = acc[ai][bj][m][1] * rs; u32x4 w;
;                         w.x = cvt_pk_bf16(v0[0], v0[1]); w.y = cvt_pk_bf16(v0[2], v0[3]); w.z = cvt_pk_bf16(v1[0], v1[1]); w.w = cvt_pk_bf16(v1[2], v1[3]);
;                         __builtin_nontemporal_store(w, (u32x4*)(rowp + col)); } } }
.LBB0_133:
	s_waitcnt vmcnt(8)
	v_fmamk_f32 v145, v170, 0x3a800000, v225
	v_rsq_f32_e32 v150, v145
	v_lshl_or_b32 v146, s88, 8, v155
	v_mov_b64_e32 v[148:149], s[76:77]
	v_mad_i64_i32 v[148:149], s[0:1], v144, s71, v[148:149]
	v_mov_b32_e32 v151, v150
	v_cmp_gt_i32_e32 vcc, s96, v146
	v_ashrrev_i32_e32 v147, 31, v146
	s_and_saveexec_b64 s[0:1], vcc
	s_cbranch_execz .LBB0_135
	v_mov_b32_e32 v172, v150
	v_mov_b32_e32 v173, v150
	v_pk_mul_f32 v[130:131], v[150:151], v[130:131]
	v_pk_mul_f32 v[132:133], v[172:173], v[132:133]
	v_pk_mul_f32 v[172:173], v[172:173], v[128:129]
	v_pk_mul_f32 v[128:129], v[150:151], v[126:127]
	v_cvt_pk_bf16_f32 v126, v130, v131
	v_lshl_add_u64 v[130:131], v[146:147], 1, v[148:149]
	v_cvt_pk_bf16_f32 v127, v132, v133
	v_cvt_pk_bf16_f32 v128, v128, v129
	v_cvt_pk_bf16_f32 v129, v172, v173
	global_store_dwordx4 v[130:131], v[126:129], off nt

; __device__ __forceinline__ float bf2f(bf16_t b) { return __uint_as_float((unsigned)b << 16); }
; __device__ __forceinline__ void conf_unit(const Ctx& X, LAS unsigned char* lds, int b, int c, int tid, int wave, int lane, int layer) {
;     ...
;     {
;         const int ch = tid & 255, half = tid >> 8;
;         float acc[32];
; #pragma unroll
;         for (int tk = 0; tk < 32; ++tk) acc[tk] = bias;
; #pragma unroll
;         for (int rr = 0; rr < 62; ++rr) { const float g = bf2f(GL[(half * 32 + rr) * 256 + ch]);
; #pragma unroll
;             for (int tk = 0; tk < 32; ++tk) { const int k = rr - tk; if (k >= 0 && k < 31) acc[tk] += w[k] * g; } }
; __device__ __forceinline__ void mixer_local_phase(const Ctx& X, LAS unsigned char* lds, int layer, int tid, int wave, int lane) {
;     ...
;     for (int it_ = 0; it_ < nit_; ++it_) {
;         const int u = (int)blockIdx.x + (int)gridDim.x * ((it_ + (int)(blockIdx.x >> 3)) % nit_);
;         if (u >= 3584) continue;
;         asm volatile("" : "+v"(tid_h), "+v"(lane), "+v"(tid));
;         if (u < 3072) { const int mixer = u >> 10, idx = u & 1023, hp = idx & 1, cb = idx >> 1, b = cb >> 7, c = cb & 127, h = hp * 2 + hs;
.LBB0_261:
	s_or_b64 exec, exec, s[0:1]
	s_waitcnt vmcnt(0)
	v_ashrrev_i32_e32 v6, 8, v180
	v_lshlrev_b32_e32 v7, 14, v6
	v_lshlrev_b32_sdwa v8, v228, v180 dst_sel:DWORD dst_unused:UNUSED_PAD src0_sel:DWORD src1_sel:BYTE_0
	s_waitcnt lgkmcnt(0)
	s_barrier
	s_add_i32 s98, s20, 1
	s_cmp_ge_u32 s98, s70
	s_cbranch_scc1 .LpfC_done
	s_add_i32 s98, s98, s37
	s_mul_hi_u32 s99, s98, s87
	s_mul_i32 s99, s99, s70
	s_sub_i32 s98, s98, s99
	s_sub_i32 s99, s98, s70
	s_cmp_ge_u32 s98, s70
	s_cselect_b32 s98, s99, s98
	s_sub_i32 s99, s98, s70
	s_cmp_ge_u32 s98, s70
	s_cselect_b32 s98, s99, s98
	s_mul_i32 s98, s98, s18
	s_add_i32 s98, s98, s2
	v_lshrrev_b32_e32 v237, 3, v224
	v_and_b32_e32 v238, 7, v224
	s_cmpk_ge_u32 s98, 0xc00
	s_cbranch_scc1 .LpfC_conf
	s_lshr_b32 s99, s98, 10
	s_and_b32 s98, s98, 0x3ff
	s_and_b32 s100, s98, 1
	s_lshr_b32 s98, s98, 1
	s_cmp_eq_u32 s99, 2
	s_mul_i32 s99, s99, 0xc00
	s_cselect_b32 s101, 0x400, 0
	s_sub_u32 s99, s99, s101
	s_lshl_b32 s100, s100, 8
	s_add_u32 s99, s99, s100
	v_min_u32_e32 v238, 5, v238
	v_lshrrev_b32_e32 v239, 1, v238
	v_and_b32_e32 v238, 1, v238
	v_lshlrev_b32_e32 v239, 9, v239
	v_lshl_or_b32 v238, v238, 7, v239
	s_branch .LpfC_go
.LpfC_conf:
	s_sub_u32 s98, s98, 0xc00
	s_movk_i32 s99, 0x800
	v_lshlrev_b32_e32 v238, 7, v238
.LpfC_go:
	s_lshr_b32 s100, s98, 7
	s_lshl_b32 s100, s100, 13
	s_and_b32 s98, s98, 0x7f
	s_lshl_b32 s98, s98, 6
	s_add_u32 s98, s98, s100
	s_mul_i32 s98, s98, 0x1c00
	s_add_u32 s98, s98, s99
	s_add_u32 s82, s76, s98
	s_addc_u32 s83, s77, 0
	v_mad_u32_u24 v237, v237, s71, v238
	global_load_dword v236, v237, s[82:83]
.LpfC_done:
	v_add3_u32 v11, v83, v7, v8
	ds_read_u16 v7, v11
	ds_read_u16 v8, v11 offset:512
	ds_read_u16 v9, v11 offset:1024
	ds_read_u16 v10, v11 offset:1536
	ds_read_u16 v12, v11 offset:2048
	ds_read_u16 v13, v11 offset:2560
	ds_read_u16 v14, v11 offset:3072
	ds_read_u16 v15, v11 offset:3584
	s_waitcnt lgkmcnt(7)
	v_lshlrev_b32_e32 v7, 16, v7
	v_fma_f32 v7, v82, v7, v52
	s_waitcnt lgkmcnt(6)
	v_lshlrev_b32_e32 v8, 16, v8
	v_fmac_f32_e32 v7, v81, v8
	v_fma_f32 v8, v82, v8, v52
	s_waitcnt lgkmcnt(5)
	v_lshlrev_b32_e32 v9, 16, v9
	v_fmac_f32_e32 v7, v80, v9
	v_fmac_f32_e32 v8, v81, v9
	v_fma_f32 v9, v82, v9, v52
	s_waitcnt lgkmcnt(4)
	v_lshlrev_b32_e32 v10, 16, v10
	ds_read_u16 v16, v11 offset:4096
	ds_read_u16 v17, v11 offset:4608
	ds_read_u16 v18, v11 offset:5120
	ds_read_u16 v19, v11 offset:5632
	ds_read_u16 v20, v11 offset:6144
	ds_read_u16 v21, v11 offset:6656
	ds_read_u16 v22, v11 offset:7168
	ds_read_u16 v23, v11 offset:7680
	v_fmac_f32_e32 v7, v79, v10
	v_fmac_f32_e32 v8, v80, v10
	v_fmac_f32_e32 v9, v81, v10
	v_fma_f32 v10, v82, v10, v52
	s_waitcnt lgkmcnt(11)
	v_lshlrev_b32_e32 v12, 16, v12
	v_fmac_f32_e32 v7, v78, v12
	v_fmac_f32_e32 v8, v79, v12
	v_fmac_f32_e32 v9, v80, v12
	v_fmac_f32_e32 v10, v81, v12
	v_fma_f32 v12, v82, v12, v52
	s_waitcnt lgkmcnt(10)
	v_lshlrev_b32_e32 v13, 16, v13
	v_fmac_f32_e32 v7, v77, v13
	v_fmac_f32_e32 v8, v78, v13
	v_fmac_f32_e32 v9, v79, v13
	v_fmac_f32_e32 v10, v80, v13
	v_fmac_f32_e32 v12, v81, v13
	v_fma_f32 v13, v82, v13, v52
	s_waitcnt lgkmcnt(9)
	v_lshlrev_b32_e32 v14, 16, v14
	v_fmac_f32_e32 v7, v76, v14
	v_fmac_f32_e32 v8, v77, v14
	v_fmac_f32_e32 v9, v78, v14
	v_fmac_f32_e32 v10, v79, v14
	v_fmac_f32_e32 v12, v80, v14
	v_fmac_f32_e32 v13, v81, v14
	v_fma_f32 v14, v82, v14, v52
	s_waitcnt lgkmcnt(8)
	v_lshlrev_b32_e32 v15, 16, v15
	v_fmac_f32_e32 v7, v75, v15
	v_fmac_f32_e32 v8, v76, v15
	v_fmac_f32_e32 v9, v77, v15
	v_fmac_f32_e32 v10, v78, v15
	v_fmac_f32_e32 v12, v79, v15
	v_fmac_f32_e32 v13, v80, v15
	v_fmac_f32_e32 v14, v81, v15
	v_fma_f32 v15, v82, v15, v52
	s_waitcnt lgkmcnt(7)
	v_lshlrev_b32_e32 v16, 16, v16
	v_fmac_f32_e32 v7, v74, v16
	v_fmac_f32_e32 v8, v75, v16
	v_fmac_f32_e32 v9, v76, v16
	v_fmac_f32_e32 v10, v77, v16
	v_fmac_f32_e32 v12, v78, v16
	v_fmac_f32_e32 v13, v79, v16
	v_fmac_f32_e32 v14, v80, v16
	v_fmac_f32_e32 v15, v81, v16
	v_fma_f32 v16, v82, v16, v52
	s_waitcnt lgkmcnt(6)
	v_lshlrev_b32_e32 v17, 16, v17
	v_fmac_f32_e32 v7, v73, v17
	v_fmac_f32_e32 v8, v74, v17
	v_fmac_f32_e32 v9, v75, v17
	v_fmac_f32_e32 v10, v76, v17
	v_fmac_f32_e32 v12, v77, v17
	v_fmac_f32_e32 v13, v78, v17
	v_fmac_f32_e32 v14, v79, v17
	v_fmac_f32_e32 v15, v80, v17
	v_fmac_f32_e32 v16, v81, v17
	v_fma_f32 v17, v82, v17, v52
	s_waitcnt lgkmcnt(5)
	v_lshlrev_b32_e32 v18, 16, v18
	v_fmac_f32_e32 v7, v72, v18
	v_fmac_f32_e32 v8, v73, v18
	v_fmac_f32_e32 v9, v74, v18
	v_fmac_f32_e32 v10, v75, v18
	v_fmac_f32_e32 v12, v76, v18
	v_fmac_f32_e32 v13, v77, v18
	v_fmac_f32_e32 v14, v78, v18
	v_fmac_f32_e32 v15, v79, v18
	v_fmac_f32_e32 v16, v80, v18
	v_fmac_f32_e32 v17, v81, v18
	v_fma_f32 v18, v82, v18, v52
	s_waitcnt lgkmcnt(4)
	v_lshlrev_b32_e32 v19, 16, v19
	ds_read_u16 v24, v11 offset:8192
	ds_read_u16 v25, v11 offset:8704
	ds_read_u16 v26, v11 offset:9216
	ds_read_u16 v27, v11 offset:9728
	ds_read_u16 v28, v11 offset:10240
	ds_read_u16 v29, v11 offset:10752
	ds_read_u16 v30, v11 offset:11264
	ds_read_u16 v31, v11 offset:11776
	v_fmac_f32_e32 v7, v71, v19
	v_fmac_f32_e32 v8, v72, v19
	v_fmac_f32_e32 v9, v73, v19
	v_fmac_f32_e32 v10, v74, v19
	v_fmac_f32_e32 v12, v75, v19
	v_fmac_f32_e32 v13, v76, v19
	v_fmac_f32_e32 v14, v77, v19
	v_fmac_f32_e32 v15, v78, v19
	v_fmac_f32_e32 v16, v79, v19
	v_fmac_f32_e32 v17, v80, v19
	v_fmac_f32_e32 v18, v81, v19
	v_fma_f32 v19, v82, v19, v52
	s_waitcnt lgkmcnt(11)
	v_lshlrev_b32_e32 v20, 16, v20
	v_fmac_f32_e32 v7, v70, v20
	v_fmac_f32_e32 v8, v71, v20
	v_fmac_f32_e32 v9, v72, v20
	v_fmac_f32_e32 v10, v73, v20
	v_fmac_f32_e32 v12, v74, v20
	v_fmac_f32_e32 v13, v75, v20
	v_fmac_f32_e32 v14, v76, v20
	v_fmac_f32_e32 v15, v77, v20
	v_fmac_f32_e32 v16, v78, v20
	v_fmac_f32_e32 v17, v79, v20
	v_fmac_f32_e32 v18, v80, v20
	v_fmac_f32_e32 v19, v81, v20
	v_fma_f32 v20, v82, v20, v52
	s_waitcnt lgkmcnt(10)
; __device__ __forceinline__ float bf2f(bf16_t b) { return __uint_as_float((unsigned)b << 16); }
; __device__ __forceinline__ void conf_unit(const Ctx& X, LAS unsigned char* lds, int b, int c, int tid, int wave, int lane, int layer) {
;     ...
; #pragma unroll
;         for (int rr = 0; rr < 62; ++rr) { const float g = bf2f(GL[(half * 32 + rr) * 256 + ch]);
; #pragma unroll
;             for (int tk = 0; tk < 32; ++tk) { const int k = rr - tk; if (k >= 0 && k < 31) acc[tk] += w[k] * g; } }
	v_lshlrev_b32_e32 v21, 16, v21
	v_fmac_f32_e32 v7, v69, v21
	v_fmac_f32_e32 v8, v70, v21
	v_fmac_f32_e32 v9, v71, v21
	v_fmac_f32_e32 v10, v72, v21
	v_fmac_f32_e32 v12, v73, v21
	v_fmac_f32_e32 v13, v74, v21
	v_fmac_f32_e32 v14, v75, v21
	v_fmac_f32_e32 v15, v76, v21
	v_fmac_f32_e32 v16, v77, v21
	v_fmac_f32_e32 v17, v78, v21
	v_fmac_f32_e32 v18, v79, v21
	v_fmac_f32_e32 v19, v80, v21
	v_fmac_f32_e32 v20, v81, v21
	v_fma_f32 v21, v82, v21, v52
	s_waitcnt lgkmcnt(9)
	v_lshlrev_b32_e32 v22, 16, v22
	v_fmac_f32_e32 v7, v68, v22
	v_fmac_f32_e32 v8, v69, v22
	v_fmac_f32_e32 v9, v70, v22
	v_fmac_f32_e32 v10, v71, v22
	v_fmac_f32_e32 v12, v72, v22
	v_fmac_f32_e32 v13, v73, v22
	v_fmac_f32_e32 v14, v74, v22
	v_fmac_f32_e32 v15, v75, v22
	v_fmac_f32_e32 v16, v76, v22
	v_fmac_f32_e32 v17, v77, v22
	v_fmac_f32_e32 v18, v78, v22
	v_fmac_f32_e32 v19, v79, v22
	v_fmac_f32_e32 v20, v80, v22
	v_fmac_f32_e32 v21, v81, v22
	v_fma_f32 v22, v82, v22, v52
	s_waitcnt lgkmcnt(8)
	v_lshlrev_b32_e32 v23, 16, v23
	v_fmac_f32_e32 v7, v67, v23
	v_fmac_f32_e32 v8, v68, v23
	v_fmac_f32_e32 v9, v69, v23
	v_fmac_f32_e32 v10, v70, v23
	v_fmac_f32_e32 v12, v71, v23
	v_fmac_f32_e32 v13, v72, v23
	v_fmac_f32_e32 v14, v73, v23
	v_fmac_f32_e32 v15, v74, v23
	v_fmac_f32_e32 v16, v75, v23
	v_fmac_f32_e32 v17, v76, v23
	v_fmac_f32_e32 v18, v77, v23
	v_fmac_f32_e32 v19, v78, v23
	v_fmac_f32_e32 v20, v79, v23
	v_fmac_f32_e32 v21, v80, v23
	v_fmac_f32_e32 v22, v81, v23
	v_fma_f32 v23, v82, v23, v52
	s_waitcnt lgkmcnt(7)
	v_lshlrev_b32_e32 v24, 16, v24
	v_fmac_f32_e32 v7, v66, v24
	v_fmac_f32_e32 v8, v67, v24
	v_fmac_f32_e32 v9, v68, v24
	v_fmac_f32_e32 v10, v69, v24
	v_fmac_f32_e32 v12, v70, v24
	v_fmac_f32_e32 v13, v71, v24
	v_fmac_f32_e32 v14, v72, v24
	v_fmac_f32_e32 v15, v73, v24
	v_fmac_f32_e32 v16, v74, v24
	v_fmac_f32_e32 v17, v75, v24
	v_fmac_f32_e32 v18, v76, v24
	v_fmac_f32_e32 v19, v77, v24
	v_fmac_f32_e32 v20, v78, v24
	v_fmac_f32_e32 v21, v79, v24
	v_fmac_f32_e32 v22, v80, v24
	v_fmac_f32_e32 v23, v81, v24
	v_fma_f32 v24, v82, v24, v52
	s_waitcnt lgkmcnt(6)
	v_lshlrev_b32_e32 v25, 16, v25
	v_fmac_f32_e32 v7, v65, v25
	v_fmac_f32_e32 v8, v66, v25
	v_fmac_f32_e32 v9, v67, v25
	v_fmac_f32_e32 v10, v68, v25
	v_fmac_f32_e32 v12, v69, v25
	v_fmac_f32_e32 v13, v70, v25
	v_fmac_f32_e32 v14, v71, v25
	v_fmac_f32_e32 v15, v72, v25
	v_fmac_f32_e32 v16, v73, v25
	v_fmac_f32_e32 v17, v74, v25
	v_fmac_f32_e32 v18, v75, v25
	v_fmac_f32_e32 v19, v76, v25
	v_fmac_f32_e32 v20, v77, v25
	v_fmac_f32_e32 v21, v78, v25
	v_fmac_f32_e32 v22, v79, v25
	v_fmac_f32_e32 v23, v80, v25
	v_fmac_f32_e32 v24, v81, v25
	v_fma_f32 v25, v82, v25, v52
	s_waitcnt lgkmcnt(5)
	v_lshlrev_b32_e32 v26, 16, v26
	v_fmac_f32_e32 v7, v64, v26
	v_fmac_f32_e32 v8, v65, v26
	v_fmac_f32_e32 v9, v66, v26
	v_fmac_f32_e32 v10, v67, v26
	v_fmac_f32_e32 v12, v68, v26
	v_fmac_f32_e32 v13, v69, v26
	v_fmac_f32_e32 v14, v70, v26
	v_fmac_f32_e32 v15, v71, v26
	v_fmac_f32_e32 v16, v72, v26
	v_fmac_f32_e32 v17, v73, v26
	v_fmac_f32_e32 v18, v74, v26
	v_fmac_f32_e32 v19, v75, v26
	v_fmac_f32_e32 v20, v76, v26
	v_fmac_f32_e32 v21, v77, v26
	v_fmac_f32_e32 v22, v78, v26
	v_fmac_f32_e32 v23, v79, v26
	v_fmac_f32_e32 v24, v80, v26
	v_fmac_f32_e32 v25, v81, v26
	v_fma_f32 v26, v82, v26, v52
	s_waitcnt lgkmcnt(4)
	v_lshlrev_b32_e32 v27, 16, v27
	ds_read_u16 v32, v11 offset:12288
	ds_read_u16 v33, v11 offset:12800
	ds_read_u16 v34, v11 offset:13312
	ds_read_u16 v35, v11 offset:13824
	ds_read_u16 v36, v11 offset:14336
	ds_read_u16 v37, v11 offset:14848
	ds_read_u16 v38, v11 offset:15360
	ds_read_u16 v39, v11 offset:15872
	v_fmac_f32_e32 v7, v63, v27
	v_fmac_f32_e32 v8, v64, v27
	v_fmac_f32_e32 v9, v65, v27
	v_fmac_f32_e32 v10, v66, v27
	v_fmac_f32_e32 v12, v67, v27
	v_fmac_f32_e32 v13, v68, v27
	v_fmac_f32_e32 v14, v69, v27
	v_fmac_f32_e32 v15, v70, v27
	v_fmac_f32_e32 v16, v71, v27
	v_fmac_f32_e32 v17, v72, v27
	v_fmac_f32_e32 v18, v73, v27
	v_fmac_f32_e32 v19, v74, v27
	v_fmac_f32_e32 v20, v75, v27
	v_fmac_f32_e32 v21, v76, v27
	v_fmac_f32_e32 v22, v77, v27
	v_fmac_f32_e32 v23, v78, v27
	v_fmac_f32_e32 v24, v79, v27
	v_fmac_f32_e32 v25, v80, v27
	v_fmac_f32_e32 v26, v81, v27
	v_fma_f32 v27, v82, v27, v52
	s_waitcnt lgkmcnt(11)
	v_lshlrev_b32_e32 v28, 16, v28
	v_fmac_f32_e32 v7, v62, v28
	v_fmac_f32_e32 v8, v63, v28
	v_fmac_f32_e32 v9, v64, v28
	v_fmac_f32_e32 v10, v65, v28
	v_fmac_f32_e32 v12, v66, v28
	v_fmac_f32_e32 v13, v67, v28
	v_fmac_f32_e32 v14, v68, v28
	v_fmac_f32_e32 v15, v69, v28
	v_fmac_f32_e32 v16, v70, v28
	v_fmac_f32_e32 v17, v71, v28
	v_fmac_f32_e32 v18, v72, v28
	v_fmac_f32_e32 v19, v73, v28
	v_fmac_f32_e32 v20, v74, v28
	v_fmac_f32_e32 v21, v75, v28
	v_fmac_f32_e32 v22, v76, v28
	v_fmac_f32_e32 v23, v77, v28
	v_fmac_f32_e32 v24, v78, v28
	v_fmac_f32_e32 v25, v79, v28
	v_fmac_f32_e32 v26, v80, v28
	v_fmac_f32_e32 v27, v81, v28
	v_fma_f32 v28, v82, v28, v52
	s_waitcnt lgkmcnt(10)
	v_lshlrev_b32_e32 v29, 16, v29
	v_fmac_f32_e32 v7, v61, v29
	v_fmac_f32_e32 v8, v62, v29
	v_fmac_f32_e32 v9, v63, v29
	v_fmac_f32_e32 v10, v64, v29
	v_fmac_f32_e32 v12, v65, v29
	v_fmac_f32_e32 v13, v66, v29
	v_fmac_f32_e32 v14, v67, v29
	v_fmac_f32_e32 v15, v68, v29
	v_fmac_f32_e32 v16, v69, v29
	v_fmac_f32_e32 v17, v70, v29
	v_fmac_f32_e32 v18, v71, v29
	v_fmac_f32_e32 v19, v72, v29
	v_fmac_f32_e32 v20, v73, v29
	v_fmac_f32_e32 v21, v74, v29
	v_fmac_f32_e32 v22, v75, v29
	v_fmac_f32_e32 v23, v76, v29
	v_fmac_f32_e32 v24, v77, v29
	v_fmac_f32_e32 v25, v78, v29
	v_fmac_f32_e32 v26, v79, v29
	v_fmac_f32_e32 v27, v80, v29
	v_fmac_f32_e32 v28, v81, v29
	v_fma_f32 v29, v82, v29, v52
	s_waitcnt lgkmcnt(9)
; __device__ __forceinline__ float bf2f(bf16_t b) { return __uint_as_float((unsigned)b << 16); }
; __device__ __forceinline__ void conf_unit(const Ctx& X, LAS unsigned char* lds, int b, int c, int tid, int wave, int lane, int layer) {
;     ...
; #pragma unroll
;         for (int rr = 0; rr < 62; ++rr) { const float g = bf2f(GL[(half * 32 + rr) * 256 + ch]);
; #pragma unroll
;             for (int tk = 0; tk < 32; ++tk) { const int k = rr - tk; if (k >= 0 && k < 31) acc[tk] += w[k] * g; } }
	v_lshlrev_b32_e32 v30, 16, v30
	v_fmac_f32_e32 v7, v60, v30
	v_fmac_f32_e32 v8, v61, v30
	v_fmac_f32_e32 v9, v62, v30
	v_fmac_f32_e32 v10, v63, v30
	v_fmac_f32_e32 v12, v64, v30
	v_fmac_f32_e32 v13, v65, v30
	v_fmac_f32_e32 v14, v66, v30
	v_fmac_f32_e32 v15, v67, v30
	v_fmac_f32_e32 v16, v68, v30
	v_fmac_f32_e32 v17, v69, v30
	v_fmac_f32_e32 v18, v70, v30
	v_fmac_f32_e32 v19, v71, v30
	v_fmac_f32_e32 v20, v72, v30
	v_fmac_f32_e32 v21, v73, v30
	v_fmac_f32_e32 v22, v74, v30
	v_fmac_f32_e32 v23, v75, v30
	v_fmac_f32_e32 v24, v76, v30
	v_fmac_f32_e32 v25, v77, v30
	v_fmac_f32_e32 v26, v78, v30
	v_fmac_f32_e32 v27, v79, v30
	v_fmac_f32_e32 v28, v80, v30
	v_fmac_f32_e32 v29, v81, v30
	v_fma_f32 v30, v82, v30, v52
	s_waitcnt lgkmcnt(8)
	v_lshlrev_b32_e32 v31, 16, v31
	v_fmac_f32_e32 v7, v59, v31
	v_fmac_f32_e32 v8, v60, v31
	v_fmac_f32_e32 v9, v61, v31
	v_fmac_f32_e32 v10, v62, v31
	v_fmac_f32_e32 v12, v63, v31
	v_fmac_f32_e32 v13, v64, v31
	v_fmac_f32_e32 v14, v65, v31
	v_fmac_f32_e32 v15, v66, v31
	v_fmac_f32_e32 v16, v67, v31
	v_fmac_f32_e32 v17, v68, v31
	v_fmac_f32_e32 v18, v69, v31
	v_fmac_f32_e32 v19, v70, v31
	v_fmac_f32_e32 v20, v71, v31
	v_fmac_f32_e32 v21, v72, v31
	v_fmac_f32_e32 v22, v73, v31
	v_fmac_f32_e32 v23, v74, v31
	v_fmac_f32_e32 v24, v75, v31
	v_fmac_f32_e32 v25, v76, v31
	v_fmac_f32_e32 v26, v77, v31
	v_fmac_f32_e32 v27, v78, v31
	v_fmac_f32_e32 v28, v79, v31
	v_fmac_f32_e32 v29, v80, v31
	v_fmac_f32_e32 v30, v81, v31
	v_fma_f32 v31, v82, v31, v52
	s_waitcnt lgkmcnt(7)
	v_lshlrev_b32_e32 v32, 16, v32
	v_fmac_f32_e32 v7, v58, v32
	v_fmac_f32_e32 v8, v59, v32
	v_fmac_f32_e32 v9, v60, v32
	v_fmac_f32_e32 v10, v61, v32
	v_fmac_f32_e32 v12, v62, v32
	v_fmac_f32_e32 v13, v63, v32
	v_fmac_f32_e32 v14, v64, v32
	v_fmac_f32_e32 v15, v65, v32
	v_fmac_f32_e32 v16, v66, v32
	v_fmac_f32_e32 v17, v67, v32
	v_fmac_f32_e32 v18, v68, v32
	v_fmac_f32_e32 v19, v69, v32
	v_fmac_f32_e32 v20, v70, v32
	v_fmac_f32_e32 v21, v71, v32
	v_fmac_f32_e32 v22, v72, v32
	v_fmac_f32_e32 v23, v73, v32
	v_fmac_f32_e32 v24, v74, v32
	v_fmac_f32_e32 v25, v75, v32
	v_fmac_f32_e32 v26, v76, v32
	v_fmac_f32_e32 v27, v77, v32
	v_fmac_f32_e32 v28, v78, v32
	v_fmac_f32_e32 v29, v79, v32
	v_fmac_f32_e32 v30, v80, v32
	v_fmac_f32_e32 v31, v81, v32
	v_fma_f32 v32, v82, v32, v52
	s_waitcnt lgkmcnt(6)
	v_lshlrev_b32_e32 v33, 16, v33
	v_fmac_f32_e32 v7, v57, v33
	v_fmac_f32_e32 v8, v58, v33
	v_fmac_f32_e32 v9, v59, v33
	v_fmac_f32_e32 v10, v60, v33
	v_fmac_f32_e32 v12, v61, v33
	v_fmac_f32_e32 v13, v62, v33
	v_fmac_f32_e32 v14, v63, v33
	v_fmac_f32_e32 v15, v64, v33
	v_fmac_f32_e32 v16, v65, v33
	v_fmac_f32_e32 v17, v66, v33
	v_fmac_f32_e32 v18, v67, v33
	v_fmac_f32_e32 v19, v68, v33
	v_fmac_f32_e32 v20, v69, v33
	v_fmac_f32_e32 v21, v70, v33
	v_fmac_f32_e32 v22, v71, v33
	v_fmac_f32_e32 v23, v72, v33
	v_fmac_f32_e32 v24, v73, v33
	v_fmac_f32_e32 v25, v74, v33
	v_fmac_f32_e32 v26, v75, v33
	v_fmac_f32_e32 v27, v76, v33
	v_fmac_f32_e32 v28, v77, v33
	v_fmac_f32_e32 v29, v78, v33
	v_fmac_f32_e32 v30, v79, v33
	v_fmac_f32_e32 v31, v80, v33
	v_fmac_f32_e32 v32, v81, v33
	v_fma_f32 v33, v82, v33, v52
	s_waitcnt lgkmcnt(5)
	v_lshlrev_b32_e32 v34, 16, v34
	v_fmac_f32_e32 v7, v56, v34
	v_fmac_f32_e32 v8, v57, v34
	v_fmac_f32_e32 v9, v58, v34
	v_fmac_f32_e32 v10, v59, v34
	v_fmac_f32_e32 v12, v60, v34
	v_fmac_f32_e32 v13, v61, v34
	v_fmac_f32_e32 v14, v62, v34
	v_fmac_f32_e32 v15, v63, v34
	v_fmac_f32_e32 v16, v64, v34
	v_fmac_f32_e32 v17, v65, v34
	v_fmac_f32_e32 v18, v66, v34
	v_fmac_f32_e32 v19, v67, v34
	v_fmac_f32_e32 v20, v68, v34
	v_fmac_f32_e32 v21, v69, v34
	v_fmac_f32_e32 v22, v70, v34
	v_fmac_f32_e32 v23, v71, v34
	v_fmac_f32_e32 v24, v72, v34
	v_fmac_f32_e32 v25, v73, v34
	v_fmac_f32_e32 v26, v74, v34
	v_fmac_f32_e32 v27, v75, v34
	v_fmac_f32_e32 v28, v76, v34
	v_fmac_f32_e32 v29, v77, v34
	v_fmac_f32_e32 v30, v78, v34
	v_fmac_f32_e32 v31, v79, v34
	v_fmac_f32_e32 v32, v80, v34
	v_fmac_f32_e32 v33, v81, v34
	v_fma_f32 v34, v82, v34, v52
	s_waitcnt lgkmcnt(4)
	v_lshlrev_b32_e32 v35, 16, v35
	v_fmac_f32_e32 v7, v55, v35
	v_fmac_f32_e32 v8, v56, v35
	v_fmac_f32_e32 v9, v57, v35
	v_fmac_f32_e32 v10, v58, v35
	v_fmac_f32_e32 v12, v59, v35
	v_fmac_f32_e32 v13, v60, v35
	v_fmac_f32_e32 v14, v61, v35
	v_fmac_f32_e32 v15, v62, v35
	v_fmac_f32_e32 v16, v63, v35
	v_fmac_f32_e32 v17, v64, v35
	v_fmac_f32_e32 v18, v65, v35
	v_fmac_f32_e32 v19, v66, v35
	v_fmac_f32_e32 v20, v67, v35
	v_fmac_f32_e32 v21, v68, v35
	v_fmac_f32_e32 v22, v69, v35
	v_fmac_f32_e32 v23, v70, v35
	v_fmac_f32_e32 v24, v71, v35
	v_fmac_f32_e32 v25, v72, v35
	v_fmac_f32_e32 v26, v73, v35
	v_fmac_f32_e32 v27, v74, v35
	v_fmac_f32_e32 v28, v75, v35
	v_fmac_f32_e32 v29, v76, v35
	v_fmac_f32_e32 v30, v77, v35
	v_fmac_f32_e32 v31, v78, v35
	v_fmac_f32_e32 v32, v79, v35
	v_fmac_f32_e32 v33, v80, v35
	v_fmac_f32_e32 v34, v81, v35
	v_fma_f32 v35, v82, v35, v52
	s_waitcnt lgkmcnt(3)
	v_lshlrev_b32_e32 v36, 16, v36
	v_fmac_f32_e32 v7, v54, v36
	v_fmac_f32_e32 v8, v55, v36
	v_fmac_f32_e32 v9, v56, v36
	v_fmac_f32_e32 v10, v57, v36
	v_fmac_f32_e32 v12, v58, v36
	v_fmac_f32_e32 v13, v59, v36
	v_fmac_f32_e32 v14, v60, v36
	v_fmac_f32_e32 v15, v61, v36
	v_fmac_f32_e32 v16, v62, v36
	v_fmac_f32_e32 v17, v63, v36
	v_fmac_f32_e32 v18, v64, v36
	v_fmac_f32_e32 v19, v65, v36
	v_fmac_f32_e32 v20, v66, v36
	v_fmac_f32_e32 v21, v67, v36
	v_fmac_f32_e32 v22, v68, v36
	v_fmac_f32_e32 v23, v69, v36
	v_fmac_f32_e32 v24, v70, v36
	v_fmac_f32_e32 v25, v71, v36
	v_fmac_f32_e32 v26, v72, v36
	v_fmac_f32_e32 v27, v73, v36
	v_fmac_f32_e32 v28, v74, v36
	v_fmac_f32_e32 v29, v75, v36
	v_fmac_f32_e32 v30, v76, v36
	v_fmac_f32_e32 v31, v77, v36
	v_fmac_f32_e32 v32, v78, v36
	v_fmac_f32_e32 v33, v79, v36
	v_fmac_f32_e32 v34, v80, v36
	v_fmac_f32_e32 v35, v81, v36
	v_fma_f32 v36, v82, v36, v52
	s_waitcnt lgkmcnt(2)
; __device__ __forceinline__ float bf2f(bf16_t b) { return __uint_as_float((unsigned)b << 16); }
; __device__ __forceinline__ void conf_unit(const Ctx& X, LAS unsigned char* lds, int b, int c, int tid, int wave, int lane, int layer) {
;     ...
; #pragma unroll
;         for (int rr = 0; rr < 62; ++rr) { const float g = bf2f(GL[(half * 32 + rr) * 256 + ch]);
; #pragma unroll
;             for (int tk = 0; tk < 32; ++tk) { const int k = rr - tk; if (k >= 0 && k < 31) acc[tk] += w[k] * g; } }
	v_lshlrev_b32_e32 v37, 16, v37
	v_fmac_f32_e32 v7, v53, v37
	v_fmac_f32_e32 v8, v54, v37
	v_fmac_f32_e32 v9, v55, v37
	v_fmac_f32_e32 v10, v56, v37
	v_fmac_f32_e32 v12, v57, v37
	v_fmac_f32_e32 v13, v58, v37
	v_fmac_f32_e32 v14, v59, v37
	v_fmac_f32_e32 v15, v60, v37
	v_fmac_f32_e32 v16, v61, v37
	v_fmac_f32_e32 v17, v62, v37
	v_fmac_f32_e32 v18, v63, v37
	v_fmac_f32_e32 v19, v64, v37
	v_fmac_f32_e32 v20, v65, v37
	v_fmac_f32_e32 v21, v66, v37
	v_fmac_f32_e32 v22, v67, v37
	v_fmac_f32_e32 v23, v68, v37
	v_fmac_f32_e32 v24, v69, v37
	v_fmac_f32_e32 v25, v70, v37
	v_fmac_f32_e32 v26, v71, v37
	v_fmac_f32_e32 v27, v72, v37
	v_fmac_f32_e32 v28, v73, v37
	v_fmac_f32_e32 v29, v74, v37
	v_fmac_f32_e32 v30, v75, v37
	v_fmac_f32_e32 v31, v76, v37
	v_fmac_f32_e32 v32, v77, v37
	v_fmac_f32_e32 v33, v78, v37
	v_fmac_f32_e32 v34, v79, v37
	v_fmac_f32_e32 v35, v80, v37
	v_fmac_f32_e32 v36, v81, v37
	v_fma_f32 v37, v82, v37, v52
	s_waitcnt lgkmcnt(1)
	v_lshlrev_b32_e32 v38, 16, v38
	v_fmac_f32_e32 v7, v51, v38
	v_fmac_f32_e32 v8, v53, v38
	v_fmac_f32_e32 v9, v54, v38
	v_fmac_f32_e32 v10, v55, v38
	v_fmac_f32_e32 v12, v56, v38
	v_fmac_f32_e32 v13, v57, v38
	v_fmac_f32_e32 v14, v58, v38
	v_fmac_f32_e32 v15, v59, v38
	v_fmac_f32_e32 v16, v60, v38
	v_fmac_f32_e32 v17, v61, v38
	v_fmac_f32_e32 v18, v62, v38
	v_fmac_f32_e32 v19, v63, v38
	v_fmac_f32_e32 v20, v64, v38
	v_fmac_f32_e32 v21, v65, v38
	v_fmac_f32_e32 v22, v66, v38
	v_fmac_f32_e32 v23, v67, v38
	v_fmac_f32_e32 v24, v68, v38
	v_fmac_f32_e32 v25, v69, v38
	v_fmac_f32_e32 v26, v70, v38
	v_fmac_f32_e32 v27, v71, v38
	v_fmac_f32_e32 v28, v72, v38
	v_fmac_f32_e32 v29, v73, v38
	v_fmac_f32_e32 v30, v74, v38
	v_fmac_f32_e32 v31, v75, v38
	v_fmac_f32_e32 v32, v76, v38
	v_fmac_f32_e32 v33, v77, v38
	v_fmac_f32_e32 v34, v78, v38
	v_fmac_f32_e32 v35, v79, v38
	v_fmac_f32_e32 v36, v80, v38
	v_fmac_f32_e32 v37, v81, v38
	v_fma_f32 v38, v82, v38, v52
	s_waitcnt lgkmcnt(0)
	v_lshlrev_b32_e32 v39, 16, v39
	v_fmac_f32_e32 v8, v51, v39
	v_fmac_f32_e32 v9, v53, v39
	v_fmac_f32_e32 v10, v54, v39
	v_fmac_f32_e32 v12, v55, v39
	v_fmac_f32_e32 v13, v56, v39
	v_fmac_f32_e32 v14, v57, v39
	v_fmac_f32_e32 v15, v58, v39
	v_fmac_f32_e32 v16, v59, v39
	v_fmac_f32_e32 v17, v60, v39
	v_fmac_f32_e32 v18, v61, v39
	v_fmac_f32_e32 v19, v62, v39
	v_fmac_f32_e32 v20, v63, v39
	v_fmac_f32_e32 v21, v64, v39
	v_fmac_f32_e32 v22, v65, v39
	v_fmac_f32_e32 v23, v66, v39
	v_fmac_f32_e32 v24, v67, v39
	v_fmac_f32_e32 v25, v68, v39
	v_fmac_f32_e32 v26, v69, v39
	v_fmac_f32_e32 v27, v70, v39
	v_fmac_f32_e32 v28, v71, v39
	v_fmac_f32_e32 v29, v72, v39
	v_fmac_f32_e32 v30, v73, v39
	v_fmac_f32_e32 v31, v74, v39
	v_fmac_f32_e32 v32, v75, v39
	v_fmac_f32_e32 v33, v76, v39
	v_fmac_f32_e32 v34, v77, v39
	v_fmac_f32_e32 v35, v78, v39
	v_fmac_f32_e32 v36, v79, v39
	v_fmac_f32_e32 v37, v80, v39
	v_fmac_f32_e32 v38, v81, v39
	v_fmac_f32_e32 v52, v82, v39
	ds_read_u16 v39, v11 offset:16384
	v_lshlrev_b32_e32 v6, 15, v6
	v_add3_u32 v6, v50, v6, v156
	v_ashrrev_i32_e32 v131, 31, v130
	v_readlane_b32 s1, v254, 45
	s_waitcnt lgkmcnt(0)
	v_lshlrev_b32_e32 v39, 16, v39
	v_fmac_f32_e32 v9, v51, v39
	v_fmac_f32_e32 v10, v53, v39
	v_fmac_f32_e32 v12, v54, v39
	v_fmac_f32_e32 v13, v55, v39
	v_fmac_f32_e32 v14, v56, v39
	v_fmac_f32_e32 v15, v57, v39
	v_fmac_f32_e32 v16, v58, v39
	v_fmac_f32_e32 v17, v59, v39
	v_fmac_f32_e32 v18, v60, v39
	v_fmac_f32_e32 v19, v61, v39
	v_fmac_f32_e32 v20, v62, v39
	v_fmac_f32_e32 v21, v63, v39
	v_fmac_f32_e32 v22, v64, v39
	v_fmac_f32_e32 v23, v65, v39
	v_fmac_f32_e32 v24, v66, v39
	v_fmac_f32_e32 v25, v67, v39
	v_fmac_f32_e32 v26, v68, v39
	v_fmac_f32_e32 v27, v69, v39
	v_fmac_f32_e32 v28, v70, v39
	v_fmac_f32_e32 v29, v71, v39
	v_fmac_f32_e32 v30, v72, v39
	v_fmac_f32_e32 v31, v73, v39
	v_fmac_f32_e32 v32, v74, v39
	v_fmac_f32_e32 v33, v75, v39
	v_fmac_f32_e32 v34, v76, v39
	v_fmac_f32_e32 v35, v77, v39
	v_fmac_f32_e32 v36, v78, v39
	v_fmac_f32_e32 v37, v79, v39
	v_fmac_f32_e32 v38, v80, v39
	v_fmac_f32_e32 v52, v81, v39
	ds_read_u16 v39, v11 offset:16896
	s_add_i32 s1, s1, s16
	s_add_i32 s16, s1, s7
	s_lshl_b64 s[4:5], s[16:17], 11
	v_readlane_b32 s1, v254, 43
	s_waitcnt lgkmcnt(0)
	v_lshlrev_b32_e32 v39, 16, v39
	v_fmac_f32_e32 v10, v51, v39
	v_fmac_f32_e32 v12, v53, v39
	v_fmac_f32_e32 v13, v54, v39
	v_fmac_f32_e32 v14, v55, v39
	v_fmac_f32_e32 v15, v56, v39
	v_fmac_f32_e32 v16, v57, v39
	v_fmac_f32_e32 v17, v58, v39
	v_fmac_f32_e32 v18, v59, v39
	v_fmac_f32_e32 v19, v60, v39
	v_fmac_f32_e32 v20, v61, v39
	v_fmac_f32_e32 v21, v62, v39
	v_fmac_f32_e32 v22, v63, v39
	v_fmac_f32_e32 v23, v64, v39
	v_fmac_f32_e32 v24, v65, v39
	v_fmac_f32_e32 v25, v66, v39
	v_fmac_f32_e32 v26, v67, v39
	v_fmac_f32_e32 v27, v68, v39
	v_fmac_f32_e32 v28, v69, v39
	v_fmac_f32_e32 v29, v70, v39
	v_fmac_f32_e32 v30, v71, v39
	v_fmac_f32_e32 v31, v72, v39
	v_fmac_f32_e32 v32, v73, v39
	v_fmac_f32_e32 v33, v74, v39
	v_fmac_f32_e32 v34, v75, v39
	v_fmac_f32_e32 v35, v76, v39
	v_fmac_f32_e32 v36, v77, v39
	v_fmac_f32_e32 v37, v78, v39
	v_fmac_f32_e32 v38, v79, v39
	v_fmac_f32_e32 v52, v80, v39
	ds_read_u16 v39, v11 offset:17408
	s_add_u32 s4, s1, s4
	v_readlane_b32 s1, v254, 44
	s_addc_u32 s5, s1, s5
	s_mov_b64 s[22:23], s[64:65]
	s_waitcnt lgkmcnt(0)
; __device__ __forceinline__ float bf2f(bf16_t b) { return __uint_as_float((unsigned)b << 16); }
; __device__ __forceinline__ void conf_unit(const Ctx& X, LAS unsigned char* lds, int b, int c, int tid, int wave, int lane, int layer) {
;     ...
; #pragma unroll
;         for (int rr = 0; rr < 62; ++rr) { const float g = bf2f(GL[(half * 32 + rr) * 256 + ch]);
; #pragma unroll
;             for (int tk = 0; tk < 32; ++tk) { const int k = rr - tk; if (k >= 0 && k < 31) acc[tk] += w[k] * g; } }
	v_lshlrev_b32_e32 v39, 16, v39
	v_fmac_f32_e32 v12, v51, v39
	v_fmac_f32_e32 v13, v53, v39
	v_fmac_f32_e32 v14, v54, v39
	v_fmac_f32_e32 v15, v55, v39
	v_fmac_f32_e32 v16, v56, v39
	v_fmac_f32_e32 v17, v57, v39
	v_fmac_f32_e32 v18, v58, v39
	v_fmac_f32_e32 v19, v59, v39
	v_fmac_f32_e32 v20, v60, v39
	v_fmac_f32_e32 v21, v61, v39
	v_fmac_f32_e32 v22, v62, v39
	v_fmac_f32_e32 v23, v63, v39
	v_fmac_f32_e32 v24, v64, v39
	v_fmac_f32_e32 v25, v65, v39
	v_fmac_f32_e32 v26, v66, v39
	v_fmac_f32_e32 v27, v67, v39
	v_fmac_f32_e32 v28, v68, v39
	v_fmac_f32_e32 v29, v69, v39
	v_fmac_f32_e32 v30, v70, v39
	v_fmac_f32_e32 v31, v71, v39
	v_fmac_f32_e32 v32, v72, v39
	v_fmac_f32_e32 v33, v73, v39
	v_fmac_f32_e32 v34, v74, v39
	v_fmac_f32_e32 v35, v75, v39
	v_fmac_f32_e32 v36, v76, v39
	v_fmac_f32_e32 v37, v77, v39
	v_fmac_f32_e32 v38, v78, v39
	v_fmac_f32_e32 v52, v79, v39
	ds_read_u16 v39, v11 offset:17920
	s_mov_b32 s0, 0
	v_readlane_b32 s19, v255, 26
	s_waitcnt lgkmcnt(0)
	v_lshlrev_b32_e32 v39, 16, v39
	v_fmac_f32_e32 v13, v51, v39
	v_fmac_f32_e32 v14, v53, v39
	v_fmac_f32_e32 v15, v54, v39
	v_fmac_f32_e32 v16, v55, v39
	v_fmac_f32_e32 v17, v56, v39
	v_fmac_f32_e32 v18, v57, v39
	v_fmac_f32_e32 v19, v58, v39
	v_fmac_f32_e32 v20, v59, v39
	v_fmac_f32_e32 v21, v60, v39
	v_fmac_f32_e32 v22, v61, v39
	v_fmac_f32_e32 v23, v62, v39
	v_fmac_f32_e32 v24, v63, v39
	v_fmac_f32_e32 v25, v64, v39
	v_fmac_f32_e32 v26, v65, v39
	v_fmac_f32_e32 v27, v66, v39
	v_fmac_f32_e32 v28, v67, v39
	v_fmac_f32_e32 v29, v68, v39
	v_fmac_f32_e32 v30, v69, v39
	v_fmac_f32_e32 v31, v70, v39
	v_fmac_f32_e32 v32, v71, v39
	v_fmac_f32_e32 v33, v72, v39
	v_fmac_f32_e32 v34, v73, v39
	v_fmac_f32_e32 v35, v74, v39
	v_fmac_f32_e32 v36, v75, v39
	v_fmac_f32_e32 v37, v76, v39
	v_fmac_f32_e32 v38, v77, v39
	v_fmac_f32_e32 v52, v78, v39
	ds_read_u16 v39, v11 offset:18432
	s_waitcnt lgkmcnt(0)
	v_lshlrev_b32_e32 v39, 16, v39
	v_fmac_f32_e32 v14, v51, v39
	v_fmac_f32_e32 v15, v53, v39
	v_fmac_f32_e32 v16, v54, v39
	v_fmac_f32_e32 v17, v55, v39
	v_fmac_f32_e32 v18, v56, v39
	v_fmac_f32_e32 v19, v57, v39
	v_fmac_f32_e32 v20, v58, v39
	v_fmac_f32_e32 v21, v59, v39
	v_fmac_f32_e32 v22, v60, v39
	v_fmac_f32_e32 v23, v61, v39
	v_fmac_f32_e32 v24, v62, v39
	v_fmac_f32_e32 v25, v63, v39
	v_fmac_f32_e32 v26, v64, v39
	v_fmac_f32_e32 v27, v65, v39
	v_fmac_f32_e32 v28, v66, v39
	v_fmac_f32_e32 v29, v67, v39
	v_fmac_f32_e32 v30, v68, v39
	v_fmac_f32_e32 v31, v69, v39
	v_fmac_f32_e32 v32, v70, v39
	v_fmac_f32_e32 v33, v71, v39
	v_fmac_f32_e32 v34, v72, v39
	v_fmac_f32_e32 v35, v73, v39
	v_fmac_f32_e32 v36, v74, v39
	v_fmac_f32_e32 v37, v75, v39
	v_fmac_f32_e32 v38, v76, v39
	v_fmac_f32_e32 v52, v77, v39
	ds_read_u16 v39, v11 offset:18944
	s_waitcnt lgkmcnt(0)
	v_lshlrev_b32_e32 v39, 16, v39
	v_fmac_f32_e32 v15, v51, v39
	v_fmac_f32_e32 v16, v53, v39
	v_fmac_f32_e32 v17, v54, v39
	v_fmac_f32_e32 v18, v55, v39
	v_fmac_f32_e32 v19, v56, v39
	v_fmac_f32_e32 v20, v57, v39
	v_fmac_f32_e32 v21, v58, v39
	v_fmac_f32_e32 v22, v59, v39
	v_fmac_f32_e32 v23, v60, v39
	v_fmac_f32_e32 v24, v61, v39
	v_fmac_f32_e32 v25, v62, v39
	v_fmac_f32_e32 v26, v63, v39
	v_fmac_f32_e32 v27, v64, v39
	v_fmac_f32_e32 v28, v65, v39
	v_fmac_f32_e32 v29, v66, v39
	v_fmac_f32_e32 v30, v67, v39
	v_fmac_f32_e32 v31, v68, v39
	v_fmac_f32_e32 v32, v69, v39
	v_fmac_f32_e32 v33, v70, v39
	v_fmac_f32_e32 v34, v71, v39
	v_fmac_f32_e32 v35, v72, v39
	v_fmac_f32_e32 v36, v73, v39
	v_fmac_f32_e32 v37, v74, v39
	v_fmac_f32_e32 v38, v75, v39
	v_fmac_f32_e32 v52, v76, v39
	ds_read_u16 v39, v11 offset:19456
	s_waitcnt lgkmcnt(0)
	v_lshlrev_b32_e32 v39, 16, v39
	v_fmac_f32_e32 v16, v51, v39
	v_fmac_f32_e32 v17, v53, v39
	v_fmac_f32_e32 v18, v54, v39
	v_fmac_f32_e32 v19, v55, v39
	v_fmac_f32_e32 v20, v56, v39
	v_fmac_f32_e32 v21, v57, v39
	v_fmac_f32_e32 v22, v58, v39
	v_fmac_f32_e32 v23, v59, v39
	v_fmac_f32_e32 v24, v60, v39
	v_fmac_f32_e32 v25, v61, v39
	v_fmac_f32_e32 v26, v62, v39
	v_fmac_f32_e32 v27, v63, v39
	v_fmac_f32_e32 v28, v64, v39
	v_fmac_f32_e32 v29, v65, v39
	v_fmac_f32_e32 v30, v66, v39
	v_fmac_f32_e32 v31, v67, v39
	v_fmac_f32_e32 v32, v68, v39
	v_fmac_f32_e32 v33, v69, v39
	v_fmac_f32_e32 v34, v70, v39
	v_fmac_f32_e32 v35, v71, v39
	v_fmac_f32_e32 v36, v72, v39
	v_fmac_f32_e32 v37, v73, v39
	v_fmac_f32_e32 v38, v74, v39
	v_fmac_f32_e32 v52, v75, v39
	ds_read_u16 v39, v11 offset:19968
	s_waitcnt lgkmcnt(0)
	v_lshlrev_b32_e32 v39, 16, v39
	v_fmac_f32_e32 v17, v51, v39
	v_fmac_f32_e32 v18, v53, v39
	v_fmac_f32_e32 v19, v54, v39
	v_fmac_f32_e32 v20, v55, v39
	v_fmac_f32_e32 v21, v56, v39
	v_fmac_f32_e32 v22, v57, v39
	v_fmac_f32_e32 v23, v58, v39
	v_fmac_f32_e32 v24, v59, v39
	v_fmac_f32_e32 v25, v60, v39
	v_fmac_f32_e32 v26, v61, v39
	v_fmac_f32_e32 v27, v62, v39
	v_fmac_f32_e32 v28, v63, v39
	v_fmac_f32_e32 v29, v64, v39
	v_fmac_f32_e32 v30, v65, v39
	v_fmac_f32_e32 v31, v66, v39
	v_fmac_f32_e32 v32, v67, v39
	v_fmac_f32_e32 v33, v68, v39
	v_fmac_f32_e32 v34, v69, v39
	v_fmac_f32_e32 v35, v70, v39
	v_fmac_f32_e32 v36, v71, v39
	v_fmac_f32_e32 v37, v72, v39
	v_fmac_f32_e32 v38, v73, v39
	v_fmac_f32_e32 v52, v74, v39
	ds_read_u16 v39, v11 offset:20480
	s_waitcnt lgkmcnt(0)
	v_lshlrev_b32_e32 v39, 16, v39
	v_fmac_f32_e32 v18, v51, v39
	v_fmac_f32_e32 v19, v53, v39
	v_fmac_f32_e32 v20, v54, v39
	v_fmac_f32_e32 v21, v55, v39
	v_fmac_f32_e32 v22, v56, v39
	v_fmac_f32_e32 v23, v57, v39
	v_fmac_f32_e32 v24, v58, v39
	v_fmac_f32_e32 v25, v59, v39
	v_fmac_f32_e32 v26, v60, v39
	v_fmac_f32_e32 v27, v61, v39
	v_fmac_f32_e32 v28, v62, v39
	v_fmac_f32_e32 v29, v63, v39
	v_fmac_f32_e32 v30, v64, v39
	v_fmac_f32_e32 v31, v65, v39
	v_fmac_f32_e32 v32, v66, v39
	v_fmac_f32_e32 v33, v67, v39
	v_fmac_f32_e32 v34, v68, v39
	v_fmac_f32_e32 v35, v69, v39
	v_fmac_f32_e32 v36, v70, v39
	v_fmac_f32_e32 v37, v71, v39
	v_fmac_f32_e32 v38, v72, v39
	v_fmac_f32_e32 v52, v73, v39
	ds_read_u16 v39, v11 offset:20992
	s_waitcnt lgkmcnt(0)
; __device__ __forceinline__ float bf2f(bf16_t b) { return __uint_as_float((unsigned)b << 16); }
; __device__ __forceinline__ void conf_unit(const Ctx& X, LAS unsigned char* lds, int b, int c, int tid, int wave, int lane, int layer) {
;     ...
;         for (int rr = 0; rr < 62; ++rr) { const float g = bf2f(GL[(half * 32 + rr) * 256 + ch]);
; #pragma unroll
;             for (int tk = 0; tk < 32; ++tk) { const int k = rr - tk; if (k >= 0 && k < 31) acc[tk] += w[k] * g; } }
	v_lshlrev_b32_e32 v39, 16, v39
	v_fmac_f32_e32 v19, v51, v39
	v_fmac_f32_e32 v20, v53, v39
	v_fmac_f32_e32 v21, v54, v39
	v_fmac_f32_e32 v22, v55, v39
	v_fmac_f32_e32 v23, v56, v39
	v_fmac_f32_e32 v24, v57, v39
	v_fmac_f32_e32 v25, v58, v39
	v_fmac_f32_e32 v26, v59, v39
	v_fmac_f32_e32 v27, v60, v39
	v_fmac_f32_e32 v28, v61, v39
	v_fmac_f32_e32 v29, v62, v39
	v_fmac_f32_e32 v30, v63, v39
	v_fmac_f32_e32 v31, v64, v39
	v_fmac_f32_e32 v32, v65, v39
	v_fmac_f32_e32 v33, v66, v39
	v_fmac_f32_e32 v34, v67, v39
	v_fmac_f32_e32 v35, v68, v39
	v_fmac_f32_e32 v36, v69, v39
	v_fmac_f32_e32 v37, v70, v39
	v_fmac_f32_e32 v38, v71, v39
	v_fmac_f32_e32 v52, v72, v39
	ds_read_u16 v39, v11 offset:21504
	s_waitcnt lgkmcnt(0)
	v_lshlrev_b32_e32 v39, 16, v39
	v_fmac_f32_e32 v20, v51, v39
	v_fmac_f32_e32 v21, v53, v39
	v_fmac_f32_e32 v22, v54, v39
	v_fmac_f32_e32 v23, v55, v39
	v_fmac_f32_e32 v24, v56, v39
	v_fmac_f32_e32 v25, v57, v39
	v_fmac_f32_e32 v26, v58, v39
	v_fmac_f32_e32 v27, v59, v39
	v_fmac_f32_e32 v28, v60, v39
	v_fmac_f32_e32 v29, v61, v39
	v_fmac_f32_e32 v30, v62, v39
	v_fmac_f32_e32 v31, v63, v39
	v_fmac_f32_e32 v32, v64, v39
	v_fmac_f32_e32 v33, v65, v39
	v_fmac_f32_e32 v34, v66, v39
	v_fmac_f32_e32 v35, v67, v39
	v_fmac_f32_e32 v36, v68, v39
	v_fmac_f32_e32 v37, v69, v39
	v_fmac_f32_e32 v38, v70, v39
	v_fmac_f32_e32 v52, v71, v39
	ds_read_u16 v39, v11 offset:22016
	s_waitcnt lgkmcnt(0)
	v_lshlrev_b32_e32 v39, 16, v39
	v_fmac_f32_e32 v21, v51, v39
	v_fmac_f32_e32 v22, v53, v39
	v_fmac_f32_e32 v23, v54, v39
	v_fmac_f32_e32 v24, v55, v39
	v_fmac_f32_e32 v25, v56, v39
	v_fmac_f32_e32 v26, v57, v39
	v_fmac_f32_e32 v27, v58, v39
	v_fmac_f32_e32 v28, v59, v39
	v_fmac_f32_e32 v29, v60, v39
	v_fmac_f32_e32 v30, v61, v39
	v_fmac_f32_e32 v31, v62, v39
	v_fmac_f32_e32 v32, v63, v39
	v_fmac_f32_e32 v33, v64, v39
	v_fmac_f32_e32 v34, v65, v39
	v_fmac_f32_e32 v35, v66, v39
	v_fmac_f32_e32 v36, v67, v39
	v_fmac_f32_e32 v37, v68, v39
	v_fmac_f32_e32 v38, v69, v39
	v_fmac_f32_e32 v52, v70, v39
	ds_read_u16 v39, v11 offset:22528
	s_waitcnt lgkmcnt(0)
	v_lshlrev_b32_e32 v39, 16, v39
	v_fmac_f32_e32 v22, v51, v39
	v_fmac_f32_e32 v23, v53, v39
	v_fmac_f32_e32 v24, v54, v39
	v_fmac_f32_e32 v25, v55, v39
	v_fmac_f32_e32 v26, v56, v39
	v_fmac_f32_e32 v27, v57, v39
	v_fmac_f32_e32 v28, v58, v39
	v_fmac_f32_e32 v29, v59, v39
	v_fmac_f32_e32 v30, v60, v39
	v_fmac_f32_e32 v31, v61, v39
	v_fmac_f32_e32 v32, v62, v39
	v_fmac_f32_e32 v33, v63, v39
	v_fmac_f32_e32 v34, v64, v39
	v_fmac_f32_e32 v35, v65, v39
	v_fmac_f32_e32 v36, v66, v39
	v_fmac_f32_e32 v37, v67, v39
	v_fmac_f32_e32 v38, v68, v39
	v_fmac_f32_e32 v52, v69, v39
	ds_read_u16 v39, v11 offset:23040
	s_waitcnt lgkmcnt(0)
	v_lshlrev_b32_e32 v39, 16, v39
	v_fmac_f32_e32 v23, v51, v39
	v_fmac_f32_e32 v24, v53, v39
	v_fmac_f32_e32 v25, v54, v39
	v_fmac_f32_e32 v26, v55, v39
	v_fmac_f32_e32 v27, v56, v39
	v_fmac_f32_e32 v28, v57, v39
	v_fmac_f32_e32 v29, v58, v39
	v_fmac_f32_e32 v30, v59, v39
	v_fmac_f32_e32 v31, v60, v39
	v_fmac_f32_e32 v32, v61, v39
	v_fmac_f32_e32 v33, v62, v39
	v_fmac_f32_e32 v34, v63, v39
	v_fmac_f32_e32 v35, v64, v39
	v_fmac_f32_e32 v36, v65, v39
	v_fmac_f32_e32 v37, v66, v39
	v_fmac_f32_e32 v38, v67, v39
	v_fmac_f32_e32 v52, v68, v39
	ds_read_u16 v39, v11 offset:23552
	s_waitcnt lgkmcnt(0)
	v_lshlrev_b32_e32 v39, 16, v39
	v_fmac_f32_e32 v24, v51, v39
	v_fmac_f32_e32 v25, v53, v39
	v_fmac_f32_e32 v26, v54, v39
	v_fmac_f32_e32 v27, v55, v39
	v_fmac_f32_e32 v28, v56, v39
	v_fmac_f32_e32 v29, v57, v39
	v_fmac_f32_e32 v30, v58, v39
	v_fmac_f32_e32 v31, v59, v39
	v_fmac_f32_e32 v32, v60, v39
	v_fmac_f32_e32 v33, v61, v39
	v_fmac_f32_e32 v34, v62, v39
	v_fmac_f32_e32 v35, v63, v39
	v_fmac_f32_e32 v36, v64, v39
	v_fmac_f32_e32 v37, v65, v39
	v_fmac_f32_e32 v38, v66, v39
	v_fmac_f32_e32 v52, v67, v39
	ds_read_u16 v39, v11 offset:24064
	s_waitcnt lgkmcnt(0)
	v_lshlrev_b32_e32 v39, 16, v39
	v_fmac_f32_e32 v25, v51, v39
	v_fmac_f32_e32 v26, v53, v39
	v_fmac_f32_e32 v27, v54, v39
	v_fmac_f32_e32 v28, v55, v39
	v_fmac_f32_e32 v29, v56, v39
	v_fmac_f32_e32 v30, v57, v39
	v_fmac_f32_e32 v31, v58, v39
	v_fmac_f32_e32 v32, v59, v39
	v_fmac_f32_e32 v33, v60, v39
	v_fmac_f32_e32 v34, v61, v39
	v_fmac_f32_e32 v35, v62, v39
	v_fmac_f32_e32 v36, v63, v39
	v_fmac_f32_e32 v37, v64, v39
	v_fmac_f32_e32 v38, v65, v39
	v_fmac_f32_e32 v52, v66, v39
	ds_read_u16 v39, v11 offset:24576
	s_waitcnt lgkmcnt(0)
	v_lshlrev_b32_e32 v39, 16, v39
	v_fmac_f32_e32 v26, v51, v39
	v_fmac_f32_e32 v27, v53, v39
	v_fmac_f32_e32 v28, v54, v39
	v_fmac_f32_e32 v29, v55, v39
	v_fmac_f32_e32 v30, v56, v39
	v_fmac_f32_e32 v31, v57, v39
	v_fmac_f32_e32 v32, v58, v39
	v_fmac_f32_e32 v33, v59, v39
	v_fmac_f32_e32 v34, v60, v39
	v_fmac_f32_e32 v35, v61, v39
	v_fmac_f32_e32 v36, v62, v39
	v_fmac_f32_e32 v37, v63, v39
	v_fmac_f32_e32 v38, v64, v39
	v_fmac_f32_e32 v52, v65, v39
	ds_read_u16 v39, v11 offset:25088
	s_waitcnt lgkmcnt(0)
	v_lshlrev_b32_e32 v39, 16, v39
	v_fmac_f32_e32 v27, v51, v39
	v_fmac_f32_e32 v28, v53, v39
	v_fmac_f32_e32 v29, v54, v39
	v_fmac_f32_e32 v30, v55, v39
	v_fmac_f32_e32 v31, v56, v39
	v_fmac_f32_e32 v32, v57, v39
	v_fmac_f32_e32 v33, v58, v39
	v_fmac_f32_e32 v34, v59, v39
	v_fmac_f32_e32 v35, v60, v39
	v_fmac_f32_e32 v36, v61, v39
	v_fmac_f32_e32 v37, v62, v39
	v_fmac_f32_e32 v38, v63, v39
	v_fmac_f32_e32 v52, v64, v39
	ds_read_u16 v39, v11 offset:25600
	s_waitcnt lgkmcnt(0)
; #define LAS __attribute__((address_space(3)))
; __device__ __forceinline__ float bf2f(bf16_t b) { return __uint_as_float((unsigned)b << 16); }
; #define LBAR() do { asm volatile("s_waitcnt lgkmcnt(0)" ::: "memory"); __builtin_amdgcn_s_barrier(); asm volatile("" ::: "memory"); } while (0)
; __device__ __forceinline__ void conf_unit(const Ctx& X, LAS unsigned char* lds, int b, int c, int tid, int wave, int lane, int layer) {
;     ...
;         for (int rr = 0; rr < 62; ++rr) { const float g = bf2f(GL[(half * 32 + rr) * 256 + ch]);
; #pragma unroll
;             for (int tk = 0; tk < 32; ++tk) { const int k = rr - tk; if (k >= 0 && k < 31) acc[tk] += w[k] * g; } }
; #pragma unroll
;         for (int tk = 0; tk < 32; ++tk) Y[(half * 32 + tk) * 256 + ch] = acc[tk];
;     }
;     LBAR();
;     {
;         const f32x4 lw = *((const f32x4*)(X.in[6] + layer * 256) + lane), lb = *((const f32x4*)(X.in[7] + layer * 256) + lane);
; #pragma unroll 2
;         for (int tk = wave * 8; tk < wave * 8 + 8; ++tk) {
;             const f32x4 v = *((const LAS f32x4*)(Y + tk * 256) + lane);
;             const float mu = wave_sum((v.x + v.y) + (v.z + v.w)) * (1.f / 256.f);
	v_lshlrev_b32_e32 v39, 16, v39
	v_fmac_f32_e32 v28, v51, v39
	v_fmac_f32_e32 v29, v53, v39
	v_fmac_f32_e32 v30, v54, v39
	v_fmac_f32_e32 v31, v55, v39
	v_fmac_f32_e32 v32, v56, v39
	v_fmac_f32_e32 v33, v57, v39
	v_fmac_f32_e32 v34, v58, v39
	v_fmac_f32_e32 v35, v59, v39
	v_fmac_f32_e32 v36, v60, v39
	v_fmac_f32_e32 v37, v61, v39
	v_fmac_f32_e32 v38, v62, v39
	v_fmac_f32_e32 v52, v63, v39
	ds_read_u16 v39, v11 offset:26112
	s_waitcnt lgkmcnt(0)
	v_lshlrev_b32_e32 v39, 16, v39
	v_fmac_f32_e32 v29, v51, v39
	v_fmac_f32_e32 v30, v53, v39
	v_fmac_f32_e32 v31, v54, v39
	v_fmac_f32_e32 v32, v55, v39
	v_fmac_f32_e32 v33, v56, v39
	v_fmac_f32_e32 v34, v57, v39
	v_fmac_f32_e32 v35, v58, v39
	v_fmac_f32_e32 v36, v59, v39
	v_fmac_f32_e32 v37, v60, v39
	v_fmac_f32_e32 v38, v61, v39
	v_fmac_f32_e32 v52, v62, v39
	ds_read_u16 v39, v11 offset:26624
	s_waitcnt lgkmcnt(0)
	v_lshlrev_b32_e32 v39, 16, v39
	v_fmac_f32_e32 v30, v51, v39
	v_fmac_f32_e32 v31, v53, v39
	v_fmac_f32_e32 v32, v54, v39
	v_fmac_f32_e32 v33, v55, v39
	v_fmac_f32_e32 v34, v56, v39
	v_fmac_f32_e32 v35, v57, v39
	v_fmac_f32_e32 v36, v58, v39
	v_fmac_f32_e32 v37, v59, v39
	v_fmac_f32_e32 v38, v60, v39
	v_fmac_f32_e32 v52, v61, v39
	ds_read_u16 v39, v11 offset:27136
	s_waitcnt lgkmcnt(0)
	v_lshlrev_b32_e32 v39, 16, v39
	v_fmac_f32_e32 v31, v51, v39
	v_fmac_f32_e32 v32, v53, v39
	v_fmac_f32_e32 v33, v54, v39
	v_fmac_f32_e32 v34, v55, v39
	v_fmac_f32_e32 v35, v56, v39
	v_fmac_f32_e32 v36, v57, v39
	v_fmac_f32_e32 v37, v58, v39
	v_fmac_f32_e32 v38, v59, v39
	v_fmac_f32_e32 v52, v60, v39
	ds_read_u16 v39, v11 offset:27648
	s_waitcnt lgkmcnt(0)
	v_lshlrev_b32_e32 v39, 16, v39
	v_fmac_f32_e32 v32, v51, v39
	v_fmac_f32_e32 v33, v53, v39
	v_fmac_f32_e32 v34, v54, v39
	v_fmac_f32_e32 v35, v55, v39
	v_fmac_f32_e32 v36, v56, v39
	v_fmac_f32_e32 v37, v57, v39
	v_fmac_f32_e32 v38, v58, v39
	v_fmac_f32_e32 v52, v59, v39
	ds_read_u16 v39, v11 offset:28160
	s_waitcnt lgkmcnt(0)
	v_lshlrev_b32_e32 v39, 16, v39
	v_fmac_f32_e32 v33, v51, v39
	v_fmac_f32_e32 v34, v53, v39
	v_fmac_f32_e32 v35, v54, v39
	v_fmac_f32_e32 v36, v55, v39
	v_fmac_f32_e32 v37, v56, v39
	v_fmac_f32_e32 v38, v57, v39
	v_fmac_f32_e32 v52, v58, v39
	ds_read_u16 v39, v11 offset:28672
	s_waitcnt lgkmcnt(0)
	v_lshlrev_b32_e32 v39, 16, v39
	v_fmac_f32_e32 v34, v51, v39
	v_fmac_f32_e32 v35, v53, v39
	v_fmac_f32_e32 v36, v54, v39
	v_fmac_f32_e32 v37, v55, v39
	v_fmac_f32_e32 v38, v56, v39
	v_fmac_f32_e32 v52, v57, v39
	ds_read_u16 v39, v11 offset:29184
	s_waitcnt lgkmcnt(0)
	v_lshlrev_b32_e32 v39, 16, v39
	v_fmac_f32_e32 v35, v51, v39
	v_fmac_f32_e32 v36, v53, v39
	v_fmac_f32_e32 v37, v54, v39
	v_fmac_f32_e32 v38, v55, v39
	v_fmac_f32_e32 v52, v56, v39
	ds_read_u16 v39, v11 offset:29696
	s_waitcnt lgkmcnt(0)
	v_lshlrev_b32_e32 v39, 16, v39
	v_fmac_f32_e32 v36, v51, v39
	v_fmac_f32_e32 v37, v53, v39
	v_fmac_f32_e32 v38, v54, v39
	v_fmac_f32_e32 v52, v55, v39
	ds_read_u16 v39, v11 offset:30208
	s_waitcnt lgkmcnt(0)
	v_lshlrev_b32_e32 v39, 16, v39
	v_fmac_f32_e32 v37, v51, v39
	v_fmac_f32_e32 v38, v53, v39
	v_fmac_f32_e32 v52, v54, v39
	ds_read_u16 v39, v11 offset:30720
	ds_read_u16 v11, v11 offset:31232
	s_waitcnt lgkmcnt(1)
	v_lshlrev_b32_e32 v39, 16, v39
	v_fmac_f32_e32 v52, v53, v39
	s_waitcnt lgkmcnt(0)
	v_lshlrev_b32_e32 v11, 16, v11
	v_fmac_f32_e32 v38, v51, v39
	v_fmac_f32_e32 v52, v51, v11
	ds_write2st64_b32 v6, v7, v8 offset1:4
	ds_write2st64_b32 v6, v9, v10 offset0:8 offset1:12
	ds_write2st64_b32 v6, v12, v13 offset0:16 offset1:20
	ds_write2st64_b32 v6, v14, v15 offset0:24 offset1:28
	ds_write2st64_b32 v6, v16, v17 offset0:32 offset1:36
	ds_write2st64_b32 v6, v18, v19 offset0:40 offset1:44
	ds_write2st64_b32 v6, v20, v21 offset0:48 offset1:52
	ds_write2st64_b32 v6, v22, v23 offset0:56 offset1:60
	ds_write2st64_b32 v6, v24, v25 offset0:64 offset1:68
	ds_write2st64_b32 v6, v26, v27 offset0:72 offset1:76
	ds_write2st64_b32 v6, v28, v29 offset0:80 offset1:84
	ds_write2st64_b32 v6, v30, v31 offset0:88 offset1:92
	ds_write2st64_b32 v6, v32, v33 offset0:96 offset1:100
	ds_write2st64_b32 v6, v34, v35 offset0:104 offset1:108
	ds_write2st64_b32 v6, v36, v37 offset0:112 offset1:116
	ds_write2st64_b32 v6, v38, v52 offset0:120 offset1:124
	v_lshlrev_b64 v[10:11], 4, v[130:131]
	s_waitcnt lgkmcnt(0)
	s_barrier
	v_lshl_add_u64 v[6:7], s[12:13], 0, v[10:11]
	v_lshl_add_u64 v[10:11], s[34:35], 0, v[10:11]
	global_load_dwordx4 v[6:9], v[6:7], off
	v_and_b32_e32 v14, 64, v230
	global_load_dwordx4 v[10:13], v[10:11], off
	v_add_u32_e32 v14, 64, v14
	v_xor_b32_e32 v15, 1, v230
	v_cmp_lt_i32_e32 vcc, v15, v14
	v_lshlrev_b32_e32 v22, 4, v130
	v_add3_u32 v22, v50, s88, v22
	v_cndmask_b32_e32 v15, v230, v15, vcc
	v_lshlrev_b32_e32 v16, 2, v15
	v_xor_b32_e32 v15, 2, v230
	v_cmp_lt_i32_e32 vcc, v15, v14
	s_nop 1
	v_cndmask_b32_e32 v15, v230, v15, vcc
	v_lshlrev_b32_e32 v17, 2, v15
	v_xor_b32_e32 v15, 4, v230
	v_cmp_lt_i32_e32 vcc, v15, v14
	s_nop 1
	v_cndmask_b32_e32 v15, v230, v15, vcc
	v_lshlrev_b32_e32 v18, 2, v15
	v_xor_b32_e32 v15, 8, v230
	v_cmp_lt_i32_e32 vcc, v15, v14
	s_nop 1
	v_cndmask_b32_e32 v15, v230, v15, vcc
	v_lshlrev_b32_e32 v19, 2, v15
	v_xor_b32_e32 v15, 16, v230
	v_cmp_lt_i32_e32 vcc, v15, v14
	s_nop 1
	v_cndmask_b32_e32 v15, v230, v15, vcc
	v_lshlrev_b32_e32 v20, 2, v15
	v_xor_b32_e32 v15, 32, v230
	v_cmp_lt_i32_e32 vcc, v15, v14
	s_nop 1
	v_cndmask_b32_e32 v14, v230, v15, vcc
	v_lshlrev_b32_e32 v21, 2, v14
	v_lshlrev_b32_e32 v14, 2, v130
	v_ashrrev_i32_e32 v15, 31, v14
	v_lshl_add_u64 v[14:15], v[14:15], 1, s[4:5]
	s_waitcnt vmcnt(0)

; __device__ __forceinline__ float fexp(float x) { return __expf(x); }
; __device__ __forceinline__ float frcp(float x) { return __builtin_amdgcn_rcpf(x); }
; __device__ __forceinline__ float sigmoid_f(float x) { return frcp(1.0f + fexp(-x)); }
; #define LBAR() do { asm volatile("s_waitcnt lgkmcnt(0)" ::: "memory"); __builtin_amdgcn_s_barrier(); asm volatile("" ::: "memory"); } while (0)
; __device__ __forceinline__ void hgrn_unit(const Ctx& X, LAS unsigned char* hl, int b, int c, int h, int tid_h, int w4, int lane, int layer) {
;     ...
;             const float lb = layer == 0 ? 0.f : sigmoid_f(X.in[12][256 + ch] - X.in[12][ch]);
;             const float f = ff[e];
;             const float ls = fminf(f, 0.f) - __logf(1.0f + fexp(-fabsf(f)));
;             const float lf = layer == 0 ? ls : __logf(lb + (1.f - lb) * fexp(ls));
;             kk[e] = (1.f - lb) * frcp(1.f + fexp(f));
;             Gt[i * 64 + ds + e] = lf;
;         }
;     }
;     LBAR();
; __device__ __forceinline__ void mixer_local_phase(const Ctx& X, LAS unsigned char* lds, int layer, int tid, int wave, int lane) {
;     ...
;     const int nit_ = (3584 + (int)gridDim.x - 1) / (int)gridDim.x;
;     for (int it_ = 0; it_ < nit_; ++it_) {
;         const int u = (int)blockIdx.x + (int)gridDim.x * ((it_ + (int)(blockIdx.x >> 3)) % nit_);
;         if (u >= 3584) continue;
;         asm volatile("" : "+v"(tid_h), "+v"(lane), "+v"(tid));
;         if (u < 3072) { const int mixer = u >> 10, idx = u & 1023, hp = idx & 1, cb = idx >> 1, b = cb >> 7, c = cb & 127, h = hp * 2 + hs;
.LBB0_299:
	v_and_b32_e32 v30, 0xffff0000, v25
	v_mul_f32_e64 v25, |v30|, s66
	v_exp_f32_e32 v25, v25
	v_ashrrev_i32_e32 v75, 6, v132
	v_lshlrev_b32_e32 v84, 2, v132
	v_and_b32_e32 v85, 0xfc, v84
	v_add_f32_e32 v25, 1.0, v25
	v_cmp_gt_f32_e32 vcc, s3, v25
	v_mov_b32_e32 v77, 0
	s_nop 0
	v_cndmask_b32_e64 v31, 0, 32, vcc
	v_ldexp_f32 v25, v25, v31
	v_log_f32_e32 v25, v25
	v_cndmask_b32_e32 v60, 0, v231, vcc
	v_max_f32_e32 v31, v30, v30
	v_min_f32_e32 v31, 0, v31
	v_mul_f32_e32 v61, 0x3f317217, v25
	v_fma_f32 v61, v25, s0, -v61
	v_fmac_f32_e32 v61, 0x3377d1cf, v25
	v_fmac_f32_e32 v61, 0x3f317217, v25
	v_cmp_lt_f32_e64 vcc, |v25|, s1
	s_nop 1
	v_cndmask_b32_e32 v25, v25, v61, vcc
	v_sub_f32_e32 v25, v25, v60
	v_sub_f32_e32 v25, v31, v25
	v_mul_f32_e32 v31, 0x3fb8aa3b, v25
	v_exp_f32_e32 v60, v31
	v_sub_f32_e32 v31, 1.0, v24
	v_fmac_f32_e32 v24, v60, v31
	v_cmp_gt_f32_e32 vcc, s3, v24
	s_nop 1
	v_cndmask_b32_e64 v60, 0, 32, vcc
	v_ldexp_f32 v24, v24, v60
	v_log_f32_e32 v24, v24
	v_cndmask_b32_e32 v60, 0, v231, vcc
	v_mul_f32_e32 v61, 0x3f317217, v24
	v_fma_f32 v61, v24, s0, -v61
	v_fmac_f32_e32 v61, 0x3377d1cf, v24
	v_fmac_f32_e32 v61, 0x3f317217, v24
	v_cmp_lt_f32_e64 vcc, |v24|, s1
	s_nop 1
	v_cndmask_b32_e32 v24, v24, v61, vcc
	v_sub_f32_e32 v24, v24, v60
	v_cndmask_b32_e64 v24, v24, v25, s[26:27]
	ds_write_b32 v35, v24 offset:60
	v_lshlrev_b32_e32 v24, 12, v75
	s_waitcnt lgkmcnt(0)
	s_barrier
	s_add_i32 s98, s20, 1
	s_cmp_ge_u32 s98, s70
	s_cbranch_scc1 .LpfH_done
	s_add_i32 s98, s98, s37
	s_mul_hi_u32 s99, s98, s87
	s_mul_i32 s99, s99, s70
	s_sub_i32 s98, s98, s99
	s_sub_i32 s99, s98, s70
	s_cmp_ge_u32 s98, s70
	s_cselect_b32 s98, s99, s98
	s_sub_i32 s99, s98, s70
	s_cmp_ge_u32 s98, s70
	s_cselect_b32 s98, s99, s98
	s_mul_i32 s98, s98, s18
	s_add_i32 s98, s98, s2
	v_lshrrev_b32_e32 v237, 3, v224
	v_and_b32_e32 v238, 7, v224
	s_cmpk_ge_u32 s98, 0xc00
	s_cbranch_scc1 .LpfH_conf
	s_lshr_b32 s99, s98, 10
	s_and_b32 s98, s98, 0x3ff
	s_and_b32 s100, s98, 1
	s_lshr_b32 s98, s98, 1
	s_cmp_eq_u32 s99, 2
	s_mul_i32 s99, s99, 0xc00
	s_cselect_b32 s101, 0x400, 0
	s_sub_u32 s99, s99, s101
	s_lshl_b32 s100, s100, 8
	s_add_u32 s99, s99, s100
	v_min_u32_e32 v238, 5, v238
	v_lshrrev_b32_e32 v239, 1, v238
	v_and_b32_e32 v238, 1, v238
	v_lshlrev_b32_e32 v239, 9, v239
	v_lshl_or_b32 v238, v238, 7, v239
	s_branch .LpfH_go

; #define LBAR() do { asm volatile("s_waitcnt lgkmcnt(0)" ::: "memory"); __builtin_amdgcn_s_barrier(); asm volatile("" ::: "memory"); } while (0)
; __device__ __forceinline__ void hgrn_unit(const Ctx& X, LAS unsigned char* hl, int b, int c, int h, int tid_h, int w4, int lane, int layer) {
;     ...
;         const int d = tid_h & 63, seg = tid_h >> 6; float cs[16]; float run = 0.f;
; #pragma unroll
;         for (int jj = 0; jj < 16; ++jj) { run += Gt[(16 * seg + jj) * 64 + d]; cs[jj] = run; }
;         tot[seg * 64 + d] = run;
;         LBAR();
;         float off = 0.f;
; #pragma unroll
;         for (int s = 0; s < 3; ++s) off += (s < seg) ? tot[s * 64 + d] : 0.f;
.LpfH_done:
	v_add3_u32 v24, v32, v24, v85
	ds_read2st64_b32 v[60:61], v24 offset1:1
	ds_read2st64_b32 v[64:65], v24 offset0:2 offset1:3
	ds_read2st64_b32 v[68:69], v24 offset0:4 offset1:5
	ds_read2st64_b32 v[78:79], v24 offset0:6 offset1:7
	v_cmp_lt_i32_e32 vcc, 0, v75
	s_waitcnt lgkmcnt(3)
	v_add_f32_e32 v66, 0, v60
	v_add_f32_e32 v67, v66, v61
	s_waitcnt lgkmcnt(2)
	v_add_f32_e32 v63, v67, v64
	v_add_f32_e32 v64, v63, v65
	s_waitcnt lgkmcnt(1)
	v_add_f32_e32 v60, v64, v68
	v_add_f32_e32 v61, v60, v69
	ds_read2st64_b32 v[68:69], v24 offset0:8 offset1:9
	s_waitcnt lgkmcnt(1)
	v_add_f32_e32 v25, v61, v78
	v_add_f32_e32 v65, v25, v79
	ds_read2st64_b32 v[78:79], v24 offset0:10 offset1:11
	ds_read2st64_b32 v[80:81], v24 offset0:12 offset1:13
	ds_read2st64_b32 v[82:83], v24 offset0:14 offset1:15
	s_waitcnt lgkmcnt(3)
	v_add_f32_e32 v95, v65, v68
	v_add_f32_e32 v96, v95, v69
	s_waitcnt lgkmcnt(2)
	v_add_f32_e32 v93, v96, v78
	v_add_f32_e32 v94, v93, v79
	s_waitcnt lgkmcnt(1)
	v_add_f32_e32 v91, v94, v80
	v_add_f32_e32 v92, v91, v81
	s_waitcnt lgkmcnt(0)
	v_add_f32_e32 v68, v92, v82
	v_add_f32_e32 v69, v68, v83
	v_add_u32_e32 v78, v40, v84
	ds_write_b32 v78, v69
	s_waitcnt lgkmcnt(0)
	s_barrier
	v_add_u32_e32 v78, v40, v85
	v_mov_b32_e32 v79, 0
	s_and_saveexec_b64 s[0:1], vcc
	s_cbranch_execz .LBB0_301
	ds_read_b32 v40, v78
	s_waitcnt lgkmcnt(0)
	v_add_f32_e32 v79, 0, v40

; #define LAS __attribute__((address_space(3)))
; #define LBAR() do { asm volatile("s_waitcnt lgkmcnt(0)" ::: "memory"); __builtin_amdgcn_s_barrier(); asm volatile("" ::: "memory"); } while (0)
; __device__ __forceinline__ void gdn_unit(const Ctx& X, LAS unsigned char* hl, int b, int c, int h, int tid_h, int w4, int lane, int layer) {
;     ...
;             Gs[tid_h] = g; Bs[tid_h] = bt;
;         }
; #pragma unroll
;         for (int n = 0; n < 7; ++n) { const int item = tid_h + 256 * n; if (item < 1608) *(LAS u32x4*)(RAW + (item >> 3) * 64 + (item & 7) * 8) = rawv[n]; }
;     }
;     LBAR();
; __device__ __forceinline__ void mixer_local_phase(const Ctx& X, LAS unsigned char* lds, int layer, int tid, int wave, int lane) {
;     ...
;     const int nit_ = (3584 + (int)gridDim.x - 1) / (int)gridDim.x;
;     for (int it_ = 0; it_ < nit_; ++it_) {
;         const int u = (int)blockIdx.x + (int)gridDim.x * ((it_ + (int)(blockIdx.x >> 3)) % nit_);
;         if (u >= 3584) continue;
;         asm volatile("" : "+v"(tid_h), "+v"(lane), "+v"(tid));
;         if (u < 3072) { const int mixer = u >> 10, idx = u & 1023, hp = idx & 1, cb = idx >> 1, b = cb >> 7, c = cb & 127, h = hp * 2 + hs;
.LBB0_349:
	s_or_b64 exec, exec, s[0:1]
	s_waitcnt vmcnt(0)
	v_and_b32_e32 v103, 64, v230
	v_xor_b32_e32 v102, 1, v230
	v_add_u32_e32 v103, 64, v103
	v_cmp_lt_i32_e32 vcc, v102, v103
	s_waitcnt lgkmcnt(0)
	s_barrier
	s_add_i32 s98, s20, 1
	s_cmp_ge_u32 s98, s70
	s_cbranch_scc1 .LpfG_done
	s_add_i32 s98, s98, s37
	s_mul_hi_u32 s99, s98, s87
	s_mul_i32 s99, s99, s70
	s_sub_i32 s98, s98, s99
	s_sub_i32 s99, s98, s70
	s_cmp_ge_u32 s98, s70
	s_cselect_b32 s98, s99, s98
	s_sub_i32 s99, s98, s70
	s_cmp_ge_u32 s98, s70
	s_cselect_b32 s98, s99, s98
	s_mul_i32 s98, s98, s18
	s_add_i32 s98, s98, s2
	v_lshrrev_b32_e32 v237, 3, v224
	v_and_b32_e32 v238, 7, v224
	s_cmpk_ge_u32 s98, 0xc00
	s_cbranch_scc1 .LpfG_conf
	s_lshr_b32 s99, s98, 10
	s_and_b32 s98, s98, 0x3ff
	s_and_b32 s100, s98, 1
	s_lshr_b32 s98, s98, 1
	s_cmp_eq_u32 s99, 2
	s_mul_i32 s99, s99, 0xc00
	s_cselect_b32 s101, 0x400, 0
	s_sub_u32 s99, s99, s101
	s_lshl_b32 s100, s100, 8
	s_add_u32 s99, s99, s100
	v_min_u32_e32 v238, 5, v238
	v_lshrrev_b32_e32 v239, 1, v238
	v_and_b32_e32 v238, 1, v238
	v_lshlrev_b32_e32 v239, 9, v239
	v_lshl_or_b32 v238, v238, 7, v239
	s_branch .LpfG_go

; #define LAS __attribute__((address_space(3)))
; __device__ __forceinline__ void gdn_unit(const Ctx& X, LAS unsigned char* hl, int b, int c, int h, int tid_h, int w4, int lane, int layer) {
;     ...
;         const float G63 = Gs[63];
; #pragma unroll
;         for (int rs = 0; rs < 2; ++rs) {
;             const int i = i0 + 32 * rs;
;             const float bi = Bs[i], Gi = Gs[i];
;             float y[3][8];
; #pragma unroll
;             for (int tn = 0; tn < 3; ++tn) {
; #pragma unroll
;                 for (int e = 0; e < 8; ++e) y[tn][e] = 0.f;
; #pragma unroll
;                 for (int k = 0; k < 4; ++k) { float x8[8]; unpack8(*(const LAS u32x4*)(RAW + (tn * 67 + i + k) * 64 + cseg * 8), x8);
;                     y[tn][0] += wq[tn][k][0].x * x8[0]; y[tn][1] += wq[tn][k][0].y * x8[1]; y[tn][2] += wq[tn][k][0].z * x8[2]; y[tn][3] += wq[tn][k][0].w * x8[3];
;                     y[tn][4] += wq[tn][k][1].x * x8[4]; y[tn][5] += wq[tn][k][1].y * x8[5]; y[tn][6] += wq[tn][k][1].z * x8[6]; y[tn][7] += wq[tn][k][1].w * x8[7]; }
.LpfG_done:
	v_add_u32_e32 v193, v182, v156
	v_cndmask_b32_e32 v102, v230, v102, vcc
	v_lshlrev_b32_e32 v197, 2, v102
	v_xor_b32_e32 v102, 2, v230
	v_cmp_lt_i32_e32 vcc, v102, v103
	v_add_u32_e32 v192, v189, v156
	v_add_u32_e32 v155, v183, v156
	v_add_u32_e32 v133, v181, v156
	v_lshl_add_u32 v156, v191, 7, v135
	ds_read_b32 v194, v185 offset:252
	v_cndmask_b32_e32 v102, v230, v102, vcc
	ds_read_b128 v[106:109], v156
	ds_read_b128 v[112:115], v156 offset:128
	v_lshlrev_b32_e32 v196, 2, v102
	v_xor_b32_e32 v102, 4, v230
	v_cmp_lt_i32_e32 vcc, v102, v103
	s_waitcnt lgkmcnt(1)
	v_lshlrev_b32_e32 v104, 16, v106
	s_waitcnt lgkmcnt(0)
	v_lshlrev_b32_e32 v105, 16, v112
	v_cndmask_b32_e32 v102, v230, v102, vcc
	v_lshlrev_b32_e32 v195, 2, v102
	v_lshlrev_b32_e32 v102, 2, v191
	v_add_u32_e32 v198, v188, v102
	v_add_u32_e32 v199, v185, v102
	v_mov_b32_e32 v102, v66
	v_mov_b32_e32 v103, v74
	v_pk_mul_f32 v[134:135], v[102:103], v[104:105]
	v_and_b32_e32 v105, 0xffff0000, v112
	v_and_b32_e32 v104, 0xffff0000, v106
	v_mov_b32_e32 v74, v67
	v_pk_mul_f32 v[136:137], v[74:75], v[104:105]
	v_lshlrev_b32_e32 v105, 16, v107
	v_lshlrev_b32_e32 v104, 16, v113
	v_mov_b32_e32 v66, v76
	v_mov_b32_e32 v67, v68
	ds_read_b32 v200, v198
	ds_read_b32 v201, v199
	v_pk_mul_f32 v[118:119], v[66:67], v[104:105]
	v_and_b32_e32 v105, 0xffff0000, v107
	v_and_b32_e32 v104, 0xffff0000, v113
	v_mov_b32_e32 v68, v77
	ds_read_b128 v[122:125], v156 offset:256
	ds_read_b128 v[126:129], v156 offset:384
	v_pk_mul_f32 v[120:121], v[68:69], v[104:105]
	v_lshlrev_b32_e32 v77, 16, v114
	v_lshlrev_b32_e32 v76, 16, v108
	v_mov_b32_e32 v104, v58
	v_mov_b32_e32 v105, v98
	v_pk_mul_f32 v[110:111], v[104:105], v[76:77]
	v_and_b32_e32 v77, 0xffff0000, v108
	v_and_b32_e32 v76, 0xffff0000, v114
	v_mov_b32_e32 v58, v99
	v_pk_mul_f32 v[112:113], v[58:59], v[76:77]
	v_lshlrev_b32_e32 v99, 16, v109
	v_lshlrev_b32_e32 v98, 16, v115
	v_mov_b32_e32 v76, v100
	v_mov_b32_e32 v77, v60
	v_pk_mul_f32 v[106:107], v[76:77], v[98:99]
	v_and_b32_e32 v99, 0xffff0000, v109
	v_and_b32_e32 v98, 0xffff0000, v115
	v_mov_b32_e32 v60, v101
	v_pk_mul_f32 v[108:109], v[60:61], v[98:99]
	s_waitcnt lgkmcnt(0)
	v_lshlrev_b32_e32 v101, 16, v126
	v_lshlrev_b32_e32 v100, 16, v122
	v_mov_b32_e32 v98, v62
	v_mov_b32_e32 v99, v70
	v_pk_mul_f32 v[150:151], v[98:99], v[100:101]
	v_and_b32_e32 v101, 0xffff0000, v126
	v_and_b32_e32 v100, 0xffff0000, v122
	v_mov_b32_e32 v70, v63
	v_pk_mul_f32 v[162:163], v[70:71], v[100:101]
	v_lshlrev_b32_e32 v101, 16, v123
	v_lshlrev_b32_e32 v100, 16, v127
	v_mov_b32_e32 v62, v72
	v_mov_b32_e32 v63, v64
	v_pk_mul_f32 v[138:139], v[62:63], v[100:101]
	v_and_b32_e32 v101, 0xffff0000, v123
	v_and_b32_e32 v100, 0xffff0000, v127
	v_mov_b32_e32 v64, v73
	ds_read_b128 v[144:147], v156 offset:8576
	ds_read_b128 v[164:167], v156 offset:8704
	v_pk_mul_f32 v[142:143], v[64:65], v[100:101]
	v_lshlrev_b32_e32 v73, 16, v128
	v_lshlrev_b32_e32 v72, 16, v124
	v_mov_b32_e32 v100, v54
	v_mov_b32_e32 v101, v94
	v_pk_mul_f32 v[122:123], v[100:101], v[72:73]
	v_and_b32_e32 v73, 0xffff0000, v124
	v_and_b32_e32 v72, 0xffff0000, v128
	v_mov_b32_e32 v54, v95
	v_pk_mul_f32 v[126:127], v[54:55], v[72:73]
	v_lshlrev_b32_e32 v95, 16, v125
	v_lshlrev_b32_e32 v94, 16, v129
	v_mov_b32_e32 v72, v96
	v_mov_b32_e32 v73, v56
	v_pk_mul_f32 v[114:115], v[72:73], v[94:95]
	v_and_b32_e32 v95, 0xffff0000, v125
	v_and_b32_e32 v94, 0xffff0000, v129
	v_mov_b32_e32 v56, v97
	v_pk_mul_f32 v[116:117], v[56:57], v[94:95]
	s_waitcnt lgkmcnt(0)
	v_lshlrev_b32_e32 v97, 16, v164
	v_lshlrev_b32_e32 v96, 16, v144
	v_mov_b32_e32 v94, v46
	v_mov_b32_e32 v95, v50
	v_pk_mul_f32 v[168:169], v[94:95], v[96:97]
	v_and_b32_e32 v97, 0xffff0000, v164
	v_and_b32_e32 v96, 0xffff0000, v144
	v_mov_b32_e32 v50, v47
	v_pk_mul_f32 v[170:171], v[50:51], v[96:97]
	v_lshlrev_b32_e32 v97, 16, v145
	v_lshlrev_b32_e32 v96, 16, v165
	v_mov_b32_e32 v46, v52
	v_mov_b32_e32 v47, v48
	v_pk_mul_f32 v[148:149], v[46:47], v[96:97]
	v_and_b32_e32 v97, 0xffff0000, v145
	v_and_b32_e32 v96, 0xffff0000, v165
	v_mov_b32_e32 v48, v53
	ds_read_b128 v[202:205], v156 offset:8832
	ds_read_b128 v[206:209], v156 offset:8960
	v_pk_mul_f32 v[152:153], v[48:49], v[96:97]
	v_lshlrev_b32_e32 v53, 16, v166
	v_lshlrev_b32_e32 v52, 16, v146
	v_mov_b32_e32 v96, v38
	v_mov_b32_e32 v97, v90
	v_pk_mul_f32 v[140:141], v[96:97], v[52:53]
	v_and_b32_e32 v53, 0xffff0000, v146
	v_and_b32_e32 v52, 0xffff0000, v166
	v_mov_b32_e32 v38, v91
	v_pk_mul_f32 v[144:145], v[38:39], v[52:53]
	v_lshlrev_b32_e32 v91, 16, v147
	v_lshlrev_b32_e32 v90, 16, v167
	v_mov_b32_e32 v52, v92
	v_mov_b32_e32 v53, v40
	v_pk_mul_f32 v[124:125], v[52:53], v[90:91]
	v_and_b32_e32 v91, 0xffff0000, v147
	v_and_b32_e32 v90, 0xffff0000, v167
	v_mov_b32_e32 v40, v93
	v_pk_mul_f32 v[128:129], v[40:41], v[90:91]
	s_waitcnt lgkmcnt(0)
	v_lshlrev_b32_e32 v93, 16, v206
	v_lshlrev_b32_e32 v92, 16, v202
	v_mov_b32_e32 v90, v34
	v_mov_b32_e32 v91, v42
	v_pk_mul_f32 v[176:177], v[90:91], v[92:93]
	v_and_b32_e32 v93, 0xffff0000, v206
	v_and_b32_e32 v92, 0xffff0000, v202
	v_mov_b32_e32 v42, v35
	v_pk_mul_f32 v[178:179], v[42:43], v[92:93]
	v_lshlrev_b32_e32 v93, 16, v203
	v_lshlrev_b32_e32 v92, 16, v207
	v_mov_b32_e32 v34, v44
	v_mov_b32_e32 v35, v36
	v_pk_mul_f32 v[172:173], v[34:35], v[92:93]
	v_and_b32_e32 v93, 0xffff0000, v203
	v_and_b32_e32 v92, 0xffff0000, v207
	v_mov_b32_e32 v36, v45
	ds_read_b128 v[210:213], v156 offset:17152
	ds_read_b128 v[214:217], v156 offset:17280
	v_pk_mul_f32 v[174:175], v[36:37], v[92:93]
	v_lshlrev_b32_e32 v45, 16, v208
	v_lshlrev_b32_e32 v44, 16, v204
	v_mov_b32_e32 v92, v30
	v_mov_b32_e32 v93, v86
	v_pk_mul_f32 v[164:165], v[92:93], v[44:45]
	v_and_b32_e32 v45, 0xffff0000, v204
	v_and_b32_e32 v44, 0xffff0000, v208
	v_mov_b32_e32 v30, v87
	v_pk_mul_f32 v[166:167], v[30:31], v[44:45]
	v_lshlrev_b32_e32 v87, 16, v205
	v_lshlrev_b32_e32 v86, 16, v209
	v_mov_b32_e32 v44, v88
	v_mov_b32_e32 v45, v32
	v_pk_mul_f32 v[146:147], v[44:45], v[86:87]
	v_and_b32_e32 v87, 0xffff0000, v205
	v_and_b32_e32 v86, 0xffff0000, v209
	v_mov_b32_e32 v32, v89
	v_pk_mul_f32 v[88:89], v[32:33], v[86:87]
	s_waitcnt lgkmcnt(0)
; #define LAS __attribute__((address_space(3)))
; __device__ __forceinline__ float silu_acc(float x) { return x * frcp(1.0f + fexp(-x)); }
; __device__ __forceinline__ void gdn_unit(const Ctx& X, LAS unsigned char* hl, int b, int c, int h, int tid_h, int w4, int lane, int layer) {
;     ...
;                 for (int k = 0; k < 4; ++k) { float x8[8]; unpack8(*(const LAS u32x4*)(RAW + (tn * 67 + i + k) * 64 + cseg * 8), x8);
;                     y[tn][0] += wq[tn][k][0].x * x8[0]; y[tn][1] += wq[tn][k][0].y * x8[1]; y[tn][2] += wq[tn][k][0].z * x8[2]; y[tn][3] += wq[tn][k][0].w * x8[3];
;                     y[tn][4] += wq[tn][k][1].x * x8[4]; y[tn][5] += wq[tn][k][1].y * x8[5]; y[tn][6] += wq[tn][k][1].z * x8[6]; y[tn][7] += wq[tn][k][1].w * x8[7]; }
; #pragma unroll
;                 for (int e = 0; e < 8; ++e) y[tn][e] = silu_acc(y[tn][e]);
;             }
;             float sq = 0.f, sk = 0.f;
; #pragma unroll
;             for (int e = 0; e < 8; ++e) { sq += y[0][e] * y[0][e]; sk += y[1][e] * y[1][e]; }
	v_lshlrev_b32_e32 v203, 16, v214
	v_lshlrev_b32_e32 v202, 16, v210
	v_mov_b32_e32 v86, v22
	v_mov_b32_e32 v87, v26
	v_pk_mul_f32 v[202:203], v[86:87], v[202:203]
	v_mov_b32_e32 v26, v23
	v_add_f32_e32 v22, 0, v202
	v_add_f32_e32 v218, v22, v203
	v_and_b32_e32 v203, 0xffff0000, v214
	v_and_b32_e32 v202, 0xffff0000, v210
	v_pk_mul_f32 v[22:23], v[26:27], v[202:203]
	v_lshlrev_b32_e32 v203, 16, v211
	v_add_f32_e32 v22, 0, v22
	v_add_f32_e32 v214, v22, v23
	v_lshlrev_b32_e32 v202, 16, v215
	v_mov_b32_e32 v22, v28
	v_mov_b32_e32 v23, v24
	v_pk_mul_f32 v[202:203], v[22:23], v[202:203]
	v_and_b32_e32 v210, 0xffff0000, v217
	v_add_f32_e32 v24, 0, v203
	v_add_f32_e32 v219, v202, v24
	v_and_b32_e32 v203, 0xffff0000, v211
	v_and_b32_e32 v202, 0xffff0000, v215
	v_mov_b32_e32 v24, v29
	v_pk_mul_f32 v[28:29], v[24:25], v[202:203]
	v_lshlrev_b32_e32 v203, 16, v216
	v_add_f32_e32 v29, 0, v29
	v_add_f32_e32 v215, v28, v29
	v_lshlrev_b32_e32 v202, 16, v212
	v_mov_b32_e32 v28, v14
	v_mov_b32_e32 v29, v82
	v_pk_mul_f32 v[202:203], v[28:29], v[202:203]
	v_and_b32_e32 v211, 0xffff0000, v213
	v_add_f32_e32 v14, 0, v202
	v_add_f32_e32 v220, v14, v203
	v_and_b32_e32 v203, 0xffff0000, v212
	v_and_b32_e32 v202, 0xffff0000, v216
	v_mov_b32_e32 v14, v83
	v_pk_mul_f32 v[82:83], v[14:15], v[202:203]
	v_lshlrev_b32_e32 v203, 16, v213
	v_add_f32_e32 v83, 0, v83
	v_add_f32_e32 v212, v82, v83
	v_lshlrev_b32_e32 v202, 16, v217
	v_mov_b32_e32 v82, v84
	v_mov_b32_e32 v83, v16
	v_pk_mul_f32 v[202:203], v[82:83], v[202:203]
	s_mov_b32 s4, 0x358637bd
	v_add_f32_e32 v16, 0, v203
	v_add_f32_e32 v216, v202, v16
	ds_read_b128 v[202:205], v156 offset:17408
	ds_read_b128 v[206:209], v156 offset:17536
	v_mov_b32_e32 v16, v85
	v_pk_mul_f32 v[84:85], v[16:17], v[210:211]
	s_waitcnt lgkmcnt(1)
	v_lshlrev_b32_e32 v210, 16, v202
	v_add_f32_e32 v85, 0, v85
	v_add_f32_e32 v213, v84, v85
	s_waitcnt lgkmcnt(0)
	v_lshlrev_b32_e32 v211, 16, v206
	v_mov_b32_e32 v84, v10
	v_mov_b32_e32 v85, v18
	v_pk_mul_f32 v[210:211], v[84:85], v[210:211]
	v_mov_b32_e32 v18, v11
	v_add_f32_e32 v10, v218, v210
	v_add_f32_e32 v217, v10, v211
	v_and_b32_e32 v211, 0xffff0000, v206
	v_and_b32_e32 v210, 0xffff0000, v202
	v_pk_mul_f32 v[10:11], v[18:19], v[210:211]
	v_lshlrev_b32_e32 v211, 16, v203
	v_add_f32_e32 v10, v214, v10
	v_add_f32_e32 v206, v10, v11
	v_lshlrev_b32_e32 v210, 16, v207
	v_mov_b32_e32 v10, v20
	v_mov_b32_e32 v11, v12
	v_pk_mul_f32 v[210:211], v[10:11], v[210:211]
	v_and_b32_e32 v203, 0xffff0000, v203
	v_add_f32_e32 v12, v211, v219
	v_add_f32_e32 v210, v210, v12
	v_and_b32_e32 v202, 0xffff0000, v207
	v_mov_b32_e32 v12, v21
	v_pk_mul_f32 v[20:21], v[12:13], v[202:203]
	v_lshlrev_b32_e32 v203, 16, v208
	v_add_f32_e32 v21, v21, v215
	v_add_f32_e32 v207, v20, v21
	v_lshlrev_b32_e32 v202, 16, v204
	v_mov_b32_e32 v20, v6
	v_mov_b32_e32 v21, v78
	v_pk_mul_f32 v[202:203], v[20:21], v[202:203]
	s_nop 0
	v_add_f32_e32 v6, v220, v202
	v_add_f32_e32 v211, v6, v203
	v_and_b32_e32 v203, 0xffff0000, v204
	v_and_b32_e32 v202, 0xffff0000, v208
	v_mov_b32_e32 v6, v79
	v_pk_mul_f32 v[78:79], v[6:7], v[202:203]
	v_lshlrev_b32_e32 v203, 16, v205
	v_add_f32_e32 v79, v79, v212
	v_add_f32_e32 v204, v78, v79
	v_lshlrev_b32_e32 v202, 16, v209
	v_mov_b32_e32 v78, v80
	v_mov_b32_e32 v79, v8
	v_pk_mul_f32 v[202:203], v[78:79], v[202:203]
	s_nop 0
	v_add_f32_e32 v8, v203, v216
	v_add_f32_e32 v208, v202, v8
	v_mul_f32_e32 v8, 0xbfb8aa3b, v217
	v_and_b32_e32 v203, 0xffff0000, v205
	v_exp_f32_e32 v205, v8
	v_and_b32_e32 v202, 0xffff0000, v209
	v_mov_b32_e32 v8, v81
	v_pk_mul_f32 v[80:81], v[8:9], v[202:203]
	v_mul_f32_e32 v203, 0xbfb8aa3b, v206
	v_exp_f32_e32 v203, v203
	v_add_f32_e32 v81, v81, v213
	v_add_f32_e32 v202, 1.0, v205
	v_add_f32_e32 v205, v80, v81
	v_add_f32_e32 v80, 1.0, v203
	v_mul_f32_e32 v203, 0xbfb8aa3b, v207
	v_mul_f32_e32 v81, 0xbfb8aa3b, v210
	v_exp_f32_e32 v203, v203
	v_exp_f32_e32 v81, v81
	v_mul_f32_e32 v209, 0xbfb8aa3b, v211
	v_rcp_f32_e32 v80, v80
	v_add_f32_e32 v203, 1.0, v203
	v_exp_f32_e32 v209, v209
	v_add_f32_e32 v81, 1.0, v81
	v_rcp_f32_e32 v203, v203
	v_rcp_f32_e32 v81, v81
	v_mul_f32_e32 v206, v206, v80
	v_add_f32_e32 v80, 1.0, v209
	v_mul_f32_e32 v203, v207, v203
	v_rcp_f32_e32 v207, v80
	v_mul_f32_e32 v80, 0xbfb8aa3b, v204
	v_mul_f32_e32 v210, v210, v81
	v_exp_f32_e32 v209, v80
	v_mov_b32_e32 v80, v134
	v_mov_b32_e32 v81, v136
	v_pk_add_f32 v[80:81], v[80:81], 0 op_sel_hi:[1,0]
	v_mov_b32_e32 v136, v135
	v_pk_add_f32 v[80:81], v[80:81], v[136:137]
	v_mov_b32_e32 v136, v168
	v_mov_b32_e32 v137, v170
	v_pk_add_f32 v[136:137], v[136:137], 0 op_sel_hi:[1,0]
	v_mov_b32_e32 v170, v169
	v_mov_b32_e32 v134, v150
	v_mov_b32_e32 v135, v162
	v_mov_b32_e32 v162, v151
	v_pk_add_f32 v[136:137], v[136:137], v[170:171]
	v_mov_b32_e32 v150, v176
	v_mov_b32_e32 v151, v178
	v_pk_add_f32 v[80:81], v[80:81], v[134:135]
	v_pk_add_f32 v[136:137], v[136:137], v[150:151]
	v_mov_b32_e32 v178, v177
	v_pk_add_f32 v[80:81], v[80:81], v[162:163]
	v_pk_add_f32 v[136:137], v[136:137], v[178:179]
	v_mul_f32_e32 v134, 0xbfb8aa3b, v80
	v_mul_f32_e32 v135, 0xbfb8aa3b, v81
	v_mul_f32_e32 v150, 0xbfb8aa3b, v136
	v_mul_f32_e32 v151, 0xbfb8aa3b, v137
	v_exp_f32_e32 v134, v134
	v_exp_f32_e32 v135, v135
	v_exp_f32_e32 v150, v150
	v_exp_f32_e32 v151, v151
	v_add_f32_e32 v134, 1.0, v134
	v_add_f32_e32 v135, 1.0, v135
	v_add_f32_e32 v150, 1.0, v150
	v_add_f32_e32 v151, 1.0, v151
	v_rcp_f32_e32 v134, v134
	v_rcp_f32_e32 v135, v135
	v_rcp_f32_e32 v150, v150
	v_rcp_f32_e32 v151, v151
	v_add_f32_e32 v162, 1.0, v209
	v_pk_mul_f32 v[134:135], v[80:81], v[134:135]
	v_rcp_f32_e32 v168, v162
	v_pk_mul_f32 v[80:81], v[136:137], v[150:151]
; __device__ __forceinline__ float silu_acc(float x) { return x * frcp(1.0f + fexp(-x)); }
; __device__ __forceinline__ void gdn_unit(const Ctx& X, LAS unsigned char* hl, int b, int c, int h, int tid_h, int w4, int lane, int layer) {
;     ...
;                 for (int e = 0; e < 8; ++e) y[tn][e] = silu_acc(y[tn][e]);
;             }
;             float sq = 0.f, sk = 0.f;
; #pragma unroll
;             for (int e = 0; e < 8; ++e) { sq += y[0][e] * y[0][e]; sk += y[1][e] * y[1][e]; }
;             sq += __shfl_xor(sq, 1); sq += __shfl_xor(sq, 2); sq += __shfl_xor(sq, 4);
;             sk += __shfl_xor(sk, 1); sk += __shfl_xor(sk, 2); sk += __shfl_xor(sk, 4);
	v_mov_b32_e32 v136, v121
	v_mov_b32_e32 v137, v119
	v_pk_add_f32 v[136:137], v[136:137], 0 op_sel_hi:[1,0]
	v_mov_b32_e32 v121, v118
	v_pk_add_f32 v[118:119], v[120:121], v[136:137]
	v_mov_b32_e32 v120, v143
	v_mov_b32_e32 v121, v139
	v_pk_add_f32 v[118:119], v[120:121], v[118:119]
	v_mov_b32_e32 v143, v138
	v_pk_add_f32 v[118:119], v[142:143], v[118:119]
	v_mov_b32_e32 v139, v149
	v_mul_f32_e32 v120, 0xbfb8aa3b, v119
	v_exp_f32_e32 v136, v120
	v_mul_f32_e32 v120, 0xbfb8aa3b, v118
	v_exp_f32_e32 v138, v120
	v_mov_b32_e32 v142, v175
	v_add_f32_e32 v136, 1.0, v136
	v_rcp_f32_e32 v137, v136
	v_add_f32_e32 v136, 1.0, v138
	v_mov_b32_e32 v138, v153
	v_pk_add_f32 v[138:139], v[138:139], 0 op_sel_hi:[1,0]
	v_mov_b32_e32 v153, v148
	v_pk_add_f32 v[138:139], v[152:153], v[138:139]
	v_mov_b32_e32 v143, v173
	v_pk_add_f32 v[138:139], v[142:143], v[138:139]
	v_mov_b32_e32 v175, v172
	v_pk_add_f32 v[138:139], v[174:175], v[138:139]
	v_rcp_f32_e32 v136, v136
	v_mul_f32_e32 v142, 0xbfb8aa3b, v139
	v_exp_f32_e32 v142, v142
	v_mul_f32_e32 v143, 0xbfb8aa3b, v138
	v_exp_f32_e32 v143, v143
	v_pk_mul_f32 v[118:119], v[118:119], v[136:137]
	v_add_f32_e32 v136, 1.0, v142
	v_rcp_f32_e32 v137, v136
	v_add_f32_e32 v136, 1.0, v143
	v_pk_mov_b32 v[142:143], v[112:113], v[110:111] op_sel:[1,0]
	v_mov_b32_e32 v113, v111
	v_pk_add_f32 v[142:143], v[142:143], 0 op_sel_hi:[1,0]
	v_rcp_f32_e32 v136, v136
	v_pk_add_f32 v[110:111], v[112:113], v[142:143]
	v_pk_mov_b32 v[112:113], v[126:127], v[122:123] op_sel:[1,0]
	v_mov_b32_e32 v127, v123
	v_pk_add_f32 v[110:111], v[112:113], v[110:111]
	v_mov_b32_e32 v143, v107
	v_pk_add_f32 v[112:113], v[126:127], v[110:111]
	v_pk_mul_f32 v[162:163], v[134:135], v[134:135]
	v_mul_f32_e32 v110, 0xbfb8aa3b, v113
	v_exp_f32_e32 v110, v110
	v_mul_f32_e32 v111, 0xbfb8aa3b, v112
	v_exp_f32_e32 v111, v111
	v_pk_mul_f32 v[120:121], v[80:81], v[80:81]
	v_add_f32_e32 v110, 1.0, v110
	v_rcp_f32_e32 v123, v110
	v_add_f32_e32 v110, 1.0, v111
	v_rcp_f32_e32 v122, v110
	v_pk_mul_f32 v[110:111], v[138:139], v[136:137]
	v_pk_mov_b32 v[138:139], v[166:167], v[164:165] op_sel:[1,0]
	v_mov_b32_e32 v167, v165
	v_pk_mul_f32 v[112:113], v[112:113], v[122:123]
	v_pk_mov_b32 v[122:123], v[144:145], v[140:141] op_sel:[1,0]
	v_mov_b32_e32 v145, v141
	v_pk_add_f32 v[122:123], v[122:123], 0 op_sel_hi:[1,0]
	v_pk_mul_f32 v[126:127], v[118:119], v[118:119]
	v_pk_add_f32 v[122:123], v[144:145], v[122:123]
	v_pk_mul_f32 v[136:137], v[110:111], v[110:111]
	v_pk_add_f32 v[122:123], v[138:139], v[122:123]
	v_rcp_f32_e32 v202, v202
	v_pk_add_f32 v[122:123], v[166:167], v[122:123]
	v_mul_f32_e32 v202, v217, v202
	v_mul_f32_e32 v138, 0xbfb8aa3b, v123
	v_exp_f32_e32 v140, v138
	v_mul_f32_e32 v138, 0xbfb8aa3b, v122
	v_exp_f32_e32 v142, v138
	v_pk_mul_f32 v[138:139], v[112:113], v[112:113]
	v_add_f32_e32 v140, 1.0, v140
	v_rcp_f32_e32 v141, v140
	v_add_f32_e32 v140, 1.0, v142
	v_mov_b32_e32 v142, v109
	v_pk_add_f32 v[142:143], v[142:143], 0 op_sel_hi:[1,0]
	v_mov_b32_e32 v109, v106
	v_pk_add_f32 v[106:107], v[108:109], v[142:143]
	v_mov_b32_e32 v108, v117
	v_mov_b32_e32 v109, v115
	v_pk_add_f32 v[106:107], v[108:109], v[106:107]
	v_mov_b32_e32 v117, v114
	v_pk_add_f32 v[106:107], v[116:117], v[106:107]
	v_rcp_f32_e32 v140, v140
	v_mul_f32_e32 v108, 0xbfb8aa3b, v107
	v_exp_f32_e32 v108, v108
	v_mul_f32_e32 v109, 0xbfb8aa3b, v106
	v_exp_f32_e32 v114, v109
	v_mov_b32_e32 v115, v125
	v_add_f32_e32 v108, 1.0, v108
	v_rcp_f32_e32 v109, v108
	v_add_f32_e32 v108, 1.0, v114
	v_mov_b32_e32 v114, v129
	v_pk_add_f32 v[114:115], v[114:115], 0 op_sel_hi:[1,0]
	v_mov_b32_e32 v129, v124
	v_pk_mul_f32 v[116:117], v[122:123], v[140:141]
	v_pk_add_f32 v[114:115], v[128:129], v[114:115]
	v_mov_b32_e32 v122, v89
	v_mov_b32_e32 v123, v147
	v_pk_add_f32 v[114:115], v[122:123], v[114:115]
	v_mov_b32_e32 v89, v146
	v_pk_add_f32 v[88:89], v[88:89], v[114:115]
	v_rcp_f32_e32 v108, v108
	v_mul_f32_e32 v114, 0xbfb8aa3b, v89
	v_exp_f32_e32 v114, v114
	v_mul_f32_e32 v115, 0xbfb8aa3b, v88
	v_exp_f32_e32 v122, v115
	v_mov_b32_e32 v124, v120
	v_add_f32_e32 v114, 1.0, v114
	v_rcp_f32_e32 v115, v114
	v_add_f32_e32 v114, 1.0, v122
	v_rcp_f32_e32 v114, v114
	v_mov_b32_e32 v125, v162
	v_mov_b32_e32 v162, v121
	v_pk_add_f32 v[120:121], v[124:125], v[162:163]
	v_mov_b32_e32 v124, v137
	v_mov_b32_e32 v125, v127
	v_pk_mul_f32 v[122:123], v[116:117], v[116:117]
	v_pk_add_f32 v[120:121], v[124:125], v[120:121]
	v_mov_b32_e32 v137, v126
	v_pk_mul_f32 v[106:107], v[106:107], v[108:109]
	v_pk_mul_f32 v[88:89], v[88:89], v[114:115]
	v_pk_add_f32 v[120:121], v[136:137], v[120:121]
	v_mov_b32_e32 v124, v123
	v_mov_b32_e32 v125, v139
	v_pk_mul_f32 v[108:109], v[106:107], v[106:107]
	v_pk_mul_f32 v[114:115], v[88:89], v[88:89]
	v_pk_add_f32 v[120:121], v[124:125], v[120:121]
	v_mov_b32_e32 v123, v138
	v_pk_add_f32 v[120:121], v[122:123], v[120:121]
	v_mov_b32_e32 v122, v115
	v_mov_b32_e32 v123, v109
	v_pk_add_f32 v[120:121], v[122:123], v[120:121]
	v_mov_b32_e32 v115, v108
	v_pk_add_f32 v[108:109], v[114:115], v[120:121]
	ds_bpermute_b32 v115, v197, v109
	ds_bpermute_b32 v114, v197, v108
	v_mul_f32_e32 v120, 0xbfb8aa3b, v208
	v_mul_f32_e32 v121, 0xbfb8aa3b, v205
	v_exp_f32_e32 v120, v120
	v_exp_f32_e32 v121, v121
	s_waitcnt lgkmcnt(0)
	v_pk_add_f32 v[108:109], v[108:109], v[114:115]
	ds_bpermute_b32 v115, v196, v109
	ds_bpermute_b32 v114, v196, v108
	v_add_f32_e32 v120, 1.0, v120
	v_add_f32_e32 v121, 1.0, v121
	v_rcp_f32_e32 v120, v120
	v_rcp_f32_e32 v121, v121
	s_waitcnt lgkmcnt(0)
	v_pk_add_f32 v[108:109], v[108:109], v[114:115]
	ds_bpermute_b32 v115, v195, v109
	ds_bpermute_b32 v114, v195, v108
	v_mul_f32_e32 v122, v211, v207
	v_mul_f32_e32 v123, v204, v168
	v_mul_f32_e32 v120, v208, v120
	v_mul_f32_e32 v121, v205, v121
	s_waitcnt lgkmcnt(0)
; #define LAS __attribute__((address_space(3)))
; __device__ __forceinline__ bf16_t f2bf(float f) { return (bf16_t)(pk2(f, 0.f) & 0xffffu); }
; __device__ __forceinline__ float fexp(float x) { return __expf(x); }
; __device__ __forceinline__ u32x4 pack8(const float (&f)[8]) { u32x4 w; w.x = pk2(f[0], f[1]); w.y = pk2(f[2], f[3]); w.z = pk2(f[4], f[5]); w.w = pk2(f[6], f[7]); return w; }
; __device__ __forceinline__ void gdn_unit(const Ctx& X, LAS unsigned char* hl, int b, int c, int h, int tid_h, int w4, int lane, int layer) {
;     ...
;             const float rq = 0.125f * rsqrtf(sq + 1e-6f), rk = rsqrtf(sk + 1e-6f), kd = rk * fexp(G63 - Gi);
;             float t8[8];
; #pragma unroll
;             for (int e = 0; e < 8; ++e) t8[e] = y[0][e] * rq;
;             *(LAS u32x4*)(Q + i * LT + cseg * 8) = pack8(t8);
; #pragma unroll
;             for (int e = 0; e < 8; ++e) t8[e] = y[1][e] * rk;
;             *(LAS u32x4*)(K + i * LT + cseg * 8) = pack8(t8);
; #pragma unroll
;             for (int e = 0; e < 8; ++e) t8[e] = y[1][e] * rk * bi;
;             *(LAS u32x4*)(KB + i * LT + cseg * 8) = pack8(t8);
;             *(LAS u32x4*)(V + i * LT + cseg * 8) = pack8(y[2]);
; #pragma unroll
;             for (int e = 0; e < 8; ++e) KDT[(cseg * 8 + e) * LT + i] = f2bf(y[1][e] * kd);
	v_pk_add_f32 v[108:109], v[108:109], v[114:115]
	v_sub_f32_e32 v115, v194, v201
	v_pk_add_f32 v[108:109], v[108:109], s[4:5] op_sel_hi:[1,0]
	v_mul_f32_e32 v115, 0x3fb8aa3b, v115
	v_mul_f32_e32 v114, 0x4b800000, v109
	v_cmp_gt_f32_e32 vcc, s3, v109
	v_cmp_gt_f32_e64 s[0:1], s3, v108
	v_exp_f32_e32 v124, v115
	v_cndmask_b32_e32 v109, v109, v114, vcc
	v_rsq_f32_e32 v109, v109
	v_mul_f32_e32 v114, 0x4b800000, v108
	v_cndmask_b32_e64 v108, v108, v114, s[0:1]
	v_rsq_f32_e32 v108, v108
	v_mul_f32_e32 v114, 0x45800000, v109
	v_cndmask_b32_e32 v109, v109, v114, vcc
	v_mul_f32_e32 v109, 0x3e000000, v109
	v_mul_f32_e32 v114, 0x45800000, v108
	v_mul_f32_e32 v115, v134, v109
	v_mul_f32_e32 v125, v135, v109
	v_mul_f32_e32 v119, v119, v109
	v_mul_f32_e32 v118, v118, v109
	v_mul_f32_e32 v126, v113, v109
	v_mul_f32_e32 v127, v112, v109
	v_mul_f32_e32 v107, v107, v109
	v_mul_f32_e32 v106, v106, v109
	v_cndmask_b32_e64 v109, v108, v114, s[0:1]
	v_mul_lo_u32 v108, v191, s44
	v_cvt_pk_bf16_f32 v112, v115, v125
	v_cvt_pk_bf16_f32 v113, v119, v118
	v_cvt_pk_bf16_f32 v114, v126, v127
	v_cvt_pk_bf16_f32 v115, v107, v106
	v_add_u32_e32 v106, v193, v108
	ds_write_b128 v106, v[112:115]
	v_mul_f32_e32 v106, v80, v109
	v_mul_f32_e32 v107, v81, v109
	v_mul_f32_e32 v118, v111, v109
	v_mul_f32_e32 v119, v110, v109
	v_mul_f32_e32 v125, v117, v109
	v_mul_f32_e32 v126, v116, v109
	v_mul_f32_e32 v127, v89, v109
	v_mul_f32_e32 v128, v88, v109
	v_cvt_pk_bf16_f32 v112, v106, v107
	v_cvt_pk_bf16_f32 v113, v118, v119
	v_cvt_pk_bf16_f32 v114, v125, v126
	v_cvt_pk_bf16_f32 v115, v127, v128
	v_add_u32_e32 v129, v192, v108
	v_mul_f32_e32 v106, v200, v106
	ds_write_b128 v129, v[112:115]
	v_mul_f32_e32 v107, v200, v107
	v_mul_f32_e32 v113, v200, v118
	v_mul_f32_e32 v114, v200, v119
	v_mul_f32_e32 v115, v200, v125
	v_cvt_pk_bf16_f32 v112, v106, v107
	v_add_u32_e32 v106, v155, v108
	v_mul_f32_e32 v118, v200, v126
	v_mul_f32_e32 v119, v200, v127
	v_mul_f32_e32 v125, v200, v128
	v_mul_f32_e32 v109, v124, v109
	v_cvt_pk_bf16_f32 v113, v113, v114
	v_cvt_pk_bf16_f32 v114, v115, v118
	v_cvt_pk_bf16_f32 v115, v119, v125
	ds_write_b128 v106, v[112:115]
	v_add_u32_e32 v106, v133, v108
	v_cvt_pk_bf16_f32 v112, v202, v206
	v_cvt_pk_bf16_f32 v113, v210, v203
	v_cvt_pk_bf16_f32 v114, v122, v123
	v_cvt_pk_bf16_f32 v115, v120, v121
	ds_write_b128 v106, v[112:115]
	v_lshlrev_b32_e32 v106, 1, v191
	v_mul_f32_e32 v80, v80, v109
	v_mul_u32_u24_e32 v107, 0x90, v190
	v_cvt_pk_bf16_f32 v80, v80, v157
	v_add3_u32 v107, v131, v106, v107
	ds_write_b16 v107, v80
	v_mul_f32_e32 v80, v81, v109
	v_cvt_pk_bf16_f32 v80, v80, v157
	ds_write_b16 v107, v80 offset:144
	v_mul_f32_e32 v80, v111, v109
	v_cvt_pk_bf16_f32 v80, v80, v157
	ds_write_b16 v107, v80 offset:288
	v_mul_f32_e32 v80, v110, v109
	v_cvt_pk_bf16_f32 v80, v80, v157
	ds_write_b16 v107, v80 offset:432
	v_mul_f32_e32 v80, v117, v109
	v_cvt_pk_bf16_f32 v80, v80, v157
	ds_write_b16 v107, v80 offset:576
	v_mul_f32_e32 v80, v116, v109
	v_cvt_pk_bf16_f32 v80, v80, v157
	ds_write_b16 v107, v80 offset:720
	v_mul_f32_e32 v80, v89, v109
	v_cvt_pk_bf16_f32 v80, v80, v157
	ds_write_b16 v107, v80 offset:864
	v_mul_f32_e32 v80, v88, v109
	v_cvt_pk_bf16_f32 v80, v80, v157
	ds_write_b16 v107, v80 offset:1008
	ds_read_b128 v[112:115], v156 offset:4224
	ds_read_b128 v[116:119], v156 offset:4096
	ds_read_b32 v109, v198 offset:128
	ds_read_b32 v110, v199 offset:128
	ds_read_b128 v[120:123], v156 offset:4352
	ds_read_b128 v[124:127], v156 offset:4480
	v_and_b32_e32 v106, 15, v130
	s_waitcnt lgkmcnt(5)
	v_lshlrev_b32_e32 v81, 16, v112
	s_waitcnt lgkmcnt(4)
	v_lshlrev_b32_e32 v80, 16, v116
	v_pk_mul_f32 v[88:89], v[102:103], v[80:81]
	v_and_b32_e32 v81, 0xffff0000, v112
	v_and_b32_e32 v80, 0xffff0000, v116
	v_pk_mul_f32 v[102:103], v[74:75], v[80:81]
	v_lshlrev_b32_e32 v75, 16, v117
	v_lshlrev_b32_e32 v74, 16, v113
	v_pk_mul_f32 v[74:75], v[66:67], v[74:75]
	v_and_b32_e32 v67, 0xffff0000, v117
	v_and_b32_e32 v66, 0xffff0000, v113
	v_pk_mul_f32 v[80:81], v[68:69], v[66:67]
	v_and_b32_e32 v69, 0xffff0000, v118
	v_and_b32_e32 v68, 0xffff0000, v114
	v_pk_mul_f32 v[68:69], v[58:59], v[68:69]
	v_lshlrev_b32_e32 v59, 16, v119
	v_lshlrev_b32_e32 v58, 16, v115
	v_pk_mul_f32 v[58:59], v[76:77], v[58:59]
	v_and_b32_e32 v77, 0xffff0000, v119
	v_and_b32_e32 v76, 0xffff0000, v115
	v_pk_mul_f32 v[60:61], v[60:61], v[76:77]
	s_waitcnt lgkmcnt(0)
	v_lshlrev_b32_e32 v77, 16, v124
	v_lshlrev_b32_e32 v76, 16, v120
	v_lshlrev_b32_e32 v67, 16, v114
	v_lshlrev_b32_e32 v66, 16, v118
	v_pk_mul_f32 v[98:99], v[98:99], v[76:77]
	v_and_b32_e32 v77, 0xffff0000, v124
	v_and_b32_e32 v76, 0xffff0000, v120
	v_pk_mul_f32 v[66:67], v[104:105], v[66:67]
	v_pk_mul_f32 v[104:105], v[70:71], v[76:77]
	v_lshlrev_b32_e32 v71, 16, v121
	v_lshlrev_b32_e32 v70, 16, v125
	ds_read_b128 v[112:115], v156 offset:12672
	ds_read_b128 v[116:119], v156 offset:12800
	v_pk_mul_f32 v[70:71], v[62:63], v[70:71]
	v_and_b32_e32 v63, 0xffff0000, v121
	v_and_b32_e32 v62, 0xffff0000, v125
	v_pk_mul_f32 v[76:77], v[64:65], v[62:63]
	v_and_b32_e32 v65, 0xffff0000, v122
	v_and_b32_e32 v64, 0xffff0000, v126
	v_pk_mul_f32 v[64:65], v[54:55], v[64:65]
	v_lshlrev_b32_e32 v55, 16, v123
	v_lshlrev_b32_e32 v54, 16, v127
	v_pk_mul_f32 v[54:55], v[72:73], v[54:55]
	v_and_b32_e32 v73, 0xffff0000, v123
	v_and_b32_e32 v72, 0xffff0000, v127
	v_pk_mul_f32 v[56:57], v[56:57], v[72:73]
	s_waitcnt lgkmcnt(0)
; #define LAS __attribute__((address_space(3)))
; __device__ __forceinline__ float silu_acc(float x) { return x * frcp(1.0f + fexp(-x)); }
; __device__ __forceinline__ void gdn_unit(const Ctx& X, LAS unsigned char* hl, int b, int c, int h, int tid_h, int w4, int lane, int layer) {
;     ...
;                 for (int k = 0; k < 4; ++k) { float x8[8]; unpack8(*(const LAS u32x4*)(RAW + (tn * 67 + i + k) * 64 + cseg * 8), x8);
;                     y[tn][0] += wq[tn][k][0].x * x8[0]; y[tn][1] += wq[tn][k][0].y * x8[1]; y[tn][2] += wq[tn][k][0].z * x8[2]; y[tn][3] += wq[tn][k][0].w * x8[3];
;                     y[tn][4] += wq[tn][k][1].x * x8[4]; y[tn][5] += wq[tn][k][1].y * x8[5]; y[tn][6] += wq[tn][k][1].z * x8[6]; y[tn][7] += wq[tn][k][1].w * x8[7]; }
; #pragma unroll
;                 for (int e = 0; e < 8; ++e) y[tn][e] = silu_acc(y[tn][e]);
	v_lshlrev_b32_e32 v73, 16, v116
	v_lshlrev_b32_e32 v72, 16, v112
	v_lshlrev_b32_e32 v63, 16, v126
	v_lshlrev_b32_e32 v62, 16, v122
	v_pk_mul_f32 v[94:95], v[94:95], v[72:73]
	v_and_b32_e32 v73, 0xffff0000, v116
	v_and_b32_e32 v72, 0xffff0000, v112
	v_pk_mul_f32 v[62:63], v[100:101], v[62:63]
	v_pk_mul_f32 v[100:101], v[50:51], v[72:73]
	v_lshlrev_b32_e32 v51, 16, v113
	v_lshlrev_b32_e32 v50, 16, v117
	ds_read_b128 v[120:123], v156 offset:12928
	ds_read_b128 v[124:127], v156 offset:13056
	v_pk_mul_f32 v[50:51], v[46:47], v[50:51]
	v_and_b32_e32 v47, 0xffff0000, v113
	v_and_b32_e32 v46, 0xffff0000, v117
	v_pk_mul_f32 v[72:73], v[48:49], v[46:47]
	v_and_b32_e32 v49, 0xffff0000, v114
	v_and_b32_e32 v48, 0xffff0000, v118
	v_pk_mul_f32 v[48:49], v[38:39], v[48:49]
	v_lshlrev_b32_e32 v39, 16, v115
	v_lshlrev_b32_e32 v38, 16, v119
	v_pk_mul_f32 v[38:39], v[52:53], v[38:39]
	v_and_b32_e32 v53, 0xffff0000, v115
	v_and_b32_e32 v52, 0xffff0000, v119
	v_pk_mul_f32 v[40:41], v[40:41], v[52:53]
	s_waitcnt lgkmcnt(0)
	v_lshlrev_b32_e32 v53, 16, v124
	v_lshlrev_b32_e32 v52, 16, v120
	v_lshlrev_b32_e32 v47, 16, v118
	v_lshlrev_b32_e32 v46, 16, v114
	v_pk_mul_f32 v[90:91], v[90:91], v[52:53]
	v_and_b32_e32 v53, 0xffff0000, v124
	v_and_b32_e32 v52, 0xffff0000, v120
	v_pk_mul_f32 v[46:47], v[96:97], v[46:47]
	v_pk_mul_f32 v[96:97], v[42:43], v[52:53]
	v_lshlrev_b32_e32 v43, 16, v121
	v_lshlrev_b32_e32 v42, 16, v125
	ds_read_b128 v[112:115], v156 offset:21248
	ds_read_b128 v[116:119], v156 offset:21376
	v_pk_mul_f32 v[42:43], v[34:35], v[42:43]
	v_and_b32_e32 v35, 0xffff0000, v121
	v_and_b32_e32 v34, 0xffff0000, v125
	v_pk_mul_f32 v[52:53], v[36:37], v[34:35]
	v_and_b32_e32 v37, 0xffff0000, v122
	v_and_b32_e32 v36, 0xffff0000, v126
	v_pk_mul_f32 v[36:37], v[30:31], v[36:37]
	v_lshlrev_b32_e32 v31, 16, v123
	v_lshlrev_b32_e32 v30, 16, v127
	v_pk_mul_f32 v[30:31], v[44:45], v[30:31]
	v_and_b32_e32 v45, 0xffff0000, v123
	v_and_b32_e32 v44, 0xffff0000, v127
	v_pk_mul_f32 v[32:33], v[32:33], v[44:45]
	s_waitcnt lgkmcnt(0)
	v_lshlrev_b32_e32 v45, 16, v116
	v_lshlrev_b32_e32 v44, 16, v112
	v_pk_mul_f32 v[44:45], v[86:87], v[44:45]
	v_lshlrev_b32_e32 v35, 16, v126
	v_add_f32_e32 v44, 0, v44
	v_add_f32_e32 v86, v44, v45
	v_and_b32_e32 v45, 0xffff0000, v116
	v_and_b32_e32 v44, 0xffff0000, v112
	v_pk_mul_f32 v[26:27], v[26:27], v[44:45]
	v_lshlrev_b32_e32 v34, 16, v122
	v_add_f32_e32 v26, 0, v26
	v_add_f32_e32 v44, v26, v27
	v_lshlrev_b32_e32 v27, 16, v113
	v_lshlrev_b32_e32 v26, 16, v117
	v_pk_mul_f32 v[22:23], v[22:23], v[26:27]
	v_pk_mul_f32 v[34:35], v[92:93], v[34:35]
	v_add_f32_e32 v23, 0, v23
	v_add_f32_e32 v45, v22, v23
	v_and_b32_e32 v23, 0xffff0000, v113
	v_and_b32_e32 v22, 0xffff0000, v117
	v_pk_mul_f32 v[22:23], v[24:25], v[22:23]
	s_nop 0
	v_add_f32_e32 v23, 0, v23
	v_add_f32_e32 v87, v22, v23
	v_lshlrev_b32_e32 v23, 16, v118
	v_lshlrev_b32_e32 v22, 16, v114
	v_pk_mul_f32 v[22:23], v[28:29], v[22:23]
	s_nop 0
	v_add_f32_e32 v22, 0, v22
	v_add_f32_e32 v92, v22, v23
	v_and_b32_e32 v23, 0xffff0000, v114
	v_and_b32_e32 v22, 0xffff0000, v118
	v_pk_mul_f32 v[14:15], v[14:15], v[22:23]
	ds_read_b128 v[22:25], v156 offset:21504
	ds_read_b128 v[26:29], v156 offset:21632
	v_add_f32_e32 v15, 0, v15
	v_add_f32_e32 v93, v14, v15
	v_lshlrev_b32_e32 v15, 16, v115
	v_lshlrev_b32_e32 v14, 16, v119
	v_pk_mul_f32 v[14:15], v[82:83], v[14:15]
	s_nop 0
	v_add_f32_e32 v15, 0, v15
	v_add_f32_e32 v82, v14, v15
	v_and_b32_e32 v15, 0xffff0000, v115
	v_and_b32_e32 v14, 0xffff0000, v119
	v_pk_mul_f32 v[14:15], v[16:17], v[14:15]
	s_nop 0
	v_add_f32_e32 v15, 0, v15
	v_add_f32_e32 v16, v14, v15
	s_waitcnt lgkmcnt(0)
	v_lshlrev_b32_e32 v15, 16, v26
	v_lshlrev_b32_e32 v14, 16, v22
	v_pk_mul_f32 v[14:15], v[84:85], v[14:15]
	s_nop 0
	v_add_f32_e32 v14, v86, v14
	v_add_f32_e32 v17, v14, v15
	v_and_b32_e32 v15, 0xffff0000, v26
	v_and_b32_e32 v14, 0xffff0000, v22
	v_pk_mul_f32 v[14:15], v[18:19], v[14:15]
	v_mov_b32_e32 v19, v51
	v_add_f32_e32 v14, v44, v14
	v_add_f32_e32 v18, v14, v15
	v_lshlrev_b32_e32 v15, 16, v23
	v_lshlrev_b32_e32 v14, 16, v27
	v_pk_mul_f32 v[10:11], v[10:11], v[14:15]
	s_nop 0
	v_add_f32_e32 v11, v11, v45
	v_add_f32_e32 v14, v10, v11
	v_and_b32_e32 v11, 0xffff0000, v23
	v_and_b32_e32 v10, 0xffff0000, v27
	v_pk_mul_f32 v[10:11], v[12:13], v[10:11]
	v_mov_b32_e32 v13, v96
	v_add_f32_e32 v11, v11, v87
	v_add_f32_e32 v12, v10, v11
	v_lshlrev_b32_e32 v11, 16, v28
	v_lshlrev_b32_e32 v10, 16, v24
	v_pk_mul_f32 v[10:11], v[20:21], v[10:11]
	v_mov_b32_e32 v96, v91
	v_add_f32_e32 v10, v92, v10
	v_add_f32_e32 v44, v10, v11
	v_and_b32_e32 v11, 0xffff0000, v24
	v_and_b32_e32 v10, 0xffff0000, v28
	v_pk_mul_f32 v[6:7], v[6:7], v[10:11]
	v_mov_b32_e32 v11, v100
	v_add_f32_e32 v7, v7, v93
	v_add_f32_e32 v45, v6, v7
	v_lshlrev_b32_e32 v7, 16, v25
	v_lshlrev_b32_e32 v6, 16, v29
	v_pk_mul_f32 v[6:7], v[78:79], v[6:7]
	v_mov_b32_e32 v100, v95
	v_add_f32_e32 v7, v7, v82
	v_add_f32_e32 v78, v6, v7
	v_mul_f32_e32 v6, 0xbfb8aa3b, v17
	v_exp_f32_e32 v10, v6
	v_and_b32_e32 v7, 0xffff0000, v25
	v_and_b32_e32 v6, 0xffff0000, v29
	v_pk_mul_f32 v[6:7], v[8:9], v[6:7]
	v_mul_f32_e32 v9, 0xbfb8aa3b, v18
	v_exp_f32_e32 v9, v9
	v_add_f32_e32 v8, 1.0, v10
	v_rcp_f32_e32 v8, v8
	v_add_f32_e32 v7, v7, v16
	v_add_f32_e32 v79, v6, v7
	v_add_f32_e32 v6, 1.0, v9
	v_mul_f32_e32 v9, 0xbfb8aa3b, v44
	v_mul_f32_e32 v7, 0xbfb8aa3b, v14
	v_rcp_f32_e32 v6, v6
	v_exp_f32_e32 v9, v9
	v_exp_f32_e32 v7, v7
	v_mul_f32_e32 v82, v17, v8
	v_mul_f32_e32 v8, 0xbfb8aa3b, v12
	v_exp_f32_e32 v8, v8
	v_mul_f32_e32 v83, v18, v6
	v_add_f32_e32 v6, 1.0, v9
	v_add_f32_e32 v7, 1.0, v7
	v_rcp_f32_e32 v86, v6
	v_mul_f32_e32 v6, 0xbfb8aa3b, v45
; __device__ __forceinline__ float silu_acc(float x) { return x * frcp(1.0f + fexp(-x)); }
; __device__ __forceinline__ void gdn_unit(const Ctx& X, LAS unsigned char* hl, int b, int c, int h, int tid_h, int w4, int lane, int layer) {
;     ...
;                 for (int e = 0; e < 8; ++e) y[tn][e] = silu_acc(y[tn][e]);
;             }
;             float sq = 0.f, sk = 0.f;
; #pragma unroll
;             for (int e = 0; e < 8; ++e) { sq += y[0][e] * y[0][e]; sk += y[1][e] * y[1][e]; }
;             sq += __shfl_xor(sq, 1); sq += __shfl_xor(sq, 2); sq += __shfl_xor(sq, 4);
;             sk += __shfl_xor(sk, 1); sk += __shfl_xor(sk, 2); sk += __shfl_xor(sk, 4);
	v_rcp_f32_e32 v7, v7
	v_exp_f32_e32 v10, v6
	v_add_f32_e32 v8, 1.0, v8
	v_rcp_f32_e32 v8, v8
	v_mul_f32_e32 v84, v14, v7
	v_mov_b32_e32 v6, v88
	v_mov_b32_e32 v7, v102
	v_add_f32_e32 v14, 1.0, v10
	v_mov_b32_e32 v10, v94
	v_pk_add_f32 v[6:7], v[6:7], 0 op_sel_hi:[1,0]
	v_mov_b32_e32 v102, v89
	v_pk_add_f32 v[10:11], v[10:11], 0 op_sel_hi:[1,0]
	v_mul_f32_e32 v85, v12, v8
	v_pk_add_f32 v[6:7], v[6:7], v[102:103]
	v_mov_b32_e32 v8, v98
	v_mov_b32_e32 v9, v104
	v_pk_add_f32 v[10:11], v[10:11], v[100:101]
	v_mov_b32_e32 v12, v90
	v_pk_add_f32 v[6:7], v[6:7], v[8:9]
	v_mov_b32_e32 v104, v99
	v_pk_add_f32 v[10:11], v[10:11], v[12:13]
	v_pk_add_f32 v[6:7], v[6:7], v[104:105]
	v_pk_add_f32 v[10:11], v[10:11], v[96:97]
	v_mul_f32_e32 v8, 0xbfb8aa3b, v6
	v_mul_f32_e32 v9, 0xbfb8aa3b, v7
	v_mul_f32_e32 v12, 0xbfb8aa3b, v10
	v_mul_f32_e32 v13, 0xbfb8aa3b, v11
	v_exp_f32_e32 v8, v8
	v_exp_f32_e32 v9, v9
	v_exp_f32_e32 v12, v12
	v_exp_f32_e32 v13, v13
	v_add_f32_e32 v8, 1.0, v8
	v_add_f32_e32 v9, 1.0, v9
	v_add_f32_e32 v12, 1.0, v12
	v_add_f32_e32 v13, 1.0, v13
	v_rcp_f32_e32 v8, v8
	v_rcp_f32_e32 v9, v9
	v_rcp_f32_e32 v12, v12
	v_rcp_f32_e32 v13, v13
	v_mov_b32_e32 v20, v53
	v_pk_mul_f32 v[8:9], v[6:7], v[8:9]
	v_mov_b32_e32 v21, v43
	v_pk_mul_f32 v[6:7], v[10:11], v[12:13]
	v_mov_b32_e32 v10, v81
	v_mov_b32_e32 v11, v75
	v_pk_add_f32 v[10:11], v[10:11], 0 op_sel_hi:[1,0]
	v_mov_b32_e32 v81, v74
	v_pk_add_f32 v[10:11], v[80:81], v[10:11]
	v_mov_b32_e32 v12, v77
	v_mov_b32_e32 v13, v71
	v_pk_add_f32 v[10:11], v[12:13], v[10:11]
	v_mov_b32_e32 v77, v70
	v_pk_add_f32 v[10:11], v[76:77], v[10:11]
	v_mov_b32_e32 v53, v42
	v_mul_f32_e32 v12, 0xbfb8aa3b, v11
	v_exp_f32_e32 v16, v12
	v_mul_f32_e32 v12, 0xbfb8aa3b, v10
	v_exp_f32_e32 v18, v12
	v_pk_mov_b32 v[22:23], v[64:65], v[62:63] op_sel:[1,0]
	v_add_f32_e32 v16, 1.0, v16
	v_rcp_f32_e32 v17, v16
	v_add_f32_e32 v16, 1.0, v18
	v_mov_b32_e32 v18, v73
	v_pk_add_f32 v[18:19], v[18:19], 0 op_sel_hi:[1,0]
	v_mov_b32_e32 v73, v50
	v_pk_add_f32 v[18:19], v[72:73], v[18:19]
	v_rcp_f32_e32 v16, v16
	v_pk_add_f32 v[18:19], v[20:21], v[18:19]
	v_mov_b32_e32 v65, v63
	v_pk_add_f32 v[18:19], v[52:53], v[18:19]
	v_pk_mul_f32 v[10:11], v[10:11], v[16:17]
	v_mul_f32_e32 v20, 0xbfb8aa3b, v19
	v_exp_f32_e32 v20, v20
	v_mul_f32_e32 v21, 0xbfb8aa3b, v18
	v_exp_f32_e32 v21, v21
	v_pk_mov_b32 v[26:27], v[36:37], v[34:35] op_sel:[1,0]
	v_add_f32_e32 v16, 1.0, v20
	v_rcp_f32_e32 v17, v16
	v_add_f32_e32 v16, 1.0, v21
	v_pk_mov_b32 v[20:21], v[68:69], v[66:67] op_sel:[1,0]
	v_mov_b32_e32 v69, v67
	v_pk_add_f32 v[20:21], v[20:21], 0 op_sel_hi:[1,0]
	v_mov_b32_e32 v37, v35
	v_pk_add_f32 v[20:21], v[68:69], v[20:21]
	v_mov_b32_e32 v35, v59
	v_pk_add_f32 v[20:21], v[22:23], v[20:21]
	v_rcp_f32_e32 v16, v16
	v_pk_add_f32 v[20:21], v[64:65], v[20:21]
	v_rcp_f32_e32 v87, v14
	v_mul_f32_e32 v22, 0xbfb8aa3b, v21
	v_exp_f32_e32 v22, v22
	v_mul_f32_e32 v23, 0xbfb8aa3b, v20
	v_exp_f32_e32 v24, v23
	v_pk_mul_f32 v[14:15], v[8:9], v[8:9]
	v_add_f32_e32 v22, 1.0, v22
	v_rcp_f32_e32 v23, v22
	v_add_f32_e32 v22, 1.0, v24
	v_rcp_f32_e32 v22, v22
	v_pk_mul_f32 v[12:13], v[6:7], v[6:7]
	v_pk_mul_f32 v[16:17], v[18:19], v[16:17]
	v_pk_mul_f32 v[24:25], v[10:11], v[10:11]
	v_pk_mul_f32 v[20:21], v[20:21], v[22:23]
	v_pk_mov_b32 v[22:23], v[48:49], v[46:47] op_sel:[1,0]
	v_mov_b32_e32 v49, v47
	v_pk_add_f32 v[22:23], v[22:23], 0 op_sel_hi:[1,0]
	v_pk_mul_f32 v[18:19], v[16:17], v[16:17]
	v_pk_add_f32 v[22:23], v[48:49], v[22:23]
	v_ashrrev_i32_e32 v72, 4, v130
	v_pk_add_f32 v[22:23], v[26:27], v[22:23]
	v_lshlrev_b32_e32 v77, 2, v72
	v_pk_add_f32 v[22:23], v[36:37], v[22:23]
	v_mov_b32_e32 v36, v57
	v_mul_f32_e32 v26, 0xbfb8aa3b, v23
	v_exp_f32_e32 v28, v26
	v_mul_f32_e32 v26, 0xbfb8aa3b, v22
	v_exp_f32_e32 v34, v26
	v_mov_b32_e32 v37, v55
	v_add_f32_e32 v28, 1.0, v28
	v_rcp_f32_e32 v29, v28
	v_add_f32_e32 v28, 1.0, v34
	v_mov_b32_e32 v34, v61
	v_pk_add_f32 v[34:35], v[34:35], 0 op_sel_hi:[1,0]
	v_mov_b32_e32 v61, v58
	v_pk_add_f32 v[34:35], v[60:61], v[34:35]
	v_mov_b32_e32 v57, v54
	v_pk_add_f32 v[34:35], v[36:37], v[34:35]
	v_rcp_f32_e32 v28, v28
	v_pk_add_f32 v[34:35], v[56:57], v[34:35]
	v_pk_mul_f32 v[26:27], v[20:21], v[20:21]
	v_mul_f32_e32 v36, 0xbfb8aa3b, v35
	v_exp_f32_e32 v36, v36
	v_mul_f32_e32 v37, 0xbfb8aa3b, v34
	v_exp_f32_e32 v37, v37
	v_pk_mul_f32 v[22:23], v[22:23], v[28:29]
	v_add_f32_e32 v28, 1.0, v36
	v_rcp_f32_e32 v29, v28
	v_add_f32_e32 v28, 1.0, v37
	v_mov_b32_e32 v36, v41
	v_mov_b32_e32 v37, v39
	v_pk_add_f32 v[36:37], v[36:37], 0 op_sel_hi:[1,0]
	v_mov_b32_e32 v41, v38
	v_pk_add_f32 v[36:37], v[40:41], v[36:37]
	v_mov_b32_e32 v38, v33
	v_mov_b32_e32 v39, v31
	v_pk_add_f32 v[36:37], v[38:39], v[36:37]
	v_mov_b32_e32 v33, v30
	v_pk_add_f32 v[30:31], v[32:33], v[36:37]
	v_rcp_f32_e32 v28, v28
	v_mul_f32_e32 v32, 0xbfb8aa3b, v31
	v_exp_f32_e32 v32, v32
	v_mul_f32_e32 v33, 0xbfb8aa3b, v30
	v_exp_f32_e32 v36, v33
	v_mov_b32_e32 v38, v12
	v_add_f32_e32 v32, 1.0, v32
	v_rcp_f32_e32 v33, v32
	v_add_f32_e32 v32, 1.0, v36
	v_rcp_f32_e32 v32, v32
	v_mov_b32_e32 v39, v14
	v_mov_b32_e32 v14, v13
	v_pk_add_f32 v[12:13], v[38:39], v[14:15]
	v_mov_b32_e32 v14, v19
	v_mov_b32_e32 v15, v25
	v_pk_mul_f32 v[36:37], v[22:23], v[22:23]
	v_pk_add_f32 v[12:13], v[14:15], v[12:13]
	v_mov_b32_e32 v19, v24
	v_pk_mul_f32 v[28:29], v[34:35], v[28:29]
	v_pk_mul_f32 v[30:31], v[30:31], v[32:33]
	v_pk_add_f32 v[12:13], v[18:19], v[12:13]
	v_mov_b32_e32 v14, v37
	v_mov_b32_e32 v15, v27
	v_pk_mul_f32 v[34:35], v[28:29], v[28:29]
	v_pk_mul_f32 v[32:33], v[30:31], v[30:31]
	v_pk_add_f32 v[12:13], v[14:15], v[12:13]
	v_mov_b32_e32 v37, v26
	v_pk_add_f32 v[12:13], v[36:37], v[12:13]
	v_mov_b32_e32 v14, v33
	v_mov_b32_e32 v15, v35
	v_pk_add_f32 v[12:13], v[14:15], v[12:13]
	v_mov_b32_e32 v33, v34
	v_pk_add_f32 v[12:13], v[32:33], v[12:13]
	ds_bpermute_b32 v15, v197, v13
	ds_bpermute_b32 v14, v197, v12
	v_mul_f32_e32 v18, 0xbfb8aa3b, v78
	v_mul_f32_e32 v19, 0xbfb8aa3b, v79
	v_exp_f32_e32 v18, v18
	v_exp_f32_e32 v19, v19
	s_waitcnt lgkmcnt(0)
; #define LAS __attribute__((address_space(3)))
; __device__ __forceinline__ bf16_t f2bf(float f) { return (bf16_t)(pk2(f, 0.f) & 0xffffu); }
; __device__ __forceinline__ float fexp(float x) { return __expf(x); }
; __device__ __forceinline__ u32x4 pack8(const float (&f)[8]) { u32x4 w; w.x = pk2(f[0], f[1]); w.y = pk2(f[2], f[3]); w.z = pk2(f[4], f[5]); w.w = pk2(f[6], f[7]); return w; }
; #define LBAR() do { asm volatile("s_waitcnt lgkmcnt(0)" ::: "memory"); __builtin_amdgcn_s_barrier(); asm volatile("" ::: "memory"); } while (0)
; __device__ __forceinline__ void gdn_unit(const Ctx& X, LAS unsigned char* hl, int b, int c, int h, int tid_h, int w4, int lane, int layer) {
;     ...
;             const float rq = 0.125f * rsqrtf(sq + 1e-6f), rk = rsqrtf(sk + 1e-6f), kd = rk * fexp(G63 - Gi);
;             float t8[8];
; #pragma unroll
;             for (int e = 0; e < 8; ++e) t8[e] = y[0][e] * rq;
;             *(LAS u32x4*)(Q + i * LT + cseg * 8) = pack8(t8);
; #pragma unroll
;             for (int e = 0; e < 8; ++e) t8[e] = y[1][e] * rk;
;             *(LAS u32x4*)(K + i * LT + cseg * 8) = pack8(t8);
; #pragma unroll
;             for (int e = 0; e < 8; ++e) t8[e] = y[1][e] * rk * bi;
;             *(LAS u32x4*)(KB + i * LT + cseg * 8) = pack8(t8);
;             *(LAS u32x4*)(V + i * LT + cseg * 8) = pack8(y[2]);
; #pragma unroll
;             for (int e = 0; e < 8; ++e) KDT[(cseg * 8 + e) * LT + i] = f2bf(y[1][e] * kd);
;         }
;     }
;     LBAR();
;     }
;     {
;         f32x4 aA[4], aP[4];
; #pragma unroll
;         for (int ct = 0; ct < 4; ++ct) { aA[ct] = mma16(KB, 16 * w4, K, 16 * ct, (f32x4){0.f, 0.f, 0.f, 0.f}, r, q); aP[ct] = mma16(Q, 16 * w4, K, 16 * ct, (f32x4){0.f, 0.f, 0.f, 0.f}, r, q); }
; #pragma unroll
;         for (int ct = 0; ct < 4; ++ct)
; #pragma unroll
;             for (int j = 0; j < 4; ++j) { const int ii = 16 * w4 + 4 * q + j, col = 16 * ct + r;
;                 const float L = fexp(fminf(Gs[ii] - Gs[col], 0.f));
;                 AB[ii * LT + col] = f2bf(ii > col ? aA[ct][j] * L : 0.f);
;                 P[ii * LT + col] = f2bf(ii >= col ? aP[ct][j] * L : 0.f); }
	v_pk_add_f32 v[12:13], v[12:13], v[14:15]
	ds_bpermute_b32 v15, v196, v13
	ds_bpermute_b32 v14, v196, v12
	v_add_f32_e32 v18, 1.0, v18
	v_add_f32_e32 v19, 1.0, v19
	v_rcp_f32_e32 v18, v18
	v_rcp_f32_e32 v19, v19
	s_waitcnt lgkmcnt(0)
	v_pk_add_f32 v[12:13], v[12:13], v[14:15]
	ds_bpermute_b32 v15, v195, v13
	ds_bpermute_b32 v14, v195, v12
	v_mul_f32_e32 v24, v44, v86
	v_mul_f32_e32 v25, v45, v87
	v_mul_f32_e32 v18, v78, v18
	v_mul_f32_e32 v19, v79, v19
	s_waitcnt lgkmcnt(0)
	v_pk_add_f32 v[12:13], v[12:13], v[14:15]
	v_sub_f32_e32 v15, v194, v110
	v_pk_add_f32 v[12:13], v[12:13], s[4:5] op_sel_hi:[1,0]
	v_mul_f32_e32 v15, 0x3fb8aa3b, v15
	v_mul_f32_e32 v14, 0x4b800000, v13
	v_cmp_gt_f32_e32 vcc, s3, v13
	v_cmp_gt_f32_e64 s[0:1], s3, v12
	v_exp_f32_e32 v15, v15
	v_cndmask_b32_e32 v13, v13, v14, vcc
	v_rsq_f32_e32 v13, v13
	v_mul_f32_e32 v14, 0x4b800000, v12
	v_cndmask_b32_e64 v12, v12, v14, s[0:1]
	v_rsq_f32_e32 v12, v12
	v_mul_f32_e32 v14, 0x45800000, v13
	v_cndmask_b32_e32 v13, v13, v14, vcc
	v_mul_f32_e32 v13, 0x3e000000, v13
	v_mul_f32_e32 v8, v8, v13
	v_mul_f32_e32 v9, v9, v13
	v_mul_f32_e32 v11, v11, v13
	v_mul_f32_e32 v10, v10, v13
	v_mul_f32_e32 v21, v21, v13
	v_mul_f32_e32 v20, v20, v13
	v_mul_f32_e32 v26, v29, v13
	v_mul_f32_e32 v13, v28, v13
	v_mul_f32_e32 v14, 0x45800000, v12
	v_cvt_pk_bf16_f32 v8, v8, v9
	v_cvt_pk_bf16_f32 v9, v11, v10
	v_cvt_pk_bf16_f32 v10, v21, v20
	v_cvt_pk_bf16_f32 v11, v26, v13
	v_add_u32_e32 v13, 0x1200, v108
	v_cndmask_b32_e64 v12, v12, v14, s[0:1]
	v_add_u32_e32 v14, v193, v13
	ds_write_b128 v14, v[8:11]
	v_mul_f32_e32 v14, v6, v12
	v_mul_f32_e32 v20, v7, v12
	v_mul_f32_e32 v21, v17, v12
	v_mul_f32_e32 v26, v16, v12
	v_mul_f32_e32 v27, v23, v12
	v_mul_f32_e32 v28, v22, v12
	v_mul_f32_e32 v29, v31, v12
	v_mul_f32_e32 v32, v30, v12
	v_cvt_pk_bf16_f32 v8, v14, v20
	v_cvt_pk_bf16_f32 v9, v21, v26
	v_cvt_pk_bf16_f32 v10, v27, v28
	v_cvt_pk_bf16_f32 v11, v29, v32
	v_add_u32_e32 v33, v192, v13
	ds_write_b128 v33, v[8:11]
	v_mul_f32_e32 v8, v109, v14
	v_mul_f32_e32 v9, v109, v20
	v_mul_f32_e32 v10, v109, v21
	v_mul_f32_e32 v11, v109, v26
	v_mul_f32_e32 v14, v109, v27
	v_mul_f32_e32 v12, v15, v12
	v_mul_f32_e32 v20, v109, v28
	v_mul_f32_e32 v21, v109, v29
	v_mul_f32_e32 v26, v109, v32
	v_cvt_pk_bf16_f32 v8, v8, v9
	v_cvt_pk_bf16_f32 v9, v10, v11
	v_cvt_pk_bf16_f32 v10, v14, v20
	v_cvt_pk_bf16_f32 v11, v21, v26
	v_add_u32_e32 v14, v155, v13
	v_add_u32_e32 v13, v133, v13
	v_mul_f32_e32 v6, v6, v12
	ds_write_b128 v14, v[8:11]
	v_cvt_pk_bf16_f32 v8, v82, v83
	v_cvt_pk_bf16_f32 v9, v84, v85
	v_cvt_pk_bf16_f32 v10, v24, v25
	v_cvt_pk_bf16_f32 v11, v18, v19
	ds_write_b128 v13, v[8:11]
	v_cvt_pk_bf16_f32 v6, v6, v157
	ds_write_b16 v107, v6 offset:64
	v_mul_f32_e32 v6, v7, v12
	v_cvt_pk_bf16_f32 v6, v6, v157
	ds_write_b16 v107, v6 offset:208
	v_mul_f32_e32 v6, v17, v12
	v_cvt_pk_bf16_f32 v6, v6, v157
	ds_write_b16 v107, v6 offset:352
	v_mul_f32_e32 v6, v16, v12
	v_cvt_pk_bf16_f32 v6, v6, v157
	ds_write_b16 v107, v6 offset:496
	v_mul_f32_e32 v6, v23, v12
	v_cvt_pk_bf16_f32 v6, v6, v157
	ds_write_b16 v107, v6 offset:640
	v_mul_f32_e32 v6, v22, v12
	v_cvt_pk_bf16_f32 v6, v6, v157
	ds_write_b16 v107, v6 offset:784
	v_mul_f32_e32 v6, v31, v12
	v_cvt_pk_bf16_f32 v6, v6, v157
	ds_write_b16 v107, v6 offset:928
	v_mul_f32_e32 v6, v30, v12
	v_cvt_pk_bf16_f32 v6, v6, v157
	ds_write_b16 v107, v6 offset:1072
	v_or_b32_e32 v6, s39, v106
	v_mul_u32_u24_e32 v78, 0x90, v6
	v_and_b32_e32 v14, -16, v130
	v_mul_u32_u24_e32 v82, 0x90, v106
	s_waitcnt lgkmcnt(0)
	s_barrier
	v_add3_u32 v6, v183, v78, v14
	v_add3_u32 v54, v189, v14, v82
	ds_read_b128 v[18:21], v6
	ds_read_b128 v[10:13], v6 offset:64
	ds_read_b128 v[22:25], v54
	ds_read_b128 v[26:29], v54 offset:64
	v_add3_u32 v34, v182, v78, v14
	s_waitcnt lgkmcnt(1)
	v_mfma_f32_16x16x32_bf16 v[6:9], v[18:21], v[22:25], 0
	ds_read_b128 v[14:17], v34
	v_add_u32_e32 v73, s39, v77
	v_lshl_add_u32 v83, v73, 2, v185
	s_waitcnt lgkmcnt(1)
	v_mfma_f32_16x16x32_bf16 v[30:33], v[10:13], v[26:29], v[6:9]
	v_lshl_add_u32 v58, v106, 2, v185
	s_movk_i32 s0, 0x48
	v_mul_lo_u32 v59, v73, s0
	ds_read_b128 v[6:9], v34 offset:64
	ds_read_b32 v46, v83
	ds_read_b32 v47, v58
	s_waitcnt lgkmcnt(3)
	v_mfma_f32_16x16x32_bf16 v[22:25], v[14:17], v[22:25], 0
	ds_read_b128 v[38:41], v54 offset:2304
	ds_read_b128 v[42:45], v54 offset:2368
	v_cmp_gt_i32_e32 vcc, v73, v106
	v_add_lshl_u32 v60, v59, v106, 1
	s_waitcnt lgkmcnt(4)
	v_mfma_f32_16x16x32_bf16 v[34:37], v[6:9], v[26:29], v[22:25]
	s_waitcnt lgkmcnt(2)
	s_nop 1
	v_sub_f32_e32 v22, v46, v47
	v_min_f32_e32 v22, 0, v22
	v_mul_f32_e32 v22, 0x3fb8aa3b, v22
	v_exp_f32_e32 v55, v22
	ds_read_b128 v[46:49], v54 offset:4608
	ds_read_b128 v[50:53], v54 offset:4672
	ds_read_b128 v[26:29], v54 offset:6912
	ds_read_b128 v[22:25], v54 offset:6976
	v_or_b32_e32 v54, v59, v106
	v_lshlrev_b32_e32 v54, 1, v54
	v_mul_f32_e32 v30, v30, v55
	v_cndmask_b32_e32 v30, 0, v30, vcc
	v_cvt_pk_bf16_f32 v30, v30, v157
	v_add_u32_e32 v56, v186, v54
	ds_write_b16 v56, v30
	v_mul_f32_e32 v30, v34, v55
	v_cmp_lt_i32_e32 vcc, v73, v106
	v_add_u32_e32 v54, v184, v54
	v_or_b32_e32 v74, 1, v73
	v_cndmask_b32_e64 v30, v30, 0, vcc
	v_cvt_pk_bf16_f32 v30, v30, v157
	ds_read_b32 v34, v83 offset:4
	ds_read_b32 v55, v58
	ds_write_b16 v54, v30
	v_or_b32_e32 v75, 2, v73
	v_or_b32_e32 v76, 3, v73
	v_or_b32_e32 v79, 16, v106
	s_waitcnt lgkmcnt(1)
; __device__ __forceinline__ bf16_t f2bf(float f) { return (bf16_t)(pk2(f, 0.f) & 0xffffu); }
; __device__ __forceinline__ float fexp(float x) { return __expf(x); }
; __device__ __forceinline__ void gdn_unit(const Ctx& X, LAS unsigned char* hl, int b, int c, int h, int tid_h, int w4, int lane, int layer) {
;     ...
;         for (int ct = 0; ct < 4; ++ct) { aA[ct] = mma16(KB, 16 * w4, K, 16 * ct, (f32x4){0.f, 0.f, 0.f, 0.f}, r, q); aP[ct] = mma16(Q, 16 * w4, K, 16 * ct, (f32x4){0.f, 0.f, 0.f, 0.f}, r, q); }
; #pragma unroll
;         for (int ct = 0; ct < 4; ++ct)
; #pragma unroll
;             for (int j = 0; j < 4; ++j) { const int ii = 16 * w4 + 4 * q + j, col = 16 * ct + r;
;                 const float L = fexp(fminf(Gs[ii] - Gs[col], 0.f));
;                 AB[ii * LT + col] = f2bf(ii > col ? aA[ct][j] * L : 0.f);
;                 P[ii * LT + col] = f2bf(ii >= col ? aP[ct][j] * L : 0.f); }
	v_sub_f32_e32 v34, v34, v55
	v_min_f32_e32 v34, 0, v34
	v_mul_f32_e32 v34, 0x3fb8aa3b, v34
	v_exp_f32_e32 v34, v34
	v_mfma_f32_16x16x32_bf16 v[54:57], v[18:21], v[38:41], 0
	v_or_b32_e32 v80, 32, v106
	v_or_b32_e32 v81, 48, v106
	v_mul_f32_e32 v30, v31, v34
	v_cndmask_b32_e64 v30, v30, 0, vcc
	v_add_u32_e32 v31, 0x90, v60
	v_cvt_pk_bf16_f32 v30, v30, v157
	v_add_u32_e32 v61, v186, v31
	ds_write_b16 v61, v30
	v_mul_f32_e32 v30, v35, v34
	v_cmp_ge_i32_e32 vcc, v74, v106
	v_add_u32_e32 v62, v184, v31
	v_add_u32_e32 v31, 0x90, v59
	v_cndmask_b32_e32 v30, 0, v30, vcc
	v_cvt_pk_bf16_f32 v30, v30, v157
	ds_read_b32 v34, v83 offset:8
	ds_read_b32 v35, v58
	ds_write_b16 v62, v30
	v_cmp_gt_i32_e32 vcc, v75, v106
	v_add_lshl_u32 v59, v31, v106, 1
	v_mfma_f32_16x16x32_bf16 v[54:57], v[10:13], v[42:45], v[54:57]
	s_waitcnt lgkmcnt(1)
	v_sub_f32_e32 v34, v34, v35
	v_min_f32_e32 v34, 0, v34
	v_mul_f32_e32 v34, 0x3fb8aa3b, v34
	v_exp_f32_e32 v34, v34
	v_readlane_b32 s0, v252, 48
	v_readlane_b32 s1, v252, 49
	v_mul_f32_e32 v30, v32, v34
	v_or_b32_e32 v32, v31, v106
	v_cndmask_b32_e32 v30, 0, v30, vcc
	v_lshlrev_b32_e32 v32, 1, v32
	v_cvt_pk_bf16_f32 v30, v30, v157
	v_add_u32_e32 v35, v186, v32
	ds_write_b16 v35, v30
	v_mul_f32_e32 v30, v36, v34
	v_cmp_ge_i32_e32 vcc, v75, v106
	v_add_u32_e32 v32, v184, v32
	s_nop 0
	v_cndmask_b32_e32 v30, 0, v30, vcc
	v_cvt_pk_bf16_f32 v30, v30, v157
	ds_read_b32 v34, v83 offset:12
	ds_read_b32 v35, v58
	ds_write_b16 v32, v30
	v_cmp_gt_i32_e32 vcc, v76, v106
	s_waitcnt lgkmcnt(1)
	v_sub_f32_e32 v34, v34, v35
	v_min_f32_e32 v34, 0, v34
	v_mul_f32_e32 v34, 0x3fb8aa3b, v34
	v_exp_f32_e32 v34, v34
	v_add_u32_e32 v35, 0x90, v59
	v_add_u32_e32 v63, v186, v35
	v_mul_f32_e32 v30, v33, v34
	v_cndmask_b32_e32 v30, 0, v30, vcc
	v_cvt_pk_bf16_f32 v30, v30, v157
	ds_write_b16 v63, v30
	v_mul_f32_e32 v30, v37, v34
	v_cmp_ge_i32_e32 vcc, v76, v106
	s_nop 1
	v_cndmask_b32_e32 v30, 0, v30, vcc
	v_cvt_pk_bf16_f32 v34, v30, v157
	ds_read_b32 v36, v83
	ds_read_b32 v37, v58 offset:64
	v_mfma_f32_16x16x32_bf16 v[30:33], v[14:17], v[38:41], 0
	v_add_u32_e32 v38, v184, v35
	ds_write_b16 v38, v34
	v_cmp_gt_i32_e32 vcc, v73, v79
	s_waitcnt lgkmcnt(1)
	v_sub_f32_e32 v36, v36, v37
	v_min_f32_e32 v36, 0, v36
	v_mul_f32_e32 v36, 0x3fb8aa3b, v36
	v_exp_f32_e32 v36, v36
	v_mfma_f32_16x16x32_bf16 v[30:33], v[6:9], v[42:45], v[30:33]
	v_add_u32_e32 v39, v186, v60
	v_add_u32_e32 v40, v184, v60
	v_mul_f32_e32 v34, v54, v36
	v_cndmask_b32_e32 v34, 0, v34, vcc
	v_cmp_lt_i32_e32 vcc, v73, v79
	s_nop 2
	v_mul_f32_e32 v30, v30, v36
	v_cvt_pk_bf16_f32 v34, v34, v157
	ds_write_b16 v39, v34 offset:32
	v_cndmask_b32_e64 v30, v30, 0, vcc
	v_cvt_pk_bf16_f32 v30, v30, v157
	ds_read_b32 v34, v83 offset:4
	ds_read_b32 v35, v58 offset:64
	ds_write_b16 v40, v30 offset:32
	v_add_u32_e32 v41, v186, v59
	v_add_u32_e32 v42, v184, v59
	s_waitcnt lgkmcnt(1)
	v_sub_f32_e32 v34, v34, v35
	v_min_f32_e32 v34, 0, v34
	v_mul_f32_e32 v34, 0x3fb8aa3b, v34
	v_exp_f32_e32 v34, v34
	s_nop 0
	v_mul_f32_e32 v30, v55, v34
	v_cndmask_b32_e64 v30, v30, 0, vcc
	v_cvt_pk_bf16_f32 v30, v30, v157
	ds_write_b16 v61, v30 offset:32
	v_mul_f32_e32 v30, v31, v34
	v_cmp_ge_i32_e32 vcc, v74, v79
	s_nop 1
	v_cndmask_b32_e32 v30, 0, v30, vcc
	v_cvt_pk_bf16_f32 v30, v30, v157
	ds_read_b32 v31, v83 offset:8
	ds_read_b32 v34, v58 offset:64
	ds_write_b16 v62, v30 offset:32
	v_cmp_gt_i32_e32 vcc, v75, v79
	s_waitcnt lgkmcnt(1)
	v_sub_f32_e32 v31, v31, v34
	v_min_f32_e32 v31, 0, v31
	v_mul_f32_e32 v31, 0x3fb8aa3b, v31
	v_exp_f32_e32 v31, v31
	v_mfma_f32_16x16x32_bf16 v[34:37], v[18:21], v[46:49], 0
	v_mul_f32_e32 v30, v56, v31
	v_cndmask_b32_e32 v30, 0, v30, vcc
	v_cvt_pk_bf16_f32 v30, v30, v157
	ds_write_b16 v41, v30 offset:32
	v_mul_f32_e32 v30, v32, v31
	v_cmp_ge_i32_e32 vcc, v75, v79
	v_mfma_f32_16x16x32_bf16 v[34:37], v[10:13], v[50:53], v[34:37]
	s_nop 0
	v_cndmask_b32_e32 v30, 0, v30, vcc
	v_cvt_pk_bf16_f32 v30, v30, v157
	ds_read_b32 v31, v83 offset:12
	ds_read_b32 v32, v58 offset:64
	ds_write_b16 v42, v30 offset:32
	v_cmp_gt_i32_e32 vcc, v76, v79
	v_mfma_f32_16x16x32_bf16 v[18:21], v[18:21], v[26:29], 0
	s_waitcnt lgkmcnt(1)
	v_sub_f32_e32 v31, v31, v32
	v_min_f32_e32 v31, 0, v31
	v_mul_f32_e32 v31, 0x3fb8aa3b, v31
	v_exp_f32_e32 v31, v31
	v_mfma_f32_16x16x32_bf16 v[10:13], v[10:13], v[22:25], v[18:21]
	v_mul_f32_e32 v30, v57, v31
	v_cndmask_b32_e32 v30, 0, v30, vcc
	v_cvt_pk_bf16_f32 v30, v30, v157
	ds_write_b16 v63, v30 offset:32
	v_mul_f32_e32 v30, v33, v31
	v_cmp_ge_i32_e32 vcc, v76, v79
	s_nop 1
	v_cndmask_b32_e32 v30, 0, v30, vcc
	v_cvt_pk_bf16_f32 v43, v30, v157
	ds_read_b32 v44, v83
	ds_read_b32 v45, v58 offset:128
	v_mfma_f32_16x16x32_bf16 v[30:33], v[14:17], v[46:49], 0
	v_cmp_gt_i32_e32 vcc, v73, v80
	ds_write_b16 v38, v43 offset:32
	s_waitcnt lgkmcnt(1)
	v_sub_f32_e32 v44, v44, v45
	v_min_f32_e32 v44, 0, v44
	v_mul_f32_e32 v44, 0x3fb8aa3b, v44
	v_exp_f32_e32 v44, v44
	v_mfma_f32_16x16x32_bf16 v[30:33], v[6:9], v[50:53], v[30:33]
	v_mul_f32_e32 v34, v34, v44
	v_cndmask_b32_e32 v34, 0, v34, vcc
	v_cmp_lt_i32_e32 vcc, v73, v80
	s_nop 4
	v_mul_f32_e32 v30, v30, v44
	v_cvt_pk_bf16_f32 v34, v34, v157
	ds_write_b16 v39, v34 offset:64
	v_cndmask_b32_e64 v30, v30, 0, vcc
	v_cvt_pk_bf16_f32 v30, v30, v157
	ds_read_b32 v34, v83 offset:4
	ds_read_b32 v43, v58 offset:128
	ds_write_b16 v40, v30 offset:64
	v_mfma_f32_16x16x32_bf16 v[14:17], v[14:17], v[26:29], 0
	s_waitcnt lgkmcnt(1)
; #define LAS __attribute__((address_space(3)))
; __device__ __forceinline__ float bf2f(bf16_t b) { return __uint_as_float((unsigned)b << 16); }
; __device__ __forceinline__ bf16_t f2bf(float f) { return (bf16_t)(pk2(f, 0.f) & 0xffffu); }
; __device__ __forceinline__ float fexp(float x) { return __expf(x); }
; #define LBAR() do { asm volatile("s_waitcnt lgkmcnt(0)" ::: "memory"); __builtin_amdgcn_s_barrier(); asm volatile("" ::: "memory"); } while (0)
; __device__ __forceinline__ void gdn_unit(const Ctx& X, LAS unsigned char* hl, int b, int c, int h, int tid_h, int w4, int lane, int layer) {
;     ...
;             for (int j = 0; j < 4; ++j) { const int ii = 16 * w4 + 4 * q + j, col = 16 * ct + r;
;                 const float L = fexp(fminf(Gs[ii] - Gs[col], 0.f));
;                 AB[ii * LT + col] = f2bf(ii > col ? aA[ct][j] * L : 0.f);
;                 P[ii * LT + col] = f2bf(ii >= col ? aP[ct][j] * L : 0.f); }
;     }
;     LBAR();
;     float rc[64];
;     if (w4 < 2) {
;         const int col = tid_h & 63; const LAS bf16_t* src = w4 == 0 ? V : KB;
; #pragma unroll
;         for (int i = 0; i < 64; ++i) { const float sc = w4 == 0 ? Bs[i] : fexp(Gs[i]); rc[i] = bf2f(src[i * LT + col]) * sc; }
	v_sub_f32_e32 v34, v34, v43
	v_min_f32_e32 v34, 0, v34
	v_mul_f32_e32 v34, 0x3fb8aa3b, v34
	v_exp_f32_e32 v34, v34
	v_mfma_f32_16x16x32_bf16 v[6:9], v[6:9], v[22:25], v[14:17]
	v_mul_f32_e32 v30, v35, v34
	v_cndmask_b32_e64 v30, v30, 0, vcc
	v_cvt_pk_bf16_f32 v30, v30, v157
	ds_write_b16 v61, v30 offset:64
	v_mul_f32_e32 v30, v31, v34
	v_cmp_ge_i32_e32 vcc, v74, v80
	s_nop 1
	v_cndmask_b32_e32 v30, 0, v30, vcc
	v_cvt_pk_bf16_f32 v30, v30, v157
	ds_read_b32 v31, v83 offset:8
	ds_read_b32 v34, v58 offset:128
	ds_write_b16 v62, v30 offset:64
	v_cmp_gt_i32_e32 vcc, v75, v80
	s_waitcnt lgkmcnt(1)
	v_sub_f32_e32 v31, v31, v34
	v_min_f32_e32 v31, 0, v31
	v_mul_f32_e32 v31, 0x3fb8aa3b, v31
	v_exp_f32_e32 v31, v31
	s_nop 0
	v_mul_f32_e32 v30, v36, v31
	v_cndmask_b32_e32 v30, 0, v30, vcc
	v_cvt_pk_bf16_f32 v30, v30, v157
	ds_write_b16 v41, v30 offset:64
	v_mul_f32_e32 v30, v32, v31
	v_cmp_ge_i32_e32 vcc, v75, v80
	s_nop 1
	v_cndmask_b32_e32 v30, 0, v30, vcc
	v_cvt_pk_bf16_f32 v30, v30, v157
	ds_read_b32 v31, v83 offset:12
	ds_read_b32 v32, v58 offset:128
	v_cmp_gt_i32_e32 vcc, v76, v80
	ds_write_b16 v42, v30 offset:64
	s_waitcnt lgkmcnt(1)
	v_sub_f32_e32 v31, v31, v32
	v_min_f32_e32 v31, 0, v31
	v_mul_f32_e32 v31, 0x3fb8aa3b, v31
	v_exp_f32_e32 v31, v31
	s_nop 0
	v_mul_f32_e32 v18, v37, v31
	v_cndmask_b32_e32 v18, 0, v18, vcc
	v_cvt_pk_bf16_f32 v18, v18, v157
	ds_write_b16 v63, v18 offset:64
	v_mul_f32_e32 v18, v33, v31
	v_cmp_ge_i32_e32 vcc, v76, v80
	s_nop 1
	v_cndmask_b32_e32 v18, 0, v18, vcc
	v_cvt_pk_bf16_f32 v18, v18, v157
	ds_read_b32 v19, v83
	ds_read_b32 v20, v58 offset:192
	v_cmp_gt_i32_e32 vcc, v73, v81
	ds_write_b16 v38, v18 offset:64
	s_waitcnt lgkmcnt(1)
	v_sub_f32_e32 v19, v19, v20
	v_min_f32_e32 v19, 0, v19
	v_mul_f32_e32 v19, 0x3fb8aa3b, v19
	v_exp_f32_e32 v19, v19
	s_nop 0
	v_mul_f32_e32 v10, v10, v19
	v_cndmask_b32_e32 v10, 0, v10, vcc
	v_mul_f32_e32 v6, v6, v19
	v_cmp_lt_i32_e32 vcc, v73, v81
	v_cvt_pk_bf16_f32 v10, v10, v157
	ds_write_b16 v39, v10 offset:96
	s_nop 0
	v_cndmask_b32_e64 v6, v6, 0, vcc
	v_cvt_pk_bf16_f32 v6, v6, v157
	ds_read_b32 v10, v83 offset:4
	ds_read_b32 v14, v58 offset:192
	ds_write_b16 v40, v6 offset:96
	s_waitcnt lgkmcnt(1)
	v_sub_f32_e32 v10, v10, v14
	v_min_f32_e32 v10, 0, v10
	v_mul_f32_e32 v10, 0x3fb8aa3b, v10
	v_exp_f32_e32 v10, v10
	s_nop 0
	v_mul_f32_e32 v6, v11, v10
	v_cndmask_b32_e64 v6, v6, 0, vcc
	v_cvt_pk_bf16_f32 v6, v6, v157
	ds_write_b16 v61, v6 offset:96
	v_mul_f32_e32 v6, v7, v10
	v_cmp_ge_i32_e32 vcc, v74, v81
	s_nop 1
	v_cndmask_b32_e32 v6, 0, v6, vcc
	v_cvt_pk_bf16_f32 v6, v6, v157
	ds_read_b32 v7, v83 offset:8
	ds_read_b32 v10, v58 offset:192
	ds_write_b16 v62, v6 offset:96
	v_cmp_gt_i32_e32 vcc, v75, v81
	s_waitcnt lgkmcnt(1)
	v_sub_f32_e32 v7, v7, v10
	v_min_f32_e32 v7, 0, v7
	v_mul_f32_e32 v7, 0x3fb8aa3b, v7
	v_exp_f32_e32 v7, v7
	s_nop 0
	v_mul_f32_e32 v6, v12, v7
	v_cndmask_b32_e32 v6, 0, v6, vcc
	v_cvt_pk_bf16_f32 v6, v6, v157
	ds_write_b16 v41, v6 offset:96
	v_mul_f32_e32 v6, v8, v7
	v_cmp_ge_i32_e32 vcc, v75, v81
	s_nop 1
	v_cndmask_b32_e32 v6, 0, v6, vcc
	v_cvt_pk_bf16_f32 v6, v6, v157
	ds_read_b32 v7, v83 offset:12
	ds_read_b32 v8, v58 offset:192
	ds_write_b16 v42, v6 offset:96
	v_cmp_gt_i32_e32 vcc, v76, v81
	s_waitcnt lgkmcnt(1)
	v_sub_f32_e32 v7, v7, v8
	v_min_f32_e32 v7, 0, v7
	v_mul_f32_e32 v7, 0x3fb8aa3b, v7
	v_exp_f32_e32 v7, v7
	s_nop 0
	v_mul_f32_e32 v6, v13, v7
	v_cndmask_b32_e32 v6, 0, v6, vcc
	v_cvt_pk_bf16_f32 v6, v6, v157
	ds_write_b16 v63, v6 offset:96
	v_mul_f32_e32 v6, v9, v7
	v_cmp_ge_i32_e32 vcc, v76, v81
	s_nop 1
	v_cndmask_b32_e32 v6, 0, v6, vcc
	v_cvt_pk_bf16_f32 v6, v6, v157
	ds_write_b16 v38, v6 offset:96
	s_waitcnt lgkmcnt(0)
	s_barrier
	v_cndmask_b32_e64 v6, 0, 1, s[0:1]
	v_cmp_ne_u32_e64 s[4:5], 1, v6
	s_andn2_b64 vcc, exec, s[0:1]
	s_cbranch_vccnz .LBB0_608
	v_readlane_b32 s6, v252, 46
	v_readlane_b32 s7, v252, 47
	v_and_b32_e32 v7, 63, v132
	v_cndmask_b32_e64 v8, v183, v181, s[40:41]
	v_lshl_add_u32 v8, v7, 1, v8
	s_and_b64 vcc, exec, s[6:7]
	s_cbranch_vccz .Lrc_bs
	ds_read_b32 v6, v185
	ds_read_b32 v9, v185 offset:4
	ds_read_b32 v11, v185 offset:8
	ds_read_b32 v13, v185 offset:12
	ds_read_b32 v15, v185 offset:16
	ds_read_b32 v17, v185 offset:20
	ds_read_b32 v19, v185 offset:24
	ds_read_b32 v26, v185 offset:28
	ds_read_b32 v29, v185 offset:32
	ds_read_b32 v32, v185 offset:36
	ds_read_b32 v30, v185 offset:40
	ds_read_b32 v35, v185 offset:44
	ds_read_b32 v28, v185 offset:48
	ds_read_b32 v38, v185 offset:52
	ds_read_b32 v40, v185 offset:56
	ds_read_b32 v42, v185 offset:60
	ds_read_b32 v25, v185 offset:64
	ds_read_b32 v45, v185 offset:68
	ds_read_b32 v47, v185 offset:72
	ds_read_b32 v49, v185 offset:76
	ds_read_b32 v51, v185 offset:80
	ds_read_b32 v53, v185 offset:84
	ds_read_b32 v55, v185 offset:88
	ds_read_b32 v57, v185 offset:92
	ds_read_b32 v59, v185 offset:96
	ds_read_b32 v61, v185 offset:100
	ds_read_b32 v63, v185 offset:104
	ds_read_b32 v65, v185 offset:108
	ds_read_b32 v67, v185 offset:112
	ds_read_b32 v69, v185 offset:116
	ds_read_b32 v71, v185 offset:120
	ds_read_b32 v24, v185 offset:124
	ds_read_b32 v23, v185 offset:128
	ds_read_b32 v113, v185 offset:132
	ds_read_b32 v112, v185 offset:136
	ds_read_b32 v111, v185 offset:140
	ds_read_b32 v110, v185 offset:144
	ds_read_b32 v109, v185 offset:148
	ds_read_b32 v108, v185 offset:152
	ds_read_b32 v107, v185 offset:156
	ds_read_b32 v105, v185 offset:160
	ds_read_b32 v104, v185 offset:164
	ds_read_b32 v103, v185 offset:168
	ds_read_b32 v102, v185 offset:172
	ds_read_b32 v101, v185 offset:176
	ds_read_b32 v100, v185 offset:180
	ds_read_b32 v99, v185 offset:184
	ds_read_b32 v22, v185 offset:188
; #define LAS __attribute__((address_space(3)))
; __device__ __forceinline__ float bf2f(bf16_t b) { return __uint_as_float((unsigned)b << 16); }
; __device__ __forceinline__ float fexp(float x) { return __expf(x); }
; __device__ __forceinline__ void gdn_unit(const Ctx& X, LAS unsigned char* hl, int b, int c, int h, int tid_h, int w4, int lane, int layer) {
;     ...
;     if (w4 < 2) {
;         const int col = tid_h & 63; const LAS bf16_t* src = w4 == 0 ? V : KB;
; #pragma unroll
;         for (int i = 0; i < 64; ++i) { const float sc = w4 == 0 ? Bs[i] : fexp(Gs[i]); rc[i] = bf2f(src[i * LT + col]) * sc; }
;     }
	ds_read_b32 v21, v185 offset:192
	ds_read_b32 v98, v185 offset:196
	ds_read_b32 v97, v185 offset:200
	ds_read_b32 v96, v185 offset:204
	ds_read_b32 v95, v185 offset:208
	ds_read_b32 v94, v185 offset:212
	ds_read_b32 v93, v185 offset:216
	ds_read_b32 v92, v185 offset:220
	ds_read_b32 v91, v185 offset:224
	ds_read_b32 v90, v185 offset:228
	ds_read_b32 v89, v185 offset:232
	ds_read_b32 v88, v185 offset:236
	ds_read_b32 v87, v185 offset:240
	ds_read_b32 v86, v185 offset:244
	ds_read_b32 v85, v185 offset:248
	ds_read_b32 v144, v185 offset:252
	ds_read_u16 v7, v8
	ds_read_u16 v10, v8 offset:144
	ds_read_u16 v12, v8 offset:288
	ds_read_u16 v14, v8 offset:432
	ds_read_u16 v16, v8 offset:576
	ds_read_u16 v18, v8 offset:720
	ds_read_u16 v20, v8 offset:864
	ds_read_u16 v27, v8 offset:1008
	ds_read_u16 v31, v8 offset:1152
	ds_read_u16 v33, v8 offset:1296
	ds_read_u16 v34, v8 offset:1440
	ds_read_u16 v36, v8 offset:1584
	ds_read_u16 v37, v8 offset:1728
	ds_read_u16 v39, v8 offset:1872
	ds_read_u16 v41, v8 offset:2016
	ds_read_u16 v43, v8 offset:2160
	ds_read_u16 v44, v8 offset:2304
	ds_read_u16 v46, v8 offset:2448
	ds_read_u16 v48, v8 offset:2592
	ds_read_u16 v50, v8 offset:2736
	ds_read_u16 v52, v8 offset:2880
	ds_read_u16 v54, v8 offset:3024
	ds_read_u16 v56, v8 offset:3168
	ds_read_u16 v58, v8 offset:3312
	ds_read_u16 v60, v8 offset:3456
	ds_read_u16 v62, v8 offset:3600
	ds_read_u16 v64, v8 offset:3744
	ds_read_u16 v66, v8 offset:3888
	ds_read_u16 v68, v8 offset:4032
	ds_read_u16 v70, v8 offset:4176
	ds_read_u16 v84, v8 offset:4320
	ds_read_u16 v114, v8 offset:4464
	ds_read_u16 v115, v8 offset:4608
	ds_read_u16 v116, v8 offset:4752
	ds_read_u16 v117, v8 offset:4896
	ds_read_u16 v118, v8 offset:5040
	ds_read_u16 v119, v8 offset:5184
	ds_read_u16 v120, v8 offset:5328
	ds_read_u16 v121, v8 offset:5472
	ds_read_u16 v122, v8 offset:5616
	ds_read_u16 v123, v8 offset:5760
	ds_read_u16 v124, v8 offset:5904
	ds_read_u16 v125, v8 offset:6048
	ds_read_u16 v126, v8 offset:6192
	ds_read_u16 v127, v8 offset:6336
	ds_read_u16 v128, v8 offset:6480
	ds_read_u16 v129, v8 offset:6624
	ds_read_u16 v133, v8 offset:6768
	ds_read_u16 v134, v8 offset:6912
	ds_read_u16 v135, v8 offset:7056
	ds_read_u16 v136, v8 offset:7200
	ds_read_u16 v137, v8 offset:7344
	ds_read_u16 v138, v8 offset:7488
	ds_read_u16 v139, v8 offset:7632
	ds_read_u16 v140, v8 offset:7776
	ds_read_u16 v141, v8 offset:7920
	ds_read_u16 v142, v8 offset:8064
	ds_read_u16 v143, v8 offset:8208
	ds_read_u16 v145, v8 offset:8352
	ds_read_u16 v146, v8 offset:8496
	ds_read_u16 v147, v8 offset:8640
	ds_read_u16 v148, v8 offset:8784
	ds_read_u16 v149, v8 offset:8928
	s_waitcnt lgkmcnt(15)
	v_mul_f32_e32 v6, 0x3fb8aa3b, v6
	v_exp_f32_e32 v6, v6
	v_mul_f32_e32 v9, 0x3fb8aa3b, v9
	v_exp_f32_e32 v9, v9
	v_mul_f32_e32 v11, 0x3fb8aa3b, v11
	v_exp_f32_e32 v11, v11
	v_mul_f32_e32 v13, 0x3fb8aa3b, v13
	v_exp_f32_e32 v13, v13
	v_mul_f32_e32 v15, 0x3fb8aa3b, v15
	v_exp_f32_e32 v15, v15
	v_mul_f32_e32 v17, 0x3fb8aa3b, v17
	v_exp_f32_e32 v17, v17
	v_mul_f32_e32 v19, 0x3fb8aa3b, v19
	v_exp_f32_e32 v19, v19
	v_mul_f32_e32 v26, 0x3fb8aa3b, v26
	v_exp_f32_e32 v26, v26
	v_mul_f32_e32 v29, 0x3fb8aa3b, v29
	v_exp_f32_e32 v29, v29
	v_mul_f32_e32 v32, 0x3fb8aa3b, v32
	v_exp_f32_e32 v32, v32
	v_mul_f32_e32 v30, 0x3fb8aa3b, v30
	v_exp_f32_e32 v30, v30
	v_mul_f32_e32 v35, 0x3fb8aa3b, v35
	v_exp_f32_e32 v35, v35
	v_mul_f32_e32 v28, 0x3fb8aa3b, v28
	v_exp_f32_e32 v28, v28
	v_mul_f32_e32 v38, 0x3fb8aa3b, v38
	v_exp_f32_e32 v38, v38
	v_mul_f32_e32 v40, 0x3fb8aa3b, v40
	v_exp_f32_e32 v40, v40
	v_mul_f32_e32 v42, 0x3fb8aa3b, v42
	v_exp_f32_e32 v42, v42
	v_mul_f32_e32 v25, 0x3fb8aa3b, v25
	v_exp_f32_e32 v25, v25
	v_mul_f32_e32 v45, 0x3fb8aa3b, v45
	v_exp_f32_e32 v45, v45
	v_mul_f32_e32 v47, 0x3fb8aa3b, v47
	v_exp_f32_e32 v47, v47
	v_mul_f32_e32 v49, 0x3fb8aa3b, v49
	v_exp_f32_e32 v49, v49
	v_mul_f32_e32 v51, 0x3fb8aa3b, v51
	v_exp_f32_e32 v51, v51
	v_mul_f32_e32 v53, 0x3fb8aa3b, v53
	v_exp_f32_e32 v53, v53
	v_mul_f32_e32 v55, 0x3fb8aa3b, v55
	v_exp_f32_e32 v55, v55
	v_mul_f32_e32 v57, 0x3fb8aa3b, v57
	v_exp_f32_e32 v57, v57
	v_mul_f32_e32 v59, 0x3fb8aa3b, v59
	v_exp_f32_e32 v59, v59
	v_mul_f32_e32 v61, 0x3fb8aa3b, v61
	v_exp_f32_e32 v61, v61
	v_mul_f32_e32 v63, 0x3fb8aa3b, v63
	v_exp_f32_e32 v63, v63
	v_mul_f32_e32 v65, 0x3fb8aa3b, v65
	v_exp_f32_e32 v65, v65
	v_mul_f32_e32 v67, 0x3fb8aa3b, v67
	v_exp_f32_e32 v67, v67
	v_mul_f32_e32 v69, 0x3fb8aa3b, v69
	v_exp_f32_e32 v69, v69
	v_mul_f32_e32 v71, 0x3fb8aa3b, v71
	v_exp_f32_e32 v71, v71
	v_mul_f32_e32 v24, 0x3fb8aa3b, v24
	v_exp_f32_e32 v24, v24
	v_mul_f32_e32 v23, 0x3fb8aa3b, v23
	v_exp_f32_e32 v23, v23
	v_mul_f32_e32 v113, 0x3fb8aa3b, v113
	v_exp_f32_e32 v113, v113
	v_mul_f32_e32 v112, 0x3fb8aa3b, v112
	v_exp_f32_e32 v112, v112
	v_mul_f32_e32 v111, 0x3fb8aa3b, v111
	v_exp_f32_e32 v111, v111
	v_mul_f32_e32 v110, 0x3fb8aa3b, v110
	v_exp_f32_e32 v110, v110
	v_mul_f32_e32 v109, 0x3fb8aa3b, v109
	v_exp_f32_e32 v109, v109
	v_mul_f32_e32 v108, 0x3fb8aa3b, v108
	v_exp_f32_e32 v108, v108
	v_mul_f32_e32 v107, 0x3fb8aa3b, v107
	v_exp_f32_e32 v107, v107
	v_mul_f32_e32 v105, 0x3fb8aa3b, v105
	v_exp_f32_e32 v105, v105
	v_mul_f32_e32 v104, 0x3fb8aa3b, v104
	v_exp_f32_e32 v104, v104
	v_mul_f32_e32 v103, 0x3fb8aa3b, v103
	v_exp_f32_e32 v103, v103
	v_mul_f32_e32 v102, 0x3fb8aa3b, v102
	v_exp_f32_e32 v102, v102
	v_mul_f32_e32 v101, 0x3fb8aa3b, v101
	v_exp_f32_e32 v101, v101
	v_mul_f32_e32 v100, 0x3fb8aa3b, v100
	v_exp_f32_e32 v100, v100
	v_mul_f32_e32 v99, 0x3fb8aa3b, v99
	v_exp_f32_e32 v99, v99
	v_mul_f32_e32 v22, 0x3fb8aa3b, v22
	v_exp_f32_e32 v22, v22
	v_mul_f32_e32 v21, 0x3fb8aa3b, v21
	v_exp_f32_e32 v21, v21
	v_mul_f32_e32 v98, 0x3fb8aa3b, v98
	v_exp_f32_e32 v98, v98
	v_mul_f32_e32 v97, 0x3fb8aa3b, v97
	v_exp_f32_e32 v97, v97
	v_mul_f32_e32 v96, 0x3fb8aa3b, v96
	v_exp_f32_e32 v96, v96
	v_mul_f32_e32 v95, 0x3fb8aa3b, v95
	v_exp_f32_e32 v95, v95
	v_mul_f32_e32 v94, 0x3fb8aa3b, v94
	v_exp_f32_e32 v94, v94
	v_mul_f32_e32 v93, 0x3fb8aa3b, v93
	v_exp_f32_e32 v93, v93
	v_mul_f32_e32 v92, 0x3fb8aa3b, v92
	v_exp_f32_e32 v92, v92
	v_mul_f32_e32 v91, 0x3fb8aa3b, v91
	v_exp_f32_e32 v91, v91
	v_mul_f32_e32 v90, 0x3fb8aa3b, v90
	v_exp_f32_e32 v90, v90
	v_mul_f32_e32 v89, 0x3fb8aa3b, v89
	v_exp_f32_e32 v89, v89
	v_mul_f32_e32 v88, 0x3fb8aa3b, v88
	v_exp_f32_e32 v88, v88
	v_mul_f32_e32 v87, 0x3fb8aa3b, v87
	v_exp_f32_e32 v87, v87
	v_mul_f32_e32 v86, 0x3fb8aa3b, v86
	v_exp_f32_e32 v86, v86
	v_mul_f32_e32 v85, 0x3fb8aa3b, v85
	v_exp_f32_e32 v85, v85
	v_mul_f32_e32 v144, 0x3fb8aa3b, v144
	v_exp_f32_e32 v144, v144
	s_branch .Lrc_join
; #define LAS __attribute__((address_space(3)))
; __device__ __forceinline__ float bf2f(bf16_t b) { return __uint_as_float((unsigned)b << 16); }
; __device__ __forceinline__ float fexp(float x) { return __expf(x); }
; __device__ __forceinline__ void gdn_unit(const Ctx& X, LAS unsigned char* hl, int b, int c, int h, int tid_h, int w4, int lane, int layer) {
;     ...
;     if (w4 < 2) {
;         const int col = tid_h & 63; const LAS bf16_t* src = w4 == 0 ? V : KB;
; #pragma unroll
;         for (int i = 0; i < 64; ++i) { const float sc = w4 == 0 ? Bs[i] : fexp(Gs[i]); rc[i] = bf2f(src[i * LT + col]) * sc; }
;     }
.Lrc_bs:
	ds_read_b32 v6, v188
	ds_read_b32 v9, v188 offset:4
	ds_read_b32 v11, v188 offset:8
	ds_read_b32 v13, v188 offset:12
	ds_read_b32 v15, v188 offset:16
	ds_read_b32 v17, v188 offset:20
	ds_read_b32 v19, v188 offset:24
	ds_read_b32 v26, v188 offset:28
	ds_read_b32 v29, v188 offset:32
	ds_read_b32 v32, v188 offset:36
	ds_read_b32 v30, v188 offset:40
	ds_read_b32 v35, v188 offset:44
	ds_read_b32 v28, v188 offset:48
	ds_read_b32 v38, v188 offset:52
	ds_read_b32 v40, v188 offset:56
	ds_read_b32 v42, v188 offset:60
	ds_read_b32 v25, v188 offset:64
	ds_read_b32 v45, v188 offset:68
	ds_read_b32 v47, v188 offset:72
	ds_read_b32 v49, v188 offset:76
	ds_read_b32 v51, v188 offset:80
	ds_read_b32 v53, v188 offset:84
	ds_read_b32 v55, v188 offset:88
	ds_read_b32 v57, v188 offset:92
	ds_read_b32 v59, v188 offset:96
	ds_read_b32 v61, v188 offset:100
	ds_read_b32 v63, v188 offset:104
	ds_read_b32 v65, v188 offset:108
	ds_read_b32 v67, v188 offset:112
	ds_read_b32 v69, v188 offset:116
	ds_read_b32 v71, v188 offset:120
	ds_read_b32 v24, v188 offset:124
	ds_read_b32 v23, v188 offset:128
	ds_read_b32 v113, v188 offset:132
	ds_read_b32 v112, v188 offset:136
	ds_read_b32 v111, v188 offset:140
	ds_read_b32 v110, v188 offset:144
	ds_read_b32 v109, v188 offset:148
	ds_read_b32 v108, v188 offset:152
	ds_read_b32 v107, v188 offset:156
	ds_read_b32 v105, v188 offset:160
	ds_read_b32 v104, v188 offset:164
	ds_read_b32 v103, v188 offset:168
	ds_read_b32 v102, v188 offset:172
	ds_read_b32 v101, v188 offset:176
	ds_read_b32 v100, v188 offset:180
	ds_read_b32 v99, v188 offset:184
	ds_read_b32 v22, v188 offset:188
	ds_read_b32 v21, v188 offset:192
	ds_read_b32 v98, v188 offset:196
	ds_read_b32 v97, v188 offset:200
	ds_read_b32 v96, v188 offset:204
	ds_read_b32 v95, v188 offset:208
	ds_read_b32 v94, v188 offset:212
	ds_read_b32 v93, v188 offset:216
	ds_read_b32 v92, v188 offset:220
	ds_read_b32 v91, v188 offset:224
	ds_read_b32 v90, v188 offset:228
	ds_read_b32 v89, v188 offset:232
	ds_read_b32 v88, v188 offset:236
	ds_read_b32 v87, v188 offset:240
	ds_read_b32 v86, v188 offset:244
	ds_read_b32 v85, v188 offset:248
	ds_read_b32 v144, v188 offset:252
	ds_read_u16 v7, v8
	ds_read_u16 v10, v8 offset:144
	ds_read_u16 v12, v8 offset:288
	ds_read_u16 v14, v8 offset:432
	ds_read_u16 v16, v8 offset:576
	ds_read_u16 v18, v8 offset:720
	ds_read_u16 v20, v8 offset:864
	ds_read_u16 v27, v8 offset:1008
	ds_read_u16 v31, v8 offset:1152
	ds_read_u16 v33, v8 offset:1296
	ds_read_u16 v34, v8 offset:1440
	ds_read_u16 v36, v8 offset:1584
	ds_read_u16 v37, v8 offset:1728
	ds_read_u16 v39, v8 offset:1872
	ds_read_u16 v41, v8 offset:2016
	ds_read_u16 v43, v8 offset:2160
	ds_read_u16 v44, v8 offset:2304
	ds_read_u16 v46, v8 offset:2448
	ds_read_u16 v48, v8 offset:2592
	ds_read_u16 v50, v8 offset:2736
	ds_read_u16 v52, v8 offset:2880
	ds_read_u16 v54, v8 offset:3024
	ds_read_u16 v56, v8 offset:3168
	ds_read_u16 v58, v8 offset:3312
	ds_read_u16 v60, v8 offset:3456
	ds_read_u16 v62, v8 offset:3600
	ds_read_u16 v64, v8 offset:3744
	ds_read_u16 v66, v8 offset:3888
	ds_read_u16 v68, v8 offset:4032
	ds_read_u16 v70, v8 offset:4176
	ds_read_u16 v84, v8 offset:4320
	ds_read_u16 v114, v8 offset:4464
	ds_read_u16 v115, v8 offset:4608
	ds_read_u16 v116, v8 offset:4752
	ds_read_u16 v117, v8 offset:4896
	ds_read_u16 v118, v8 offset:5040
	ds_read_u16 v119, v8 offset:5184
	ds_read_u16 v120, v8 offset:5328
	ds_read_u16 v121, v8 offset:5472
	ds_read_u16 v122, v8 offset:5616
	ds_read_u16 v123, v8 offset:5760
	ds_read_u16 v124, v8 offset:5904
	ds_read_u16 v125, v8 offset:6048
	ds_read_u16 v126, v8 offset:6192
	ds_read_u16 v127, v8 offset:6336
	ds_read_u16 v128, v8 offset:6480
	ds_read_u16 v129, v8 offset:6624
	ds_read_u16 v133, v8 offset:6768
	ds_read_u16 v134, v8 offset:6912
	ds_read_u16 v135, v8 offset:7056
	ds_read_u16 v136, v8 offset:7200
	ds_read_u16 v137, v8 offset:7344
	ds_read_u16 v138, v8 offset:7488
	ds_read_u16 v139, v8 offset:7632
	ds_read_u16 v140, v8 offset:7776
	ds_read_u16 v141, v8 offset:7920
	ds_read_u16 v142, v8 offset:8064
	ds_read_u16 v143, v8 offset:8208
	ds_read_u16 v145, v8 offset:8352
	ds_read_u16 v146, v8 offset:8496
	ds_read_u16 v147, v8 offset:8640
	ds_read_u16 v148, v8 offset:8784
	ds_read_u16 v149, v8 offset:8928
; #define LAS __attribute__((address_space(3)))
; __device__ __forceinline__ float bf2f(bf16_t b) { return __uint_as_float((unsigned)b << 16); }
; __device__ __forceinline__ float fexp(float x) { return __expf(x); }
; __device__ __forceinline__ void gdn_unit(const Ctx& X, LAS unsigned char* hl, int b, int c, int h, int tid_h, int w4, int lane, int layer) {
;     ...
;     if (w4 < 2) {
;         const int col = tid_h & 63; const LAS bf16_t* src = w4 == 0 ? V : KB;
; #pragma unroll
;         for (int i = 0; i < 64; ++i) { const float sc = w4 == 0 ? Bs[i] : fexp(Gs[i]); rc[i] = bf2f(src[i * LT + col]) * sc; }
;     }
.Lrc_join:
	s_waitcnt lgkmcnt(0)
	s_branch .LBB0_607
.LBB0_356:
	s_cbranch_execz .LBB0_621
	s_branch .LBB0_233
.LBB0_607:
	s_waitcnt lgkmcnt(14)
	v_lshlrev_b32_e32 v39, 16, v39
	v_lshlrev_b32_e32 v12, 16, v12
	v_mul_f32_e32 v39, v38, v39
	v_mul_f32_e32 v38, v11, v12
	ds_read_u16 v11, v8 offset:9072
	v_lshlrev_b32_e32 v27, 16, v27
	v_lshlrev_b32_e32 v7, 16, v7
	s_waitcnt lgkmcnt(1)
	v_lshlrev_b32_e32 v149, 16, v149
	v_lshlrev_b32_e32 v148, 16, v148
	v_lshlrev_b32_e32 v147, 16, v147
	v_lshlrev_b32_e32 v146, 16, v146
	v_lshlrev_b32_e32 v145, 16, v145
	v_lshlrev_b32_e32 v143, 16, v143
	v_lshlrev_b32_e32 v142, 16, v142
	v_lshlrev_b32_e32 v141, 16, v141
	v_lshlrev_b32_e32 v140, 16, v140
	v_lshlrev_b32_e32 v139, 16, v139
	v_lshlrev_b32_e32 v138, 16, v138
	v_lshlrev_b32_e32 v137, 16, v137
	v_lshlrev_b32_e32 v136, 16, v136
	v_lshlrev_b32_e32 v135, 16, v135
	v_lshlrev_b32_e32 v134, 16, v134
	v_lshlrev_b32_e32 v133, 16, v133
	v_lshlrev_b32_e32 v129, 16, v129
	v_lshlrev_b32_e32 v128, 16, v128
	v_lshlrev_b32_e32 v127, 16, v127
	v_lshlrev_b32_e32 v126, 16, v126
	v_lshlrev_b32_e32 v125, 16, v125
	v_lshlrev_b32_e32 v124, 16, v124
	v_lshlrev_b32_e32 v123, 16, v123
	v_lshlrev_b32_e32 v122, 16, v122
	v_lshlrev_b32_e32 v121, 16, v121
	v_lshlrev_b32_e32 v120, 16, v120
	v_lshlrev_b32_e32 v119, 16, v119
	v_lshlrev_b32_e32 v118, 16, v118
	v_lshlrev_b32_e32 v117, 16, v117
	v_lshlrev_b32_e32 v116, 16, v116
	v_lshlrev_b32_e32 v115, 16, v115
	v_lshlrev_b32_e32 v114, 16, v114
	v_lshlrev_b32_e32 v84, 16, v84
	v_lshlrev_b32_e32 v70, 16, v70
	v_lshlrev_b32_e32 v68, 16, v68
	v_lshlrev_b32_e32 v66, 16, v66
	v_lshlrev_b32_e32 v64, 16, v64
	v_lshlrev_b32_e32 v62, 16, v62
	v_lshlrev_b32_e32 v60, 16, v60
	v_lshlrev_b32_e32 v58, 16, v58
	v_lshlrev_b32_e32 v56, 16, v56
	v_lshlrev_b32_e32 v54, 16, v54
	v_lshlrev_b32_e32 v52, 16, v52
	v_lshlrev_b32_e32 v50, 16, v50
	v_lshlrev_b32_e32 v48, 16, v48
	v_lshlrev_b32_e32 v46, 16, v46
	v_lshlrev_b32_e32 v44, 16, v44
	v_lshlrev_b32_e32 v43, 16, v43
	v_lshlrev_b32_e32 v41, 16, v41
	v_lshlrev_b32_e32 v37, 16, v37
	v_lshlrev_b32_e32 v36, 16, v36
	v_lshlrev_b32_e32 v34, 16, v34
	v_lshlrev_b32_e32 v33, 16, v33
	v_lshlrev_b32_e32 v31, 16, v31
	v_mul_f32_e32 v27, v26, v27
	v_lshlrev_b32_e32 v20, 16, v20
	v_lshlrev_b32_e32 v18, 16, v18
	v_lshlrev_b32_e32 v16, 16, v16
	v_lshlrev_b32_e32 v14, 16, v14
	v_lshlrev_b32_e32 v8, 16, v10
	v_mul_f32_e32 v26, v6, v7
	s_waitcnt lgkmcnt(0)
	v_lshlrev_b32_e32 v6, 16, v11
	v_mul_f32_e32 v85, v85, v149
	v_mul_f32_e32 v86, v86, v148
	v_mul_f32_e32 v87, v87, v147
	v_mul_f32_e32 v88, v88, v146
	v_mul_f32_e32 v89, v89, v145
	v_mul_f32_e32 v90, v90, v143
	v_mul_f32_e32 v91, v91, v142
	v_mul_f32_e32 v92, v92, v141
	v_mul_f32_e32 v93, v93, v140
	v_mul_f32_e32 v94, v94, v139
	v_mul_f32_e32 v95, v95, v138
	v_mul_f32_e32 v96, v96, v137
	v_mul_f32_e32 v97, v97, v136
	v_mul_f32_e32 v98, v98, v135
	v_mul_f32_e32 v21, v21, v134
	v_mul_f32_e32 v22, v22, v133
	v_mul_f32_e32 v99, v99, v129
	v_mul_f32_e32 v100, v100, v128
	v_mul_f32_e32 v101, v101, v127
	v_mul_f32_e32 v102, v102, v126
	v_mul_f32_e32 v103, v103, v125
	v_mul_f32_e32 v104, v104, v124
	v_mul_f32_e32 v105, v105, v123
	v_mul_f32_e32 v107, v107, v122
	v_mul_f32_e32 v108, v108, v121
	v_mul_f32_e32 v109, v109, v120
	v_mul_f32_e32 v110, v110, v119
	v_mul_f32_e32 v111, v111, v118
	v_mul_f32_e32 v112, v112, v117
	v_mul_f32_e32 v113, v113, v116
	v_mul_f32_e32 v23, v23, v115
	v_mul_f32_e32 v24, v24, v114
	v_mul_f32_e32 v118, v71, v84
	v_mul_f32_e32 v119, v69, v70
	v_mul_f32_e32 v120, v67, v68
	v_mul_f32_e32 v121, v65, v66
	v_mul_f32_e32 v122, v63, v64
	v_mul_f32_e32 v123, v61, v62
	v_mul_f32_e32 v124, v59, v60
	v_mul_f32_e32 v125, v57, v58
	v_mul_f32_e32 v126, v55, v56
	v_mul_f32_e32 v127, v53, v54
	v_mul_f32_e32 v128, v51, v52
	v_mul_f32_e32 v129, v49, v50
	v_mul_f32_e32 v133, v47, v48
	v_mul_f32_e32 v134, v45, v46
	v_mul_f32_e32 v25, v25, v44
	v_mul_f32_e32 v46, v42, v43
	v_mul_f32_e32 v156, v40, v41
	v_mul_f32_e32 v28, v28, v37
	v_mul_f32_e32 v35, v35, v36
	v_mul_f32_e32 v30, v30, v34
	v_mul_f32_e32 v33, v32, v33
	v_mul_f32_e32 v32, v29, v31
	v_mul_f32_e32 v34, v19, v20
	v_mul_f32_e32 v29, v17, v18
	v_mul_f32_e32 v36, v15, v16
	v_mul_f32_e32 v13, v13, v14
	v_mul_f32_e32 v8, v9, v8
	v_mul_f32_e32 v20, v144, v6

; __device__ __forceinline__ float fexp(float x) { return __expf(x); }
; __device__ __forceinline__ void ret_unit(const Ctx& X, LAS unsigned char* hl, int b, int c, int h, int tid_h, int w4, int lane) {
;     ...
;     const float lg = log1pf(-exp2f(-5.0f - (float)h));
;     {
;         const int i = tid_h >> 2, sg = tid_h & 3, d0 = sg * 8;
;         const bf16_t* pr = proj + ((size_t)b * T + c * 64 + i) * LDP;
;         const u32x4 q1 = *(const u32x4*)(pr + C_RQ + h * 64 + d0), q2 = *(const u32x4*)(pr + C_RQ + h * 64 + d0 + 32);
;         const u32x4 k1 = *(const u32x4*)(pr + C_RK + h * 64 + d0), k2 = *(const u32x4*)(pr + C_RK + h * 64 + d0 + 32);
;         const u32x4 v1 = *(const u32x4*)(pr + C_RV + h * 64 + sg * 16), v2 = *(const u32x4*)(pr + C_RV + h * 64 + sg * 16 + 8);
;         float qa[8], qb[8], ka[8], kb[8], va[8], vb[8];
;         unpack8(q1, qa); unpack8(q2, qb); unpack8(k1, ka); unpack8(k2, kb); unpack8(v1, va); unpack8(v2, vb);
;         const float pos = (float)(c * 64 + i);
;         const float qd = fexp(lg * (float)(i + 1)), kd = fexp(lg * (float)(63 - i));
.LBB0_621:
	v_cvt_f32_u32_e32 v6, s23
	s_mov_b32 s19, 0xc2fc0000
	s_lshl_b32 s1, s22, 9
	s_lshl_b32 s0, s23, 7
	v_sub_f32_e32 v6, 0xc0a00000, v6
	v_cmp_gt_f32_e32 vcc, s19, v6
	s_add_i32 s4, s0, s1
	s_and_b64 s[6:7], vcc, exec
	v_cndmask_b32_e32 v7, 0, v1, vcc
	v_add_f32_e32 v6, v6, v7
	v_exp_f32_e32 v6, v6
	s_cselect_b32 s1, 0xffffffc0, 0
	v_ashrrev_i32_e32 v30, 2, v132
	s_lshl_b32 s5, s21, 6
	v_ldexp_f32 v22, v6, s1
	v_sub_f32_e32 v8, 1.0, v22
	v_add_f32_e32 v6, -1.0, v8
	v_sub_f32_e32 v7, v6, v8
	v_add_f32_e32 v7, 1.0, v7
	v_sub_f32_e64 v6, -v22, v6
	v_add_f32_e32 v9, v6, v7
	v_frexp_mant_f32_e32 v6, v8
	s_mov_b32 s1, 0x3f2aaaab
	v_cmp_gt_f32_e32 vcc, s1, v6
	v_cvt_f64_f32_e32 v[6:7], v8
	v_frexp_exp_i32_f64_e32 v6, v[6:7]
	v_subbrev_co_u32_e32 v14, vcc, 0, v6, vcc
	v_sub_u32_e32 v6, 0, v14
	v_ldexp_f32 v7, v8, v6
	v_add_f32_e32 v8, -1.0, v7
	v_add_f32_e32 v10, 1.0, v7
	v_ldexp_f32 v6, v9, v6
	v_add_f32_e32 v9, 1.0, v8
	v_add_f32_e32 v11, -1.0, v10
	v_sub_f32_e32 v9, v7, v9
	v_sub_f32_e32 v7, v7, v11
	v_add_f32_e32 v9, v6, v9
	v_add_f32_e32 v6, v6, v7
	v_add_f32_e32 v15, v10, v6
	v_rcp_f32_e32 v17, v15
	v_sub_f32_e32 v7, v15, v10
	v_sub_f32_e32 v16, v6, v7
	v_add_f32_e32 v7, v8, v9
	v_mul_f32_e32 v19, v7, v17
	v_sub_f32_e32 v6, v7, v8
	v_mul_f32_e32 v8, v15, v19
	v_fma_f32 v10, v19, v15, -v8
	v_fmac_f32_e32 v10, v19, v16
	v_sub_f32_e32 v18, v9, v6
	v_add_f32_e32 v6, v8, v10
	v_sub_f32_e32 v9, v7, v6
	v_pk_add_f32 v[12:13], v[6:7], v[8:9] neg_lo:[0,1] neg_hi:[0,1]
	v_mov_b32_e32 v11, v6
	v_pk_add_f32 v[6:7], v[12:13], v[10:11] neg_lo:[0,1] neg_hi:[0,1]
	s_mov_b32 s1, 0x3f317218
	v_add_f32_e32 v7, v18, v7
	v_add_f32_e32 v6, v6, v7
	v_add_f32_e32 v7, v9, v6
	v_mul_f32_e32 v18, v17, v7
	v_mul_f32_e32 v8, v15, v18
	v_fma_f32 v10, v18, v15, -v8
	v_fmac_f32_e32 v10, v18, v16
	v_sub_f32_e32 v9, v9, v7
	v_add_f32_e32 v15, v6, v9
	v_add_f32_e32 v6, v8, v10
	v_sub_f32_e32 v9, v7, v6
	v_pk_add_f32 v[12:13], v[6:7], v[8:9] neg_lo:[0,1] neg_hi:[0,1]
	v_mov_b32_e32 v11, v6
	v_pk_add_f32 v[6:7], v[12:13], v[10:11] neg_lo:[0,1] neg_hi:[0,1]
	v_cmp_nlt_f32_e32 vcc, 1.0, v22
	v_add_f32_e32 v7, v15, v7
	v_add_f32_e32 v6, v6, v7
	v_add_f32_e32 v7, v19, v18
	v_add_f32_e32 v6, v9, v6
	v_sub_f32_e32 v8, v7, v19
	v_mul_f32_e32 v6, v17, v6
	v_sub_f32_e32 v8, v18, v8
	v_add_f32_e32 v8, v8, v6
	v_add_f32_e32 v10, v7, v8
	v_mul_f32_e32 v11, v10, v10
	v_fmamk_f32 v6, v11, 0x3e9b6dac, v235
	v_fmaak_f32 v155, v11, v6, 0x3f2aaada
	v_cvt_f32_i32_e32 v6, v14
	v_sub_f32_e32 v7, v10, v7
	v_sub_f32_e32 v7, v8, v7
	v_ldexp_f32 v12, v7, 1
	v_mul_f32_e32 v7, v10, v11
	v_ldexp_f32 v9, v10, 1
	v_pk_mul_f32 v[10:11], v[6:7], v[154:155]
	v_ashrrev_i32_e32 v31, 31, v30
	v_fma_f32 v8, v6, s1, -v10
	v_fmac_f32_e32 v8, 0xb102e308, v6
	v_pk_add_f32 v[6:7], v[10:11], v[8:9]
	s_mov_b32 s1, 0x33800000
	v_sub_f32_e32 v9, v7, v9
	v_sub_f32_e32 v9, v11, v9
	v_add_f32_e32 v13, v12, v9
	v_mov_b32_e32 v12, v10
	v_pk_add_f32 v[10:11], v[6:7], v[10:11] neg_lo:[0,1] neg_hi:[0,1]
	v_pk_add_f32 v[14:15], v[6:7], v[12:13]
	v_mov_b32_e32 v9, v6
	v_mov_b32_e32 v11, v15
	v_pk_add_f32 v[16:17], v[8:9], v[10:11] neg_lo:[0,1] neg_hi:[0,1]
	v_pk_add_f32 v[8:9], v[8:9], v[10:11]
	v_mov_b32_e32 v20, v7
	v_pk_add_f32 v[10:11], v[8:9], v[6:7] op_sel:[1,0] op_sel_hi:[0,1] neg_lo:[0,1] neg_hi:[0,1]
	v_pk_add_f32 v[18:19], v[14:15], v[10:11] op_sel_hi:[1,0] neg_lo:[0,1] neg_hi:[0,1]
	v_mov_b32_e32 v14, v15
	v_mov_b32_e32 v15, v9
	v_mov_b32_e32 v21, v10
	v_pk_add_f32 v[10:11], v[14:15], v[20:21] neg_lo:[0,1] neg_hi:[0,1]
	v_mov_b32_e32 v12, v13
	v_mov_b32_e32 v13, v6
	v_pk_add_f32 v[6:7], v[12:13], v[10:11] neg_lo:[0,1] neg_hi:[0,1]
	v_mov_b32_e32 v18, v16
	v_pk_add_f32 v[10:11], v[18:19], v[6:7]
	v_mov_b32_e32 v17, v9
	v_pk_add_f32 v[12:13], v[10:11], v[10:11] op_sel:[0,1] op_sel_hi:[1,0]
	v_mov_b32_e32 v37, s36
	v_pk_add_f32 v[8:9], v[8:9], v[12:13] op_sel:[1,0] op_sel_hi:[0,1]
	v_mov_b32_e32 v11, v8
	v_pk_add_f32 v[14:15], v[10:11], v[16:17] neg_lo:[0,1] neg_hi:[0,1]
	v_mov_b32_e32 v7, v12
	v_sub_f32_e32 v9, v10, v14
	v_pk_add_f32 v[6:7], v[6:7], v[14:15] neg_lo:[0,1] neg_hi:[0,1]
	v_sub_f32_e32 v9, v16, v9
	v_add_f32_e32 v6, v6, v9
	v_add_f32_e32 v6, v6, v7
	v_add_f32_e32 v6, v8, v6
	v_mov_b32_e32 v7, 0x7fc00000
	v_cndmask_b32_e32 v6, v7, v6, vcc
	v_cmp_neq_f32_e32 vcc, 1.0, v22
	v_mov_b32_e32 v7, 0xff800000
	v_mov_b64_e32 v[8:9], s[76:77]
	v_cndmask_b32_e32 v6, v7, v6, vcc
	v_cmp_gt_f32_e32 vcc, s1, v22
	s_lshl_b32 s1, s22, 13
	s_or_b32 s16, s5, s1
	v_cndmask_b32_e64 v36, v6, -v22, vcc
	v_lshl_add_u64 v[6:7], v[30:31], 0, s[16:17]
	v_mad_u64_u32 v[8:9], s[6:7], v6, s71, v[8:9]
	v_add_u32_e32 v38, 0x2400, v37
	v_and_b32_e32 v50, 3, v132
	v_add_u32_e32 v33, 0x2400, v38
	v_mad_i32_i24 v9, v7, s71, v9
	s_mov_b32 s1, s17
	v_lshl_add_u64 v[22:23], v[8:9], 0, s[0:1]
	v_add_u32_e32 v34, 0x2400, v33
	v_lshlrev_b32_e32 v156, 4, v50
	s_waitcnt vmcnt(4)
	v_lshlrev_b32_e32 v24, 5, v50
	v_mov_b32_e32 v25, v157
	v_lshl_add_u64 v[10:11], v[22:23], 0, v[156:157]
	v_add_u32_e32 v35, 0x2400, v34
	v_lshl_add_u64 v[26:27], v[22:23], 0, v[24:25]
	global_load_dwordx4 v[14:17], v[10:11], off
	global_load_dwordx4 v[18:21], v[10:11], off offset:64
	global_load_dwordx4 v[6:9], v[10:11], off offset:512
	s_nop 0
	global_load_dwordx4 v[10:13], v[10:11], off offset:576
	s_nop 0
	global_load_dwordx4 v[22:25], v[26:27], off offset:1040
	s_nop 0
	global_load_dwordx4 v[26:29], v[26:27], off offset:1024
	v_lshlrev_b32_e32 v39, 3, v50
	v_lshlrev_b32_e32 v63, 1, v30
	s_or_b32 s0, s4, s21
	s_ashr_i32 s1, s0, 31
	s_lshl_b64 s[0:1], s[0:1], 13
	s_add_u32 s4, s89, s0
	v_and_b32_e32 v32, 15, v130
	s_waitcnt vmcnt(5)
	v_lshlrev_b32_e32 v46, 16, v14
	s_waitcnt vmcnt(4)
; __device__ __forceinline__ bf16_t f2bf(float f) { return (bf16_t)(pk2(f, 0.f) & 0xffffu); }
; __device__ __forceinline__ float fexp(float x) { return __expf(x); }
; __device__ __forceinline__ void ret_unit(const Ctx& X, LAS unsigned char* hl, int b, int c, int h, int tid_h, int w4, int lane) {
;     ...
;         const float pos = (float)(c * 64 + i);
;         const float qd = fexp(lg * (float)(i + 1)), kd = fexp(lg * (float)(63 - i));
;         float qr1[8], qr2[8], kr1[8], kr2[8], qe1[8], qe2[8];
; #pragma unroll
;         for (int e = 0; e < 8; ++e) {
;             const float inv = exp2f(-(float)(d0 + e) * (13.287712379549449f / 32.0f));
;             const float rev = __builtin_amdgcn_fractf(pos * inv * 0.15915494309189535f); const float sn = __builtin_amdgcn_sinf(rev), cs = __builtin_amdgcn_cosf(rev);
;             qr1[e] = qa[e] * cs - qb[e] * sn; qr2[e] = qa[e] * sn + qb[e] * cs;
;             kr1[e] = (ka[e] * cs - kb[e] * sn) * 0.125f; kr2[e] = (ka[e] * sn + kb[e] * cs) * 0.125f;
;             qe1[e] = qr1[e] * qd; qe2[e] = qr2[e] * qd;
;             KDT[(d0 + e) * LT + i] = f2bf(kr1[e] * kd); KDT[(d0 + 32 + e) * LT + i] = f2bf(kr2[e] * kd);
;             VT[(sg * 16 + e) * LT + i] = f2bf(va[e]); VT[(sg * 16 + 8 + e) * LT + i] = f2bf(vb[e]);
;         }
	v_lshlrev_b32_e32 v47, 16, v18
	s_waitcnt vmcnt(1)
	v_lshlrev_b32_e32 v59, 16, v23
	v_and_b32_e32 v60, 0xffff0000, v23
	v_add_u32_e32 v23, s5, v30
	s_waitcnt vmcnt(0)
	v_lshlrev_b32_e32 v55, 16, v28
	v_and_b32_e32 v56, 0xffff0000, v28
	v_cvt_f32_i32_e32 v28, v23
	v_add_u32_e32 v23, 1, v30
	v_cvt_f32_i32_e32 v23, v23
	v_lshlrev_b32_e32 v57, 16, v22
	v_and_b32_e32 v58, 0xffff0000, v22
	v_lshlrev_b32_e32 v42, 16, v25
	v_mul_f32_e32 v23, v36, v23
	v_mul_f32_e32 v23, 0x3fb8aa3b, v23
	v_and_b32_e32 v22, 0xffff0000, v25
	v_exp_f32_e32 v25, v23
	v_sub_u32_e32 v23, 63, v30
	v_cvt_f32_i32_e32 v23, v23
	v_lshlrev_b32_e32 v53, 16, v27
	v_and_b32_e32 v54, 0xffff0000, v27
	v_lshlrev_b32_e32 v61, 16, v24
	v_mul_f32_e32 v23, v36, v23
	v_mul_f32_e32 v23, 0x3fb8aa3b, v23
	v_exp_f32_e32 v27, v23
	v_cvt_f32_ubyte0_e32 v23, v39
	v_and_b32_e32 v62, 0xffff0000, v24
	v_mul_f32_e32 v24, 0xbed49a78, v23
	v_cmp_gt_f32_e32 vcc, s19, v24
	v_lshlrev_b32_e32 v51, 16, v26
	v_and_b32_e32 v52, 0xffff0000, v26
	v_cndmask_b32_e32 v24, 0, v1, vcc
	v_fmac_f32_e32 v24, 0xbed49a78, v23
	v_exp_f32_e32 v23, v24
	v_cndmask_b32_e32 v24, 0, v233, vcc
	v_lshlrev_b32_e32 v41, 16, v29
	v_and_b32_e32 v26, 0xffff0000, v29
	v_ldexp_f32 v23, v23, v24
	v_mul_f32_e32 v23, v23, v28
	v_mul_f32_e32 v23, 0.15915494, v23
	v_fract_f32_e32 v23, v23
	v_sin_f32_e32 v45, v23
	v_cos_f32_e32 v44, v23
	s_addc_u32 s5, s78, s1
	v_pk_mul_f32 v[48:49], v[44:45], v[46:47]
	s_nop 0
	v_sub_f32_e32 v43, v48, v49
	v_mov_b32_e32 v48, v45
	v_mov_b32_e32 v49, v44
	v_pk_mul_f32 v[46:47], v[48:49], v[46:47]
	v_mul_f32_e32 v24, v25, v43
	v_add_f32_e32 v40, v46, v47
	v_lshlrev_b32_e32 v47, 16, v10
	v_lshlrev_b32_e32 v46, 16, v6
	v_pk_mul_f32 v[44:45], v[44:45], v[46:47]
	s_nop 0
	v_sub_f32_e32 v23, v44, v45
	v_mul_f32_e32 v31, 0x3e000000, v23
	v_pk_mul_f32 v[44:45], v[48:49], v[46:47]
	v_and_b32_e32 v49, 0xffff0000, v18
	v_add_f32_e32 v23, v44, v45
	v_mul_f32_e32 v44, v27, v31
	v_mul_u32_u24_e32 v45, 0x480, v50
	v_mul_f32_e32 v29, 0x3e000000, v23
	v_cvt_pk_bf16_f32 v44, v44, v157
	v_add3_u32 v45, v33, v45, v63
	ds_write_b16 v45, v44
	v_mul_f32_e32 v44, v27, v29
	v_cvt_pk_bf16_f32 v44, v44, v157
	ds_write_b16 v45, v44 offset:4608
	v_mul_u32_u24_e32 v44, 0x900, v50
	v_cvt_pk_bf16_f32 v45, v51, v157
	v_add3_u32 v44, v34, v44, v63
	ds_write_b16 v44, v45
	v_cvt_pk_bf16_f32 v45, v57, v157
	ds_write_b16 v44, v45 offset:1152
	v_or_b32_e32 v45, 1, v39
	v_cvt_f32_ubyte0_e32 v46, v45
	v_mul_f32_e32 v47, 0xbed49a78, v46
	v_cmp_gt_f32_e32 vcc, s19, v47
	v_and_b32_e32 v48, 0xffff0000, v14
	v_mul_u32_u24_e32 v18, 0x90, v45
	v_cndmask_b32_e32 v47, 0, v1, vcc
	v_fmac_f32_e32 v47, 0xbed49a78, v46
	v_exp_f32_e32 v46, v47
	v_cndmask_b32_e32 v47, 0, v233, vcc
	v_add3_u32 v45, v33, v18, v63
	v_mul_f32_e32 v23, v25, v40
	v_ldexp_f32 v46, v46, v47
	v_mul_f32_e32 v46, v46, v28
	v_mul_f32_e32 v46, 0.15915494, v46
	v_fract_f32_e32 v46, v46
	v_sin_f32_e32 v47, v46
	v_cos_f32_e32 v46, v46
	s_nop 0
	v_pk_mul_f32 v[50:51], v[46:47], v[48:49]
	s_nop 0
	v_sub_f32_e32 v57, v50, v51
	v_mov_b32_e32 v50, v47
	v_mov_b32_e32 v51, v46
	v_pk_mul_f32 v[48:49], v[50:51], v[48:49]
	s_nop 0
	v_add_f32_e32 v64, v48, v49
	v_and_b32_e32 v49, 0xffff0000, v10
	v_and_b32_e32 v48, 0xffff0000, v6
	v_pk_mul_f32 v[46:47], v[46:47], v[48:49]
	v_mul_f32_e32 v10, v25, v57
	v_sub_f32_e32 v6, v46, v47
	v_mul_f32_e32 v65, 0x3e000000, v6
	v_pk_mul_f32 v[46:47], v[50:51], v[48:49]
	v_mul_f32_e32 v14, v27, v65
	v_add_f32_e32 v6, v46, v47
	v_mul_f32_e32 v66, 0x3e000000, v6
	v_cvt_pk_bf16_f32 v14, v14, v157
	ds_write_b16 v45, v14
	v_mul_f32_e32 v14, v27, v66
	v_cvt_pk_bf16_f32 v14, v14, v157
	ds_write_b16 v45, v14 offset:4608
	v_cvt_pk_bf16_f32 v14, v52, v157
	ds_write_b16 v44, v14 offset:144
	v_cvt_pk_bf16_f32 v14, v58, v157
	ds_write_b16 v44, v14 offset:1296
	v_or_b32_e32 v14, 2, v39
	v_cvt_f32_ubyte0_e32 v14, v14
	v_mul_f32_e32 v18, 0xbed49a78, v14
	v_cmp_gt_f32_e32 vcc, s19, v18
	v_lshlrev_b32_e32 v49, 16, v19
	v_lshlrev_b32_e32 v48, 16, v15
	v_cndmask_b32_e32 v18, 0, v1, vcc
	v_fmac_f32_e32 v18, 0xbed49a78, v14
	v_exp_f32_e32 v14, v18
	v_cndmask_b32_e32 v18, 0, v233, vcc
	v_and_b32_e32 v19, 0xffff0000, v19
	v_mul_f32_e32 v6, v25, v64
	v_ldexp_f32 v14, v14, v18
	v_mul_f32_e32 v14, v14, v28
	v_mul_f32_e32 v14, 0.15915494, v14
	v_fract_f32_e32 v14, v14
	v_sin_f32_e32 v47, v14
	v_cos_f32_e32 v46, v14
	s_nop 0
	v_pk_mul_f32 v[50:51], v[46:47], v[48:49]
	s_nop 0
	v_sub_f32_e32 v52, v50, v51
	v_mov_b32_e32 v50, v47
	v_mov_b32_e32 v51, v46
	v_pk_mul_f32 v[48:49], v[50:51], v[48:49]
	s_nop 0
	v_add_f32_e32 v58, v48, v49
	v_lshlrev_b32_e32 v49, 16, v11
	v_lshlrev_b32_e32 v48, 16, v7
	v_pk_mul_f32 v[46:47], v[46:47], v[48:49]
	s_nop 0
	v_sub_f32_e32 v14, v46, v47
	v_pk_mul_f32 v[46:47], v[50:51], v[48:49]
	v_mul_f32_e32 v63, 0x3e000000, v14
	v_add_f32_e32 v14, v46, v47
	v_mul_f32_e32 v48, 0x3e000000, v14
	v_mul_f32_e32 v14, v27, v63
	v_cvt_pk_bf16_f32 v14, v14, v157
	ds_write_b16 v45, v14 offset:144
	v_mul_f32_e32 v14, v27, v48
	v_cvt_pk_bf16_f32 v14, v14, v157
	ds_write_b16 v45, v14 offset:4752
	v_cvt_pk_bf16_f32 v14, v53, v157
	ds_write_b16 v44, v14 offset:288
	v_cvt_pk_bf16_f32 v14, v59, v157
	ds_write_b16 v44, v14 offset:1440
	v_or_b32_e32 v14, 3, v39
	v_cvt_f32_ubyte0_e32 v14, v14
	v_mul_f32_e32 v18, 0xbed49a78, v14
	v_cmp_gt_f32_e32 vcc, s19, v18
	v_mul_f32_e32 v49, v25, v52
	v_mul_f32_e32 v50, v25, v58
	v_cndmask_b32_e32 v18, 0, v1, vcc
	v_fmac_f32_e32 v18, 0xbed49a78, v14
	v_exp_f32_e32 v14, v18
	v_cndmask_b32_e32 v18, 0, v233, vcc
	v_ldexp_f32 v14, v14, v18
	v_mul_f32_e32 v14, v14, v28
	v_mul_f32_e32 v14, 0.15915494, v14
	v_fract_f32_e32 v14, v14
	v_sin_f32_e32 v47, v14
; __device__ __forceinline__ bf16_t f2bf(float f) { return (bf16_t)(pk2(f, 0.f) & 0xffffu); }
; __device__ __forceinline__ void ret_unit(const Ctx& X, LAS unsigned char* hl, int b, int c, int h, int tid_h, int w4, int lane) {
;     ...
; #pragma unroll
;         for (int e = 0; e < 8; ++e) {
;             const float inv = exp2f(-(float)(d0 + e) * (13.287712379549449f / 32.0f));
;             const float rev = __builtin_amdgcn_fractf(pos * inv * 0.15915494309189535f); const float sn = __builtin_amdgcn_sinf(rev), cs = __builtin_amdgcn_cosf(rev);
;             qr1[e] = qa[e] * cs - qb[e] * sn; qr2[e] = qa[e] * sn + qb[e] * cs;
;             kr1[e] = (ka[e] * cs - kb[e] * sn) * 0.125f; kr2[e] = (ka[e] * sn + kb[e] * cs) * 0.125f;
;             qe1[e] = qr1[e] * qd; qe2[e] = qr2[e] * qd;
;             KDT[(d0 + e) * LT + i] = f2bf(kr1[e] * kd); KDT[(d0 + 32 + e) * LT + i] = f2bf(kr2[e] * kd);
;             VT[(sg * 16 + e) * LT + i] = f2bf(va[e]); VT[(sg * 16 + 8 + e) * LT + i] = f2bf(vb[e]);
;         }
	v_cos_f32_e32 v46, v14
	v_and_b32_e32 v18, 0xffff0000, v15
	v_pk_mul_f32 v[14:15], v[46:47], v[18:19]
	s_nop 0
	v_sub_f32_e32 v51, v14, v15
	v_mov_b32_e32 v14, v47
	v_mov_b32_e32 v15, v46
	v_pk_mul_f32 v[18:19], v[14:15], v[18:19]
	v_mul_f32_e32 v59, v25, v51
	v_add_f32_e32 v53, v18, v19
	v_and_b32_e32 v19, 0xffff0000, v11
	v_and_b32_e32 v18, 0xffff0000, v7
	v_pk_mul_f32 v[46:47], v[46:47], v[18:19]
	v_pk_mul_f32 v[14:15], v[14:15], v[18:19]
	v_sub_f32_e32 v7, v46, v47
	v_mul_f32_e32 v7, 0x3e000000, v7
	v_add_f32_e32 v11, v14, v15
	v_mul_f32_e32 v14, v27, v7
	v_mul_f32_e32 v11, 0x3e000000, v11
	v_cvt_pk_bf16_f32 v14, v14, v157
	ds_write_b16 v45, v14 offset:288
	v_mul_f32_e32 v14, v27, v11
	v_cvt_pk_bf16_f32 v14, v14, v157
	ds_write_b16 v45, v14 offset:4896
	v_cvt_pk_bf16_f32 v14, v54, v157
	ds_write_b16 v44, v14 offset:432
	v_cvt_pk_bf16_f32 v14, v60, v157
	ds_write_b16 v44, v14 offset:1584
	v_or_b32_e32 v14, 4, v39
	v_cvt_f32_ubyte0_e32 v14, v14
	v_mul_f32_e32 v15, 0xbed49a78, v14
	v_cmp_gt_f32_e32 vcc, s19, v15
	v_lshlrev_b32_e32 v19, 16, v20
	v_lshlrev_b32_e32 v18, 16, v16
	v_cndmask_b32_e32 v15, 0, v1, vcc
	v_fmac_f32_e32 v15, 0xbed49a78, v14
	v_exp_f32_e32 v14, v15
	v_cndmask_b32_e32 v15, 0, v233, vcc
	v_mul_f32_e32 v67, v25, v53
	v_ldexp_f32 v14, v14, v15
	v_mul_f32_e32 v14, v14, v28
	v_mul_f32_e32 v14, 0.15915494, v14
	v_fract_f32_e32 v14, v14
	v_sin_f32_e32 v15, v14
	v_cos_f32_e32 v14, v14
	s_nop 0
	v_pk_mul_f32 v[46:47], v[14:15], v[18:19]
	s_nop 0
	v_sub_f32_e32 v54, v46, v47
	v_mov_b32_e32 v46, v15
	v_mov_b32_e32 v47, v14
	v_pk_mul_f32 v[18:19], v[46:47], v[18:19]
	v_mul_f32_e32 v70, v25, v54
	v_add_f32_e32 v60, v18, v19
	v_lshlrev_b32_e32 v19, 16, v12
	v_lshlrev_b32_e32 v18, 16, v8
	v_pk_mul_f32 v[14:15], v[14:15], v[18:19]
	v_mul_f32_e32 v71, v25, v60
	v_sub_f32_e32 v14, v14, v15
	v_mul_f32_e32 v68, 0x3e000000, v14
	v_pk_mul_f32 v[14:15], v[46:47], v[18:19]
	v_and_b32_e32 v19, 0xffff0000, v20
	v_add_f32_e32 v14, v14, v15
	v_mul_f32_e32 v69, 0x3e000000, v14
	v_mul_f32_e32 v14, v27, v68
	v_cvt_pk_bf16_f32 v14, v14, v157
	ds_write_b16 v45, v14 offset:432
	v_mul_f32_e32 v14, v27, v69
	v_cvt_pk_bf16_f32 v14, v14, v157
	ds_write_b16 v45, v14 offset:5040
	v_cvt_pk_bf16_f32 v14, v55, v157
	ds_write_b16 v44, v14 offset:576
	v_cvt_pk_bf16_f32 v14, v61, v157
	ds_write_b16 v44, v14 offset:1728
	v_or_b32_e32 v14, 5, v39
	v_cvt_f32_ubyte0_e32 v14, v14
	v_mul_f32_e32 v15, 0xbed49a78, v14
	v_cmp_gt_f32_e32 vcc, s19, v15
	v_and_b32_e32 v18, 0xffff0000, v16
	s_nop 0
	v_cndmask_b32_e32 v15, 0, v1, vcc
	v_fmac_f32_e32 v15, 0xbed49a78, v14
	v_exp_f32_e32 v14, v15
	v_cndmask_b32_e32 v15, 0, v233, vcc
	v_ldexp_f32 v14, v14, v15
	v_mul_f32_e32 v14, v14, v28
	v_mul_f32_e32 v14, 0.15915494, v14
	v_fract_f32_e32 v14, v14
	v_sin_f32_e32 v15, v14
	v_cos_f32_e32 v14, v14
	s_nop 0
	v_pk_mul_f32 v[46:47], v[14:15], v[18:19]
	s_nop 0
	v_sub_f32_e32 v20, v46, v47
	v_mov_b32_e32 v46, v15
	v_mov_b32_e32 v47, v14
	v_pk_mul_f32 v[18:19], v[46:47], v[18:19]
	v_mul_f32_e32 v73, v25, v20
	v_add_f32_e32 v55, v18, v19
	v_and_b32_e32 v19, 0xffff0000, v12
	v_and_b32_e32 v18, 0xffff0000, v8
	v_pk_mul_f32 v[14:15], v[14:15], v[18:19]
	v_mul_f32_e32 v74, v25, v55
	v_sub_f32_e32 v8, v14, v15
	v_pk_mul_f32 v[14:15], v[46:47], v[18:19]
	v_mul_f32_e32 v61, 0x3e000000, v8
	v_add_f32_e32 v8, v14, v15
	v_mul_f32_e32 v72, 0x3e000000, v8
	v_mul_f32_e32 v8, v27, v61
	v_cvt_pk_bf16_f32 v8, v8, v157
	ds_write_b16 v45, v8 offset:576
	v_mul_f32_e32 v8, v27, v72
	v_cvt_pk_bf16_f32 v8, v8, v157
	ds_write_b16 v45, v8 offset:5184
	v_cvt_pk_bf16_f32 v8, v56, v157
	ds_write_b16 v44, v8 offset:720
	v_cvt_pk_bf16_f32 v8, v62, v157
	ds_write_b16 v44, v8 offset:1872
	v_or_b32_e32 v8, 6, v39
	v_cvt_f32_ubyte0_e32 v8, v8
	v_mul_f32_e32 v12, 0xbed49a78, v8
	v_cmp_gt_f32_e32 vcc, s19, v12
	v_lshlrev_b32_e32 v19, 16, v21
	v_lshlrev_b32_e32 v18, 16, v17
	v_cndmask_b32_e32 v12, 0, v1, vcc
	v_fmac_f32_e32 v12, 0xbed49a78, v8
	v_exp_f32_e32 v8, v12
	v_cndmask_b32_e32 v12, 0, v233, vcc
	v_ldexp_f32 v8, v8, v12
	v_mul_f32_e32 v8, v8, v28
	v_mul_f32_e32 v8, 0.15915494, v8
	v_fract_f32_e32 v8, v8
	v_sin_f32_e32 v15, v8
	v_cos_f32_e32 v14, v8
	s_nop 0
	v_pk_mul_f32 v[46:47], v[14:15], v[18:19]
	s_nop 0
	v_sub_f32_e32 v56, v46, v47
	v_mov_b32_e32 v46, v15
	v_mov_b32_e32 v47, v14
	v_pk_mul_f32 v[18:19], v[46:47], v[18:19]
; #define LAS __attribute__((address_space(3)))
; __device__ __forceinline__ bf16_t f2bf(float f) { return (bf16_t)(pk2(f, 0.f) & 0xffffu); }
; __device__ __forceinline__ u32x4 pack8(const float (&f)[8]) { u32x4 w; w.x = pk2(f[0], f[1]); w.y = pk2(f[2], f[3]); w.z = pk2(f[4], f[5]); w.w = pk2(f[6], f[7]); return w; }
; #define LBAR() do { asm volatile("s_waitcnt lgkmcnt(0)" ::: "memory"); __builtin_amdgcn_s_barrier(); asm volatile("" ::: "memory"); } while (0)
; __device__ __forceinline__ void ret_unit(const Ctx& X, LAS unsigned char* hl, int b, int c, int h, int tid_h, int w4, int lane) {
;     ...
;             const float inv = exp2f(-(float)(d0 + e) * (13.287712379549449f / 32.0f));
;             const float rev = __builtin_amdgcn_fractf(pos * inv * 0.15915494309189535f); const float sn = __builtin_amdgcn_sinf(rev), cs = __builtin_amdgcn_cosf(rev);
;             qr1[e] = qa[e] * cs - qb[e] * sn; qr2[e] = qa[e] * sn + qb[e] * cs;
;             kr1[e] = (ka[e] * cs - kb[e] * sn) * 0.125f; kr2[e] = (ka[e] * sn + kb[e] * cs) * 0.125f;
;             qe1[e] = qr1[e] * qd; qe2[e] = qr2[e] * qd;
;             KDT[(d0 + e) * LT + i] = f2bf(kr1[e] * kd); KDT[(d0 + 32 + e) * LT + i] = f2bf(kr2[e] * kd);
;             VT[(sg * 16 + e) * LT + i] = f2bf(va[e]); VT[(sg * 16 + 8 + e) * LT + i] = f2bf(vb[e]);
;         }
;         *(LAS u32x4*)(QR + i * LT + d0) = pack8(qr1); *(LAS u32x4*)(QR + i * LT + d0 + 32) = pack8(qr2);
;         *(LAS u32x4*)(KR + i * LT + d0) = pack8(kr1); *(LAS u32x4*)(KR + i * LT + d0 + 32) = pack8(kr2);
;         bf16_t* qe = WSP(bf16_t, WS_QEFF) + (size_t)uid * 4096 + i * 64;
;         *(u32x4*)(qe + d0) = pack8(qe1); *(u32x4*)(qe + d0 + 32) = pack8(qe2);
;     }
;     LBAR();
; __device__ __forceinline__ void mixer_local_phase(const Ctx& X, LAS unsigned char* lds, int layer, int tid, int wave, int lane) {
;     ...
;     const int nit_ = (3584 + (int)gridDim.x - 1) / (int)gridDim.x;
;     for (int it_ = 0; it_ < nit_; ++it_) {
;         const int u = (int)blockIdx.x + (int)gridDim.x * ((it_ + (int)(blockIdx.x >> 3)) % nit_);
;         if (u >= 3584) continue;
;         asm volatile("" : "+v"(tid_h), "+v"(lane), "+v"(tid));
;         if (u < 3072) { const int mixer = u >> 10, idx = u & 1023, hp = idx & 1, cb = idx >> 1, b = cb >> 7, c = cb & 127, h = hp * 2 + hs;
	s_nop 0
	v_add_f32_e32 v62, v18, v19
	v_lshlrev_b32_e32 v19, 16, v13
	v_lshlrev_b32_e32 v18, 16, v9
	v_pk_mul_f32 v[14:15], v[14:15], v[18:19]
	v_and_b32_e32 v13, 0xffff0000, v13
	v_sub_f32_e32 v8, v14, v15
	v_pk_mul_f32 v[14:15], v[46:47], v[18:19]
	v_mul_f32_e32 v75, 0x3e000000, v8
	v_add_f32_e32 v8, v14, v15
	v_mul_f32_e32 v46, 0x3e000000, v8
	v_mul_f32_e32 v8, v27, v75
	v_cvt_pk_bf16_f32 v8, v8, v157
	ds_write_b16 v45, v8 offset:720
	v_mul_f32_e32 v8, v27, v46
	v_cvt_pk_bf16_f32 v8, v8, v157
	ds_write_b16 v45, v8 offset:5328
	v_cvt_pk_bf16_f32 v8, v41, v157
	ds_write_b16 v44, v8 offset:864
	v_cvt_pk_bf16_f32 v8, v42, v157
	ds_write_b16 v44, v8 offset:2016
	v_or_b32_e32 v8, 7, v39
	v_cvt_f32_ubyte0_e32 v8, v8
	v_mul_f32_e32 v12, 0xbed49a78, v8
	v_cmp_gt_f32_e32 vcc, s19, v12
	v_and_b32_e32 v19, 0xffff0000, v21
	v_and_b32_e32 v18, 0xffff0000, v17
	v_cndmask_b32_e32 v12, 0, v1, vcc
	v_fmac_f32_e32 v12, 0xbed49a78, v8
	v_exp_f32_e32 v8, v12
	v_cndmask_b32_e32 v12, 0, v233, vcc
	v_mul_f32_e32 v47, v25, v56
	v_mul_f32_e32 v76, v25, v62
	v_ldexp_f32 v8, v8, v12
	v_mul_f32_e32 v8, v8, v28
	v_mul_f32_e32 v8, 0.15915494, v8
	v_fract_f32_e32 v8, v8
	v_sin_f32_e32 v15, v8
	v_cos_f32_e32 v14, v8
	v_and_b32_e32 v12, 0xffff0000, v9
	v_readlane_b32 s19, v255, 26
	v_pk_mul_f32 v[16:17], v[14:15], v[18:19]
	v_pk_mul_f32 v[8:9], v[14:15], v[12:13]
	v_sub_f32_e32 v21, v16, v17
	v_mov_b32_e32 v16, v15
	v_mov_b32_e32 v17, v14
	v_sub_f32_e32 v8, v8, v9
	v_mul_f32_e32 v28, 0x3e000000, v8
	v_pk_mul_f32 v[8:9], v[16:17], v[12:13]
	v_pk_mul_f32 v[18:19], v[16:17], v[18:19]
	v_add_f32_e32 v8, v8, v9
	v_mul_f32_e32 v9, v27, v28
	v_mul_f32_e32 v8, 0x3e000000, v8
	v_cvt_pk_bf16_f32 v9, v9, v157
	ds_write_b16 v45, v9 offset:864
	v_mul_f32_e32 v9, v27, v8
	v_cvt_pk_bf16_f32 v9, v9, v157
	ds_write_b16 v45, v9 offset:5472
	v_cvt_pk_bf16_f32 v9, v26, v157
	ds_write_b16 v44, v9 offset:1008
	v_cvt_pk_bf16_f32 v9, v22, v157
	ds_write_b16 v44, v9 offset:2160
	v_mul_lo_u32 v9, v30, s44
	v_cvt_pk_bf16_f32 v12, v43, v57
	v_cvt_pk_bf16_f32 v13, v52, v51
	v_cvt_pk_bf16_f32 v14, v54, v20
	v_cvt_pk_bf16_f32 v15, v56, v21
	v_add3_u32 v20, v37, v9, v156
	v_add_f32_e32 v19, v18, v19
	ds_write_b128 v20, v[12:15]
	v_cvt_pk_bf16_f32 v12, v40, v64
	v_cvt_pk_bf16_f32 v13, v58, v53
	v_cvt_pk_bf16_f32 v14, v60, v55
	v_cvt_pk_bf16_f32 v15, v62, v19
	ds_write_b128 v20, v[12:15] offset:64
	v_cvt_pk_bf16_f32 v12, v31, v65
	v_cvt_pk_bf16_f32 v13, v63, v7
	v_cvt_pk_bf16_f32 v14, v68, v61
	v_cvt_pk_bf16_f32 v15, v75, v28
	v_add3_u32 v7, v38, v9, v156
	ds_write_b128 v7, v[12:15]
	v_cvt_pk_bf16_f32 v12, v29, v66
	v_cvt_pk_bf16_f32 v13, v48, v11
	v_cvt_pk_bf16_f32 v14, v69, v72
	v_cvt_pk_bf16_f32 v15, v46, v8
	v_lshlrev_b32_e32 v8, 6, v30
	v_ashrrev_i32_e32 v9, 31, v8
	ds_write_b128 v7, v[12:15] offset:64
	v_lshl_add_u64 v[12:13], v[8:9], 1, s[4:5]
	v_lshl_add_u64 v[12:13], v[12:13], 0, v[156:157]
	v_mul_f32_e32 v16, v25, v21
	v_cvt_pk_bf16_f32 v8, v24, v10
	v_cvt_pk_bf16_f32 v9, v49, v59
	v_cvt_pk_bf16_f32 v10, v70, v73
	v_cvt_pk_bf16_f32 v11, v47, v16
	global_store_dwordx4 v[12:13], v[8:11], off
	v_cvt_pk_bf16_f32 v6, v23, v6
	v_mul_f32_e32 v17, v25, v19
	v_cvt_pk_bf16_f32 v7, v50, v67
	v_and_b32_e32 v20, -16, v130
	v_cvt_pk_bf16_f32 v8, v71, v74
	v_cvt_pk_bf16_f32 v9, v76, v17
	global_store_dwordx4 v[12:13], v[6:9], off offset:64
	v_add_u32_e32 v29, v38, v20
	s_waitcnt lgkmcnt(0)
	s_barrier
	s_add_i32 s98, s20, 1
	s_cmp_ge_u32 s98, s70
	s_cbranch_scc1 .LpfR_done
	s_add_i32 s98, s98, s37
	s_mul_hi_u32 s99, s98, s87
	s_mul_i32 s99, s99, s70
	s_sub_i32 s98, s98, s99
	s_sub_i32 s99, s98, s70
	s_cmp_ge_u32 s98, s70
	s_cselect_b32 s98, s99, s98
	s_sub_i32 s99, s98, s70
	s_cmp_ge_u32 s98, s70
	s_cselect_b32 s98, s99, s98
	s_mul_i32 s98, s98, s18
	s_add_i32 s98, s98, s2
	v_lshrrev_b32_e32 v237, 3, v224
	v_and_b32_e32 v238, 7, v224
	s_cmpk_ge_u32 s98, 0xc00
	s_cbranch_scc1 .LpfR_conf
	s_lshr_b32 s99, s98, 10
	s_and_b32 s98, s98, 0x3ff
	s_and_b32 s100, s98, 1
	s_lshr_b32 s98, s98, 1
	s_cmp_eq_u32 s99, 2
	s_mul_i32 s99, s99, 0xc00
	s_cselect_b32 s101, 0x400, 0
	s_sub_u32 s99, s99, s101
	s_lshl_b32 s100, s100, 8
	s_add_u32 s99, s99, s100
	v_min_u32_e32 v238, 5, v238
	v_lshrrev_b32_e32 v239, 1, v238
	v_and_b32_e32 v238, 1, v238
	v_lshlrev_b32_e32 v239, 9, v239
	v_lshl_or_b32 v238, v238, 7, v239
	s_branch .LpfR_go

; __device__ __forceinline__ bf16_t f2bf(float f) { return (bf16_t)(pk2(f, 0.f) & 0xffffu); }
; __device__ __forceinline__ float fexp(float x) { return __expf(x); }
; #define LBAR() do { asm volatile("s_waitcnt lgkmcnt(0)" ::: "memory"); __builtin_amdgcn_s_barrier(); asm volatile("" ::: "memory"); } while (0)
; __device__ __forceinline__ void ret_unit(const Ctx& X, LAS unsigned char* hl, int b, int c, int h, int tid_h, int w4, int lane) {
;     ...
;     f32x4 acc[4];
; #pragma unroll
;     for (int ct = 0; ct < 4; ++ct) acc[ct] = mma16(QR, 16 * w4, KR, 16 * ct, (f32x4){0.f, 0.f, 0.f, 0.f}, r, q);
; #pragma unroll
;     for (int ct = 0; ct < 4; ++ct)
; #pragma unroll
;         for (int j = 0; j < 4; ++j) { const int ii = 16 * w4 + 4 * q + j, col = 16 * ct + r;
;             P[ii * LT + col] = f2bf(ii >= col ? acc[ct][j] * fexp(lg * (float)(ii - col)) : 0.f); }
;     LBAR();
.LpfR_done:
	v_or_b32_e32 v6, s39, v32
	v_mul_u32_u24_e32 v19, 0x90, v6
	v_add3_u32 v10, v37, v19, v20
	v_mad_u32_u24 v14, v32, s44, v29
	ds_read_b128 v[6:9], v10
	ds_read_b128 v[38:41], v10 offset:64
	ds_read_b128 v[10:13], v14
	ds_read_b128 v[14:17], v14 offset:64
	s_waitcnt lgkmcnt(1)
	v_mfma_f32_16x16x32_bf16 v[10:13], v[6:9], v[10:13], 0
	v_ashrrev_i32_e32 v18, 4, v130
	v_or_b32_e32 v31, 16, v32
	v_or_b32_e32 v28, 32, v32
	s_waitcnt lgkmcnt(0)
	v_mfma_f32_16x16x32_bf16 v[42:45], v[38:41], v[14:17], v[10:13]
	s_add_u32 s4, s79, s0
	s_addc_u32 s5, s80, s1
	s_add_u32 s0, s74, s0
	v_mov_b32_e32 v10, 0x900
	v_mad_u32_u24 v21, v32, s44, v10
	v_add_u32_e32 v14, v29, v21
	ds_read_b128 v[10:13], v14
	ds_read_b128 v[14:17], v14 offset:64
	s_waitcnt lgkmcnt(1)
	v_mfma_f32_16x16x32_bf16 v[10:13], v[6:9], v[10:13], 0
	s_addc_u32 s1, s75, s1
	s_waitcnt lgkmcnt(0)
	v_mfma_f32_16x16x32_bf16 v[14:17], v[38:41], v[14:17], v[10:13]
	s_nop 4
	v_mov_b32_e32 v10, 0x1200
	v_mad_u32_u24 v22, v32, s44, v10
	v_add_u32_e32 v23, v29, v22
	ds_read_b128 v[10:13], v23
	ds_read_b128 v[24:27], v23 offset:64
	s_waitcnt lgkmcnt(1)
	v_mfma_f32_16x16x32_bf16 v[10:13], v[6:9], v[10:13], 0
	v_mov_b32_e32 v23, 0x1b00
	v_mad_u32_u24 v23, v32, s44, v23
	s_waitcnt lgkmcnt(0)
	v_mfma_f32_16x16x32_bf16 v[10:13], v[38:41], v[24:27], v[10:13]
	v_lshl_add_u32 v27, v18, 2, s39
	v_sub_u32_e32 v26, v27, v32
	v_cvt_f32_i32_e32 v26, v26
	v_add_u32_e32 v25, v29, v23
	ds_read_b128 v[46:49], v25
	v_cmp_ge_i32_e32 vcc, v27, v32
	v_mul_f32_e32 v26, v36, v26
	v_mul_f32_e32 v26, 0x3fb8aa3b, v26
	v_exp_f32_e32 v26, v26
	s_waitcnt lgkmcnt(0)
	v_mfma_f32_16x16x32_bf16 v[6:9], v[6:9], v[46:49], 0
	ds_read_b128 v[46:49], v25 offset:64
	v_lshlrev_b32_e32 v25, 1, v32
	v_mul_f32_e32 v26, v26, v42
	v_cndmask_b32_e32 v26, 0, v26, vcc
	v_mul_lo_u32 v29, v27, s44
	v_cvt_pk_bf16_f32 v26, v26, v157
	v_add3_u32 v25, v35, v25, v29
	v_or_b32_e32 v30, 1, v27
	ds_write_b16 v25, v26
	v_sub_u32_e32 v26, v30, v32
	v_cvt_f32_i32_e32 v26, v26
	v_cmp_ge_i32_e32 vcc, v30, v32
	v_or_b32_e32 v29, 2, v27
	v_or_b32_e32 v24, 48, v32
	v_mul_f32_e32 v26, v36, v26
	v_mul_f32_e32 v26, 0x3fb8aa3b, v26
	v_exp_f32_e32 v26, v26
	s_waitcnt lgkmcnt(1)
	v_mfma_f32_16x16x32_bf16 v[6:9], v[38:41], v[46:49], v[6:9]
	v_add_u32_e32 v38, v34, v20
	v_mad_u32_u24 v39, v32, s44, v38
	v_mul_f32_e32 v26, v26, v43
	v_cndmask_b32_e32 v26, 0, v26, vcc
	v_cvt_pk_bf16_f32 v26, v26, v157
	ds_write_b16 v25, v26 offset:144
	v_sub_u32_e32 v26, v29, v32
	v_cvt_f32_i32_e32 v26, v26
	v_cmp_ge_i32_e32 vcc, v29, v32
	v_add_u32_e32 v40, v38, v21
	v_add_u32_e32 v41, v38, v22
	v_mul_f32_e32 v26, v36, v26
	v_mul_f32_e32 v26, 0x3fb8aa3b, v26
	v_exp_f32_e32 v26, v26
	v_add_u32_e32 v38, v38, v23
	v_mul_f32_e32 v26, v26, v44
	v_cndmask_b32_e32 v26, 0, v26, vcc
	v_cvt_pk_bf16_f32 v26, v26, v157
	ds_write_b16 v25, v26 offset:288
	v_or_b32_e32 v26, 3, v27
	v_sub_u32_e32 v37, v26, v32
	v_cvt_f32_i32_e32 v37, v37
	v_cmp_ge_i32_e32 vcc, v26, v32
	v_mul_f32_e32 v37, v36, v37
	v_mul_f32_e32 v37, 0x3fb8aa3b, v37
	v_exp_f32_e32 v37, v37
	s_nop 0
	v_mul_f32_e32 v37, v37, v45
	v_cndmask_b32_e32 v37, 0, v37, vcc
	v_cvt_pk_bf16_f32 v37, v37, v157
	ds_write_b16 v25, v37 offset:432
	v_sub_u32_e32 v37, v27, v31
	v_cvt_f32_i32_e32 v37, v37
	v_cmp_ge_i32_e32 vcc, v27, v31
	v_mul_f32_e32 v37, v36, v37
	v_mul_f32_e32 v37, 0x3fb8aa3b, v37
	v_exp_f32_e32 v37, v37
	s_nop 0
	v_mul_f32_e32 v14, v37, v14
	v_cndmask_b32_e32 v14, 0, v14, vcc
	v_cvt_pk_bf16_f32 v14, v14, v157
	ds_write_b16 v25, v14 offset:32
	v_sub_u32_e32 v14, v30, v31
	v_cvt_f32_i32_e32 v14, v14
	v_cmp_ge_i32_e32 vcc, v30, v31
	v_mul_f32_e32 v14, v36, v14
	v_mul_f32_e32 v14, 0x3fb8aa3b, v14
	v_exp_f32_e32 v14, v14
	s_nop 0
	v_mul_f32_e32 v14, v14, v15
	v_cndmask_b32_e32 v14, 0, v14, vcc
	v_cvt_pk_bf16_f32 v14, v14, v157
	ds_write_b16 v25, v14 offset:176
	v_sub_u32_e32 v14, v29, v31
	v_cvt_f32_i32_e32 v14, v14
	v_cmp_ge_i32_e32 vcc, v29, v31
	v_mul_f32_e32 v14, v36, v14
	v_mul_f32_e32 v14, 0x3fb8aa3b, v14
	v_exp_f32_e32 v14, v14
	s_nop 0
	v_mul_f32_e32 v14, v14, v16
	v_cndmask_b32_e32 v14, 0, v14, vcc
	v_cvt_pk_bf16_f32 v14, v14, v157
	ds_write_b16 v25, v14 offset:320
	v_sub_u32_e32 v14, v26, v31
	v_cvt_f32_i32_e32 v14, v14
	v_cmp_ge_i32_e32 vcc, v26, v31
	v_mul_f32_e32 v14, v36, v14
	v_mul_f32_e32 v14, 0x3fb8aa3b, v14
	v_exp_f32_e32 v14, v14
	s_nop 0
	v_mul_f32_e32 v14, v14, v17
	v_cndmask_b32_e32 v14, 0, v14, vcc
	v_cvt_pk_bf16_f32 v14, v14, v157
	ds_write_b16 v25, v14 offset:464
	v_sub_u32_e32 v14, v27, v28
	v_cvt_f32_i32_e32 v14, v14
	v_cmp_ge_i32_e32 vcc, v27, v28
	v_mul_f32_e32 v14, v36, v14
	v_mul_f32_e32 v14, 0x3fb8aa3b, v14
	v_exp_f32_e32 v14, v14
	s_nop 0
	v_mul_f32_e32 v10, v14, v10
	v_cndmask_b32_e32 v10, 0, v10, vcc
	v_cvt_pk_bf16_f32 v10, v10, v157
	ds_write_b16 v25, v10 offset:64
	v_sub_u32_e32 v10, v30, v28
	v_cvt_f32_i32_e32 v10, v10
	v_cmp_ge_i32_e32 vcc, v30, v28
	v_mul_f32_e32 v10, v36, v10
	v_mul_f32_e32 v10, 0x3fb8aa3b, v10
	v_exp_f32_e32 v10, v10
	s_nop 0
	v_mul_f32_e32 v10, v10, v11
	v_cndmask_b32_e32 v10, 0, v10, vcc
	v_cvt_pk_bf16_f32 v10, v10, v157
	ds_write_b16 v25, v10 offset:208
	v_sub_u32_e32 v10, v29, v28
	v_cvt_f32_i32_e32 v10, v10
	v_cmp_ge_i32_e32 vcc, v29, v28
	v_mul_f32_e32 v10, v36, v10
	v_mul_f32_e32 v10, 0x3fb8aa3b, v10
	v_exp_f32_e32 v10, v10
	s_nop 0
	v_mul_f32_e32 v10, v10, v12
	v_cndmask_b32_e32 v10, 0, v10, vcc
	v_cvt_pk_bf16_f32 v10, v10, v157
	ds_write_b16 v25, v10 offset:352
	v_sub_u32_e32 v10, v26, v28
	v_cvt_f32_i32_e32 v10, v10
	v_cmp_ge_i32_e32 vcc, v26, v28
	v_mul_f32_e32 v10, v36, v10
	v_mul_f32_e32 v10, 0x3fb8aa3b, v10
	v_exp_f32_e32 v10, v10
	s_nop 0
	v_mul_f32_e32 v10, v10, v13
	v_cndmask_b32_e32 v10, 0, v10, vcc
	v_cvt_pk_bf16_f32 v10, v10, v157
	ds_write_b16 v25, v10 offset:496
	v_sub_u32_e32 v10, v27, v24
	v_cvt_f32_i32_e32 v10, v10
	v_cmp_ge_i32_e32 vcc, v27, v24
	v_mul_f32_e32 v10, v36, v10
	v_mul_f32_e32 v10, 0x3fb8aa3b, v10
	v_exp_f32_e32 v10, v10
	s_nop 0
	v_mul_f32_e32 v6, v10, v6
	v_cndmask_b32_e32 v6, 0, v6, vcc
	v_cvt_pk_bf16_f32 v6, v6, v157
	ds_write_b16 v25, v6 offset:96
	v_sub_u32_e32 v6, v30, v24
	v_cvt_f32_i32_e32 v6, v6
	v_cmp_ge_i32_e32 vcc, v30, v24
	v_add3_u32 v10, v35, v19, v20
	v_mul_f32_e32 v6, v36, v6
	v_mul_f32_e32 v6, 0x3fb8aa3b, v6
	v_exp_f32_e32 v6, v6
	s_nop 0
	v_mul_f32_e32 v6, v6, v7
	v_cndmask_b32_e32 v6, 0, v6, vcc
	v_cvt_pk_bf16_f32 v6, v6, v157
	ds_write_b16 v25, v6 offset:240
	v_sub_u32_e32 v6, v29, v24
	v_cvt_f32_i32_e32 v6, v6
	v_cmp_ge_i32_e32 vcc, v29, v24
	v_mul_f32_e32 v6, v36, v6
	v_mul_f32_e32 v6, 0x3fb8aa3b, v6
	v_exp_f32_e32 v6, v6
	s_nop 0
	v_mul_f32_e32 v6, v6, v8
	v_cndmask_b32_e32 v6, 0, v6, vcc
	v_cvt_pk_bf16_f32 v6, v6, v157
	ds_write_b16 v25, v6 offset:384
	v_sub_u32_e32 v6, v26, v24
	v_cvt_f32_i32_e32 v6, v6
	v_cmp_ge_i32_e32 vcc, v26, v24
	v_mul_f32_e32 v6, v36, v6
	v_mul_f32_e32 v6, 0x3fb8aa3b, v6
	v_exp_f32_e32 v6, v6
	s_nop 0
	v_mul_f32_e32 v6, v6, v9
	v_cndmask_b32_e32 v6, 0, v6, vcc
	v_cvt_pk_bf16_f32 v6, v6, v157
	ds_write_b16 v25, v6 offset:528
	s_waitcnt lgkmcnt(0)
	s_barrier
; #define LBAR() do { asm volatile("s_waitcnt lgkmcnt(0)" ::: "memory"); __builtin_amdgcn_s_barrier(); asm volatile("" ::: "memory"); } while (0)
; __device__ __forceinline__ void ret_unit(const Ctx& X, LAS unsigned char* hl, int b, int c, int h, int tid_h, int w4, int lane) {
;     ...
; #pragma unroll
;     for (int ct = 0; ct < 4; ++ct) acc[ct] = mma16(P, 16 * w4, VT, 16 * ct, (f32x4){0.f, 0.f, 0.f, 0.f}, r, q);
;     store_oloc(WSP(bf16_t, WS_OLOC), uid, w4, lane, acc);
; #pragma unroll
;     for (int ct = 0; ct < 4; ++ct) acc[ct] = mma16(KDT, 16 * w4, VT, 16 * ct, (f32x4){0.f, 0.f, 0.f, 0.f}, r, q);
;     store_bc(WSP(bf16_t, WS_BCS), uid, w4, r, q, acc);
;     LBAR();
	ds_read_b128 v[6:9], v10
	ds_read_b128 v[10:13], v10 offset:64
	ds_read_b128 v[14:17], v39
	ds_read_b128 v[24:27], v39 offset:64
	s_waitcnt lgkmcnt(1)
	v_mfma_f32_16x16x32_bf16 v[14:17], v[6:9], v[14:17], 0
	ds_read_b128 v[28:31], v40 offset:64
	ds_read_b128 v[34:37], v41 offset:64
	s_waitcnt lgkmcnt(2)
	v_mfma_f32_16x16x32_bf16 v[14:17], v[10:13], v[24:27], v[14:17]
	ds_read_b128 v[24:27], v40
	s_waitcnt lgkmcnt(0)
	v_mfma_f32_16x16x32_bf16 v[24:27], v[6:9], v[24:27], 0
	v_mfma_f32_16x16x32_bf16 v[24:27], v[10:13], v[28:31], v[24:27]
	ds_read_b128 v[28:31], v41
	s_waitcnt lgkmcnt(0)
	v_mfma_f32_16x16x32_bf16 v[28:31], v[6:9], v[28:31], 0
	v_mfma_f32_16x16x32_bf16 v[28:31], v[10:13], v[34:37], v[28:31]
	ds_read_b128 v[34:37], v38
	s_waitcnt lgkmcnt(0)
	v_mfma_f32_16x16x32_bf16 v[6:9], v[6:9], v[34:37], 0
	ds_read_b128 v[34:37], v38 offset:64
	s_waitcnt lgkmcnt(0)
	v_mfma_f32_16x16x32_bf16 v[6:9], v[10:13], v[34:37], v[6:9]
	v_lshlrev_b32_e32 v10, 4, v130
	v_ashrrev_i32_e32 v11, 31, v10
	v_lshl_add_u64 v[22:23], v[10:11], 1, s[4:5]
	v_cvt_pk_bf16_f32 v10, v14, v15
	v_cvt_pk_bf16_f32 v11, v16, v17
	v_cvt_pk_bf16_f32 v12, v24, v25
	v_cvt_pk_bf16_f32 v13, v26, v27
	v_cvt_pk_bf16_f32 v14, v28, v29
	v_cvt_pk_bf16_f32 v15, v30, v31
	v_cvt_pk_bf16_f32 v16, v6, v7
	v_cvt_pk_bf16_f32 v17, v8, v9
	global_store_dwordx4 v[22:23], v[10:13], off nt
	global_store_dwordx4 v[22:23], v[14:17], off offset:16 nt
	s_nop 0
	v_add3_u32 v10, v33, v19, v20
	s_nop 0
	ds_read_b128 v[6:9], v10
	ds_read_b128 v[10:13], v10 offset:64
	ds_read_b128 v[14:17], v39
	ds_read_b128 v[20:23], v39 offset:64
	ds_read_b128 v[24:27], v40 offset:64
	s_waitcnt lgkmcnt(2)
	v_mfma_f32_16x16x32_bf16 v[14:17], v[6:9], v[14:17], 0
	ds_read_b128 v[28:31], v41 offset:64
	s_waitcnt lgkmcnt(2)
	v_mfma_f32_16x16x32_bf16 v[14:17], v[10:13], v[20:23], v[14:17]
	ds_read_b128 v[20:23], v40
	s_waitcnt lgkmcnt(0)
	v_mfma_f32_16x16x32_bf16 v[20:23], v[6:9], v[20:23], 0
	v_mfma_f32_16x16x32_bf16 v[20:23], v[10:13], v[24:27], v[20:23]
	ds_read_b128 v[24:27], v41
	s_waitcnt lgkmcnt(0)
	v_mfma_f32_16x16x32_bf16 v[24:27], v[6:9], v[24:27], 0
	v_mfma_f32_16x16x32_bf16 v[24:27], v[10:13], v[28:31], v[24:27]
	ds_read_b128 v[28:31], v38
	s_waitcnt lgkmcnt(0)
	v_mfma_f32_16x16x32_bf16 v[6:9], v[6:9], v[28:31], 0
	ds_read_b128 v[28:31], v38 offset:64
	s_waitcnt lgkmcnt(0)
	v_mfma_f32_16x16x32_bf16 v[6:9], v[10:13], v[28:31], v[6:9]
	v_lshl_or_b32 v12, v32, 2, s81
	v_lshl_add_u32 v12, v18, 6, v12
	v_ashrrev_i32_e32 v13, 31, v12
	v_cvt_pk_bf16_f32 v10, v14, v15
	v_cvt_pk_bf16_f32 v11, v16, v17
	v_lshl_add_u64 v[14:15], v[12:13], 1, s[0:1]
	global_store_dwordx2 v[14:15], v[10:11], off
	v_cvt_pk_bf16_f32 v10, v20, v21
	v_cvt_pk_bf16_f32 v11, v22, v23
	global_store_dwordx2 v[14:15], v[10:11], off offset:2048
	v_add_u32_e32 v14, 0x800, v12
	v_ashrrev_i32_e32 v15, 31, v14
	v_lshl_add_u64 v[14:15], v[14:15], 1, s[0:1]
	v_cvt_pk_bf16_f32 v10, v24, v25
	v_cvt_pk_bf16_f32 v11, v26, v27
	global_store_dwordx2 v[14:15], v[10:11], off
	v_cvt_pk_bf16_f32 v6, v6, v7
	v_cvt_pk_bf16_f32 v7, v8, v9
	v_add_u32_e32 v8, 0xc00, v12
	v_ashrrev_i32_e32 v9, 31, v8
	v_lshl_add_u64 v[8:9], v[8:9], 1, s[0:1]
	global_store_dwordx2 v[8:9], v[6:7], off
	s_waitcnt lgkmcnt(0)
	s_barrier
	s_branch .LBB0_233

; __device__ __forceinline__ unsigned cvt_pk_bf16(float lo, float hi) { unsigned r; asm volatile("v_cvt_pk_bf16_f32 %0, %1, %2" : "=v"(r) : "v"(lo), "v"(hi)); return r; }
; __device__ __forceinline__ float silu_f(float g) { return g * __builtin_amdgcn_rcpf(1.0f + __expf(-g)); }
;     __device__ __forceinline__ void operator()(const f32x4 (&acc)[2][2][4][2], const Unit& u, int wr, int wc, int fr, int fq, const float (&rsv)[8]) const {
;     ...
;                 const float rs = __builtin_amdgcn_rsqf(rsv[ai * 4 + m] * (1.0f / 1024.0f) + 1e-6f);
;                 const f32x4 g0 = acc[ai][0][m][0] * rs, g1 = acc[ai][0][m][1] * rs, u0 = acc[ai][1][m][0] * rs, u1 = acc[ai][1][m][1] * rs; u32x4 w;
;                 w.x = cvt_pk_bf16(silu_f(g0[0]) * u0[0], silu_f(g0[1]) * u0[1]); w.y = cvt_pk_bf16(silu_f(g0[2]) * u0[2], silu_f(g0[3]) * u0[3]);
;                 w.z = cvt_pk_bf16(silu_f(g1[0]) * u1[0], silu_f(g1[1]) * u1[1]); w.w = cvt_pk_bf16(silu_f(g1[2]) * u1[2], silu_f(g1[3]) * u1[3]);
;                 __builtin_nontemporal_store(w, (u32x4*)rowp); }
.LBB0_1108:
	s_waitcnt vmcnt(8)
	v_fmamk_f32 v145, v170, 0x3a800000, v225
	v_rsq_f32_e32 v172, v145
	v_lshl_or_b32 v148, s80, 7, v155
	v_ashrrev_i32_e32 v149, 31, v148
	v_mov_b64_e32 v[146:147], s[76:77]
	v_pk_mul_f32 v[130:131], v[172:173], v[130:131] op_sel_hi:[0,1]
	v_pk_mul_f32 v[174:175], v[172:173], v[120:121] op_sel_hi:[0,1]
	v_pk_mul_f32 v[120:121], v[172:173], v[118:119] op_sel_hi:[0,1]
	v_mul_f32_e32 v118, 0xbfb8aa3b, v130
	v_mul_f32_e32 v119, 0xbfb8aa3b, v131
	v_exp_f32_e32 v118, v118
	v_exp_f32_e32 v119, v119
	v_pk_mul_f32 v[122:123], v[172:173], v[122:123] op_sel_hi:[0,1]
	v_pk_mul_f32 v[132:133], v[172:173], v[132:133] op_sel_hi:[0,1]
	v_add_f32_e32 v118, 1.0, v118
	v_add_f32_e32 v119, 1.0, v119
	v_rcp_f32_e32 v118, v118
	v_rcp_f32_e32 v119, v119
	v_pk_mul_f32 v[124:125], v[172:173], v[124:125] op_sel_hi:[0,1]
	v_pk_mul_f32 v[126:127], v[172:173], v[126:127] op_sel_hi:[0,1]
	v_mul_f32_e32 v118, v130, v118
	v_mul_f32_e32 v119, v131, v119
	v_mul_f32_e32 v118, v118, v122
	v_mul_f32_e32 v119, v119, v123
	v_cvt_pk_bf16_f32 v118, v118, v119
	v_mul_f32_e32 v119, 0xbfb8aa3b, v132
	v_mul_f32_e32 v122, 0xbfb8aa3b, v133
	v_exp_f32_e32 v119, v119
	v_exp_f32_e32 v122, v122
	v_pk_mul_f32 v[128:129], v[172:173], v[128:129] op_sel_hi:[0,1]
	v_mad_i64_i32 v[150:151], s[4:5], v144, s86, v[146:147]
	v_add_f32_e32 v119, 1.0, v119
	v_add_f32_e32 v122, 1.0, v122
	v_rcp_f32_e32 v119, v119
	v_rcp_f32_e32 v122, v122
	v_lshlrev_b64 v[148:149], 1, v[148:149]
	v_lshl_add_u64 v[150:151], v[150:151], 0, v[148:149]
	v_mul_f32_e32 v119, v132, v119
	v_mul_f32_e32 v122, v133, v122
	v_mul_f32_e32 v119, v119, v124
	v_mul_f32_e32 v122, v122, v125
	v_cvt_pk_bf16_f32 v119, v119, v122
	v_mul_f32_e32 v122, 0xbfb8aa3b, v126
	v_exp_f32_e32 v122, v122
	s_andn2_b64 vcc, exec, s[6:7]
	v_add_f32_e32 v122, 1.0, v122
	v_rcp_f32_e32 v122, v122
	s_nop 0
	v_mul_f32_e32 v122, v126, v122
	v_mul_f32_e32 v120, v122, v120
	v_mul_f32_e32 v122, 0xbfb8aa3b, v127
	v_exp_f32_e32 v122, v122
	s_nop 0
	v_add_f32_e32 v122, 1.0, v122
	v_rcp_f32_e32 v122, v122
	s_nop 0
	v_mul_f32_e32 v122, v127, v122
	v_mul_f32_e32 v121, v122, v121
	v_cvt_pk_bf16_f32 v120, v120, v121
	v_mul_f32_e32 v121, 0xbfb8aa3b, v128
	v_exp_f32_e32 v121, v121
	v_mul_f32_e32 v122, 0xbfb8aa3b, v129
	v_exp_f32_e32 v122, v122
	v_add_f32_e32 v121, 1.0, v121
	v_rcp_f32_e32 v121, v121
	v_add_f32_e32 v122, 1.0, v122
	v_rcp_f32_e32 v122, v122
	v_mul_f32_e32 v121, v128, v121
	v_mul_f32_e32 v121, v121, v174
	v_mul_f32_e32 v122, v129, v122
	v_mul_f32_e32 v122, v122, v175
	v_cvt_pk_bf16_f32 v121, v121, v122
	global_store_dwordx4 v[150:151], v[118:121], off nt
	s_nop 1
	v_fmamk_f32 v120, v169, 0x3a800000, v225
	v_rsq_f32_e32 v120, v120
	v_or_b32_e32 v118, 16, v144
	v_mad_i64_i32 v[118:119], s[4:5], v118, s86, v[146:147]
	v_pk_mul_f32 v[114:115], v[120:121], v[114:115] op_sel_hi:[0,1]
	v_pk_mul_f32 v[122:123], v[120:121], v[104:105] op_sel_hi:[0,1]
	v_pk_mul_f32 v[104:105], v[120:121], v[102:103] op_sel_hi:[0,1]
	v_mul_f32_e32 v102, 0xbfb8aa3b, v114
	v_mul_f32_e32 v103, 0xbfb8aa3b, v115
	v_exp_f32_e32 v102, v102
	v_exp_f32_e32 v103, v103
	v_pk_mul_f32 v[106:107], v[120:121], v[106:107] op_sel_hi:[0,1]
	v_pk_mul_f32 v[116:117], v[120:121], v[116:117] op_sel_hi:[0,1]
	v_add_f32_e32 v102, 1.0, v102
	v_add_f32_e32 v103, 1.0, v103
	v_rcp_f32_e32 v102, v102
	v_rcp_f32_e32 v103, v103
	v_pk_mul_f32 v[108:109], v[120:121], v[108:109] op_sel_hi:[0,1]
	v_pk_mul_f32 v[110:111], v[120:121], v[110:111] op_sel_hi:[0,1]
	v_mul_f32_e32 v102, v114, v102
	v_mul_f32_e32 v103, v115, v103
	v_mul_f32_e32 v102, v102, v106
	v_mul_f32_e32 v103, v103, v107
	v_cvt_pk_bf16_f32 v102, v102, v103
	v_mul_f32_e32 v103, 0xbfb8aa3b, v116
	v_mul_f32_e32 v106, 0xbfb8aa3b, v117
	v_exp_f32_e32 v103, v103
	v_exp_f32_e32 v106, v106
	v_pk_mul_f32 v[112:113], v[120:121], v[112:113] op_sel_hi:[0,1]
	v_lshl_add_u64 v[118:119], v[118:119], 0, v[148:149]
	v_add_f32_e32 v103, 1.0, v103
	v_add_f32_e32 v106, 1.0, v106
	v_rcp_f32_e32 v103, v103
	v_rcp_f32_e32 v106, v106
	v_mul_f32_e32 v103, v116, v103
	v_mul_f32_e32 v106, v117, v106
	v_mul_f32_e32 v103, v103, v108
	v_mul_f32_e32 v106, v106, v109
	v_cvt_pk_bf16_f32 v103, v103, v106
	v_mul_f32_e32 v106, 0xbfb8aa3b, v110
	v_exp_f32_e32 v106, v106
	s_nop 0
	v_add_f32_e32 v106, 1.0, v106
	v_rcp_f32_e32 v106, v106
	s_nop 0
	v_mul_f32_e32 v106, v110, v106
	v_mul_f32_e32 v104, v106, v104
	v_mul_f32_e32 v106, 0xbfb8aa3b, v111
	v_exp_f32_e32 v106, v106
	s_nop 0
	v_add_f32_e32 v106, 1.0, v106
	v_rcp_f32_e32 v106, v106
	s_nop 0
	v_mul_f32_e32 v106, v111, v106
	v_mul_f32_e32 v105, v106, v105
	v_cvt_pk_bf16_f32 v104, v104, v105
	v_mul_f32_e32 v105, 0xbfb8aa3b, v112
	v_exp_f32_e32 v105, v105
	v_mul_f32_e32 v106, 0xbfb8aa3b, v113
	v_exp_f32_e32 v106, v106
	v_add_f32_e32 v105, 1.0, v105
	v_rcp_f32_e32 v105, v105
	v_add_f32_e32 v106, 1.0, v106
	v_rcp_f32_e32 v106, v106
	v_mul_f32_e32 v105, v112, v105
	v_mul_f32_e32 v105, v105, v122
	v_mul_f32_e32 v106, v113, v106
	v_mul_f32_e32 v106, v106, v123
	v_cvt_pk_bf16_f32 v105, v105, v106
	global_store_dwordx4 v[118:119], v[102:105], off nt
	s_nop 1
	v_fmamk_f32 v104, v168, 0x3a800000, v225
	v_rsq_f32_e32 v104, v104
	v_or_b32_e32 v102, 32, v144
	v_mad_i64_i32 v[102:103], s[4:5], v102, s86, v[146:147]
	v_pk_mul_f32 v[98:99], v[104:105], v[98:99] op_sel_hi:[0,1]
	v_pk_mul_f32 v[106:107], v[104:105], v[88:89] op_sel_hi:[0,1]
	v_pk_mul_f32 v[88:89], v[104:105], v[86:87] op_sel_hi:[0,1]
	v_mul_f32_e32 v86, 0xbfb8aa3b, v98
	v_mul_f32_e32 v87, 0xbfb8aa3b, v99
	v_exp_f32_e32 v86, v86
	v_exp_f32_e32 v87, v87
	v_pk_mul_f32 v[90:91], v[104:105], v[90:91] op_sel_hi:[0,1]
	v_pk_mul_f32 v[100:101], v[104:105], v[100:101] op_sel_hi:[0,1]
; __device__ __forceinline__ unsigned cvt_pk_bf16(float lo, float hi) { unsigned r; asm volatile("v_cvt_pk_bf16_f32 %0, %1, %2" : "=v"(r) : "v"(lo), "v"(hi)); return r; }
; __device__ __forceinline__ float silu_f(float g) { return g * __builtin_amdgcn_rcpf(1.0f + __expf(-g)); }
;     __device__ __forceinline__ void operator()(const f32x4 (&acc)[2][2][4][2], const Unit& u, int wr, int wc, int fr, int fq, const float (&rsv)[8]) const {
;         const int row0 = u.pm * BM + wr * 64 + fr; const int col0 = u.pn * HALF + wc * 32 + 8 * fq;
; #pragma unroll
;         for (int ai = 0; ai < 2; ++ai)
; #pragma unroll
;             for (int m = 0; m < 4; ++m) { bf16_t* rowp = O + (size_t)(row0 + ai * HALF + m * 16) * ldc + col0;
;                 const float rs = __builtin_amdgcn_rsqf(rsv[ai * 4 + m] * (1.0f / 1024.0f) + 1e-6f);
;                 const f32x4 g0 = acc[ai][0][m][0] * rs, g1 = acc[ai][0][m][1] * rs, u0 = acc[ai][1][m][0] * rs, u1 = acc[ai][1][m][1] * rs; u32x4 w;
;                 w.x = cvt_pk_bf16(silu_f(g0[0]) * u0[0], silu_f(g0[1]) * u0[1]); w.y = cvt_pk_bf16(silu_f(g0[2]) * u0[2], silu_f(g0[3]) * u0[3]);
;                 w.z = cvt_pk_bf16(silu_f(g1[0]) * u1[0], silu_f(g1[1]) * u1[1]); w.w = cvt_pk_bf16(silu_f(g1[2]) * u1[2], silu_f(g1[3]) * u1[3]);
;                 __builtin_nontemporal_store(w, (u32x4*)rowp); }
	v_add_f32_e32 v86, 1.0, v86
	v_add_f32_e32 v87, 1.0, v87
	v_rcp_f32_e32 v86, v86
	v_rcp_f32_e32 v87, v87
	v_pk_mul_f32 v[92:93], v[104:105], v[92:93] op_sel_hi:[0,1]
	v_pk_mul_f32 v[94:95], v[104:105], v[94:95] op_sel_hi:[0,1]
	v_mul_f32_e32 v86, v98, v86
	v_mul_f32_e32 v87, v99, v87
	v_mul_f32_e32 v86, v86, v90
	v_mul_f32_e32 v87, v87, v91
	v_cvt_pk_bf16_f32 v86, v86, v87
	v_mul_f32_e32 v87, 0xbfb8aa3b, v100
	v_mul_f32_e32 v90, 0xbfb8aa3b, v101
	v_exp_f32_e32 v87, v87
	v_exp_f32_e32 v90, v90
	v_pk_mul_f32 v[96:97], v[104:105], v[96:97] op_sel_hi:[0,1]
	v_lshl_add_u64 v[102:103], v[102:103], 0, v[148:149]
	v_add_f32_e32 v87, 1.0, v87
	v_add_f32_e32 v90, 1.0, v90
	v_rcp_f32_e32 v87, v87
	v_rcp_f32_e32 v90, v90
	v_mul_f32_e32 v87, v100, v87
	v_mul_f32_e32 v90, v101, v90
	v_mul_f32_e32 v87, v87, v92
	v_mul_f32_e32 v90, v90, v93
	v_cvt_pk_bf16_f32 v87, v87, v90
	v_mul_f32_e32 v90, 0xbfb8aa3b, v94
	v_exp_f32_e32 v90, v90
	s_nop 0
	v_add_f32_e32 v90, 1.0, v90
	v_rcp_f32_e32 v90, v90
	s_nop 0
	v_mul_f32_e32 v90, v94, v90
	v_mul_f32_e32 v88, v90, v88
	v_mul_f32_e32 v90, 0xbfb8aa3b, v95
	v_exp_f32_e32 v90, v90
	s_nop 0
	v_add_f32_e32 v90, 1.0, v90
	v_rcp_f32_e32 v90, v90
	s_nop 0
	v_mul_f32_e32 v90, v95, v90
	v_mul_f32_e32 v89, v90, v89
	v_cvt_pk_bf16_f32 v88, v88, v89
	v_mul_f32_e32 v89, 0xbfb8aa3b, v96
	v_exp_f32_e32 v89, v89
	v_mul_f32_e32 v90, 0xbfb8aa3b, v97
	v_exp_f32_e32 v90, v90
	v_add_f32_e32 v89, 1.0, v89
	v_rcp_f32_e32 v89, v89
	v_add_f32_e32 v90, 1.0, v90
	v_rcp_f32_e32 v90, v90
	v_mul_f32_e32 v89, v96, v89
	v_mul_f32_e32 v89, v89, v106
	v_mul_f32_e32 v90, v97, v90
	v_mul_f32_e32 v90, v90, v107
	v_cvt_pk_bf16_f32 v89, v89, v90
	global_store_dwordx4 v[102:103], v[86:89], off nt
	s_nop 1
	v_fmamk_f32 v88, v167, 0x3a800000, v225
	v_rsq_f32_e32 v88, v88
	v_or_b32_e32 v86, 48, v144
	v_mad_i64_i32 v[86:87], s[4:5], v86, s86, v[146:147]
	v_pk_mul_f32 v[82:83], v[88:89], v[82:83] op_sel_hi:[0,1]
	v_pk_mul_f32 v[90:91], v[88:89], v[72:73] op_sel_hi:[0,1]
	v_pk_mul_f32 v[72:73], v[88:89], v[70:71] op_sel_hi:[0,1]
	v_mul_f32_e32 v70, 0xbfb8aa3b, v82
	v_mul_f32_e32 v71, 0xbfb8aa3b, v83
	v_exp_f32_e32 v70, v70
	v_exp_f32_e32 v71, v71
	v_pk_mul_f32 v[74:75], v[88:89], v[74:75] op_sel_hi:[0,1]
	v_pk_mul_f32 v[84:85], v[88:89], v[84:85] op_sel_hi:[0,1]
	v_add_f32_e32 v70, 1.0, v70
	v_add_f32_e32 v71, 1.0, v71
	v_rcp_f32_e32 v70, v70
	v_rcp_f32_e32 v71, v71
	v_pk_mul_f32 v[76:77], v[88:89], v[76:77] op_sel_hi:[0,1]
	v_pk_mul_f32 v[78:79], v[88:89], v[78:79] op_sel_hi:[0,1]
	v_mul_f32_e32 v70, v82, v70
	v_mul_f32_e32 v71, v83, v71
	v_mul_f32_e32 v70, v70, v74
	v_mul_f32_e32 v71, v71, v75
	v_cvt_pk_bf16_f32 v70, v70, v71
	v_mul_f32_e32 v71, 0xbfb8aa3b, v84
	v_mul_f32_e32 v74, 0xbfb8aa3b, v85
	v_exp_f32_e32 v71, v71
	v_exp_f32_e32 v74, v74
	v_pk_mul_f32 v[80:81], v[88:89], v[80:81] op_sel_hi:[0,1]
	v_lshl_add_u64 v[86:87], v[86:87], 0, v[148:149]
	v_add_f32_e32 v71, 1.0, v71
	v_add_f32_e32 v74, 1.0, v74
	v_rcp_f32_e32 v71, v71
	v_rcp_f32_e32 v74, v74
	v_mul_f32_e32 v71, v84, v71
	v_mul_f32_e32 v74, v85, v74
	v_mul_f32_e32 v71, v71, v76
	v_mul_f32_e32 v74, v74, v77
	v_cvt_pk_bf16_f32 v71, v71, v74
	v_mul_f32_e32 v74, 0xbfb8aa3b, v78
	v_exp_f32_e32 v74, v74
	s_nop 0
	v_add_f32_e32 v74, 1.0, v74
	v_rcp_f32_e32 v74, v74
	s_nop 0
	v_mul_f32_e32 v74, v78, v74
	v_mul_f32_e32 v72, v74, v72
	v_mul_f32_e32 v74, 0xbfb8aa3b, v79
	v_exp_f32_e32 v74, v74
	s_nop 0
	v_add_f32_e32 v74, 1.0, v74
	v_rcp_f32_e32 v74, v74
	s_nop 0
	v_mul_f32_e32 v74, v79, v74
	v_mul_f32_e32 v73, v74, v73
	v_cvt_pk_bf16_f32 v72, v72, v73
	v_mul_f32_e32 v73, 0xbfb8aa3b, v80
	v_exp_f32_e32 v73, v73
	v_mul_f32_e32 v74, 0xbfb8aa3b, v81
	v_exp_f32_e32 v74, v74
	v_add_f32_e32 v73, 1.0, v73
	v_rcp_f32_e32 v73, v73
	v_add_f32_e32 v74, 1.0, v74
	v_rcp_f32_e32 v74, v74
	v_mul_f32_e32 v73, v80, v73
	v_mul_f32_e32 v73, v73, v90
	v_mul_f32_e32 v74, v81, v74
	v_mul_f32_e32 v74, v74, v91
	v_cvt_pk_bf16_f32 v73, v73, v74
	global_store_dwordx4 v[86:87], v[70:73], off nt
	s_nop 1
	v_fmamk_f32 v72, v166, 0x3a800000, v225
	v_rsq_f32_e32 v72, v72
	v_add_u32_e32 v70, 0x80, v144
	v_mad_i64_i32 v[70:71], s[4:5], v70, s86, v[146:147]
	v_pk_mul_f32 v[66:67], v[72:73], v[66:67] op_sel_hi:[0,1]
	v_pk_mul_f32 v[74:75], v[72:73], v[56:57] op_sel_hi:[0,1]
	v_pk_mul_f32 v[56:57], v[72:73], v[54:55] op_sel_hi:[0,1]
	v_mul_f32_e32 v54, 0xbfb8aa3b, v66
	v_mul_f32_e32 v55, 0xbfb8aa3b, v67
	v_exp_f32_e32 v54, v54
	v_exp_f32_e32 v55, v55
	v_pk_mul_f32 v[58:59], v[72:73], v[58:59] op_sel_hi:[0,1]
	v_pk_mul_f32 v[68:69], v[72:73], v[68:69] op_sel_hi:[0,1]
	v_add_f32_e32 v54, 1.0, v54
	v_add_f32_e32 v55, 1.0, v55
	v_rcp_f32_e32 v54, v54
	v_rcp_f32_e32 v55, v55
	v_pk_mul_f32 v[60:61], v[72:73], v[60:61] op_sel_hi:[0,1]
	v_pk_mul_f32 v[62:63], v[72:73], v[62:63] op_sel_hi:[0,1]
	v_mul_f32_e32 v54, v66, v54
	v_mul_f32_e32 v55, v67, v55
	v_mul_f32_e32 v54, v54, v58
	v_mul_f32_e32 v55, v55, v59
	v_cvt_pk_bf16_f32 v54, v54, v55
	v_mul_f32_e32 v55, 0xbfb8aa3b, v68
	v_mul_f32_e32 v58, 0xbfb8aa3b, v69
	v_exp_f32_e32 v55, v55
	v_exp_f32_e32 v58, v58
	v_pk_mul_f32 v[64:65], v[72:73], v[64:65] op_sel_hi:[0,1]
	v_lshl_add_u64 v[70:71], v[70:71], 0, v[148:149]
	v_add_f32_e32 v55, 1.0, v55
	v_add_f32_e32 v58, 1.0, v58
	v_rcp_f32_e32 v55, v55
	v_rcp_f32_e32 v58, v58
	v_mul_f32_e32 v55, v68, v55
	v_mul_f32_e32 v58, v69, v58
	v_mul_f32_e32 v55, v55, v60
	v_mul_f32_e32 v58, v58, v61
	v_cvt_pk_bf16_f32 v55, v55, v58
	v_mul_f32_e32 v58, 0xbfb8aa3b, v62
	v_exp_f32_e32 v58, v58
	s_nop 0
	v_add_f32_e32 v58, 1.0, v58
	v_rcp_f32_e32 v58, v58
	s_nop 0
	v_mul_f32_e32 v58, v62, v58
	v_mul_f32_e32 v56, v58, v56
	v_mul_f32_e32 v58, 0xbfb8aa3b, v63
; __device__ __forceinline__ unsigned cvt_pk_bf16(float lo, float hi) { unsigned r; asm volatile("v_cvt_pk_bf16_f32 %0, %1, %2" : "=v"(r) : "v"(lo), "v"(hi)); return r; }
; __device__ __forceinline__ float silu_f(float g) { return g * __builtin_amdgcn_rcpf(1.0f + __expf(-g)); }
;     __device__ __forceinline__ void operator()(const f32x4 (&acc)[2][2][4][2], const Unit& u, int wr, int wc, int fr, int fq, const float (&rsv)[8]) const {
;         const int row0 = u.pm * BM + wr * 64 + fr; const int col0 = u.pn * HALF + wc * 32 + 8 * fq;
; #pragma unroll
;         for (int ai = 0; ai < 2; ++ai)
; #pragma unroll
;             for (int m = 0; m < 4; ++m) { bf16_t* rowp = O + (size_t)(row0 + ai * HALF + m * 16) * ldc + col0;
;                 const float rs = __builtin_amdgcn_rsqf(rsv[ai * 4 + m] * (1.0f / 1024.0f) + 1e-6f);
;                 const f32x4 g0 = acc[ai][0][m][0] * rs, g1 = acc[ai][0][m][1] * rs, u0 = acc[ai][1][m][0] * rs, u1 = acc[ai][1][m][1] * rs; u32x4 w;
;                 w.x = cvt_pk_bf16(silu_f(g0[0]) * u0[0], silu_f(g0[1]) * u0[1]); w.y = cvt_pk_bf16(silu_f(g0[2]) * u0[2], silu_f(g0[3]) * u0[3]);
;                 w.z = cvt_pk_bf16(silu_f(g1[0]) * u1[0], silu_f(g1[1]) * u1[1]); w.w = cvt_pk_bf16(silu_f(g1[2]) * u1[2], silu_f(g1[3]) * u1[3]);
;                 __builtin_nontemporal_store(w, (u32x4*)rowp); }
	v_exp_f32_e32 v58, v58
	s_nop 0
	v_add_f32_e32 v58, 1.0, v58
	v_rcp_f32_e32 v58, v58
	s_nop 0
	v_mul_f32_e32 v58, v63, v58
	v_mul_f32_e32 v57, v58, v57
	v_cvt_pk_bf16_f32 v56, v56, v57
	v_mul_f32_e32 v57, 0xbfb8aa3b, v64
	v_exp_f32_e32 v57, v57
	v_mul_f32_e32 v58, 0xbfb8aa3b, v65
	v_exp_f32_e32 v58, v58
	v_add_f32_e32 v57, 1.0, v57
	v_rcp_f32_e32 v57, v57
	v_add_f32_e32 v58, 1.0, v58
	v_rcp_f32_e32 v58, v58
	v_mul_f32_e32 v57, v64, v57
	v_mul_f32_e32 v57, v57, v74
	v_mul_f32_e32 v58, v65, v58
	v_mul_f32_e32 v58, v58, v75
	v_cvt_pk_bf16_f32 v57, v57, v58
	global_store_dwordx4 v[70:71], v[54:57], off nt
	s_nop 1
	v_fmamk_f32 v56, v165, 0x3a800000, v225
	v_rsq_f32_e32 v56, v56
	v_add_u32_e32 v54, 0x90, v144
	v_mad_i64_i32 v[54:55], s[4:5], v54, s86, v[146:147]
	v_pk_mul_f32 v[50:51], v[56:57], v[50:51] op_sel_hi:[0,1]
	v_pk_mul_f32 v[58:59], v[56:57], v[40:41] op_sel_hi:[0,1]
	v_pk_mul_f32 v[40:41], v[56:57], v[38:39] op_sel_hi:[0,1]
	v_mul_f32_e32 v38, 0xbfb8aa3b, v50
	v_mul_f32_e32 v39, 0xbfb8aa3b, v51
	v_exp_f32_e32 v38, v38
	v_exp_f32_e32 v39, v39
	v_pk_mul_f32 v[42:43], v[56:57], v[42:43] op_sel_hi:[0,1]
	v_pk_mul_f32 v[52:53], v[56:57], v[52:53] op_sel_hi:[0,1]
	v_add_f32_e32 v38, 1.0, v38
	v_add_f32_e32 v39, 1.0, v39
	v_rcp_f32_e32 v38, v38
	v_rcp_f32_e32 v39, v39
	v_pk_mul_f32 v[44:45], v[56:57], v[44:45] op_sel_hi:[0,1]
	v_pk_mul_f32 v[46:47], v[56:57], v[46:47] op_sel_hi:[0,1]
	v_mul_f32_e32 v38, v50, v38
	v_mul_f32_e32 v39, v51, v39
	v_mul_f32_e32 v38, v38, v42
	v_mul_f32_e32 v39, v39, v43
	v_cvt_pk_bf16_f32 v38, v38, v39
	v_mul_f32_e32 v39, 0xbfb8aa3b, v52
	v_mul_f32_e32 v42, 0xbfb8aa3b, v53
	v_exp_f32_e32 v39, v39
	v_exp_f32_e32 v42, v42
	v_pk_mul_f32 v[48:49], v[56:57], v[48:49] op_sel_hi:[0,1]
	v_lshl_add_u64 v[54:55], v[54:55], 0, v[148:149]
	v_add_f32_e32 v39, 1.0, v39
	v_add_f32_e32 v42, 1.0, v42
	v_rcp_f32_e32 v39, v39
	v_rcp_f32_e32 v42, v42
	v_mul_f32_e32 v39, v52, v39
	v_mul_f32_e32 v42, v53, v42
	v_mul_f32_e32 v39, v39, v44
	v_mul_f32_e32 v42, v42, v45
	v_cvt_pk_bf16_f32 v39, v39, v42
	v_mul_f32_e32 v42, 0xbfb8aa3b, v46
	v_exp_f32_e32 v42, v42
	s_nop 0
	v_add_f32_e32 v42, 1.0, v42
	v_rcp_f32_e32 v42, v42
	s_nop 0
	v_mul_f32_e32 v42, v46, v42
	v_mul_f32_e32 v40, v42, v40
	v_mul_f32_e32 v42, 0xbfb8aa3b, v47
	v_exp_f32_e32 v42, v42
	s_nop 0
	v_add_f32_e32 v42, 1.0, v42
	v_rcp_f32_e32 v42, v42
	s_nop 0
	v_mul_f32_e32 v42, v47, v42
	v_mul_f32_e32 v41, v42, v41
	v_cvt_pk_bf16_f32 v40, v40, v41
	v_mul_f32_e32 v41, 0xbfb8aa3b, v48
	v_exp_f32_e32 v41, v41
	v_mul_f32_e32 v42, 0xbfb8aa3b, v49
	v_exp_f32_e32 v42, v42
	v_add_f32_e32 v41, 1.0, v41
	v_rcp_f32_e32 v41, v41
	v_add_f32_e32 v42, 1.0, v42
	v_rcp_f32_e32 v42, v42
	v_mul_f32_e32 v41, v48, v41
	v_mul_f32_e32 v41, v41, v58
	v_mul_f32_e32 v42, v49, v42
	v_mul_f32_e32 v42, v42, v59
	v_cvt_pk_bf16_f32 v41, v41, v42
	global_store_dwordx4 v[54:55], v[38:41], off nt
	s_nop 1
	v_fmamk_f32 v40, v164, 0x3a800000, v225
	v_rsq_f32_e32 v40, v40
	v_add_u32_e32 v38, 0xa0, v144
	v_mad_i64_i32 v[38:39], s[4:5], v38, s86, v[146:147]
	v_pk_mul_f32 v[34:35], v[40:41], v[34:35] op_sel_hi:[0,1]
	v_pk_mul_f32 v[42:43], v[40:41], v[24:25] op_sel_hi:[0,1]
	v_pk_mul_f32 v[24:25], v[40:41], v[22:23] op_sel_hi:[0,1]
	v_mul_f32_e32 v22, 0xbfb8aa3b, v34
	v_mul_f32_e32 v23, 0xbfb8aa3b, v35
	v_exp_f32_e32 v22, v22
	v_exp_f32_e32 v23, v23
	v_pk_mul_f32 v[26:27], v[40:41], v[26:27] op_sel_hi:[0,1]
	v_pk_mul_f32 v[36:37], v[40:41], v[36:37] op_sel_hi:[0,1]
	v_add_f32_e32 v22, 1.0, v22
	v_add_f32_e32 v23, 1.0, v23
	v_rcp_f32_e32 v22, v22
	v_rcp_f32_e32 v23, v23
	v_pk_mul_f32 v[28:29], v[40:41], v[28:29] op_sel_hi:[0,1]
	v_pk_mul_f32 v[30:31], v[40:41], v[30:31] op_sel_hi:[0,1]
	v_mul_f32_e32 v22, v34, v22
	v_mul_f32_e32 v23, v35, v23
; __device__ __forceinline__ unsigned cvt_pk_bf16(float lo, float hi) { unsigned r; asm volatile("v_cvt_pk_bf16_f32 %0, %1, %2" : "=v"(r) : "v"(lo), "v"(hi)); return r; }
; __device__ __forceinline__ float silu_f(float g) { return g * __builtin_amdgcn_rcpf(1.0f + __expf(-g)); }
; #define PG8_BAR __builtin_amdgcn_s_barrier()
;     __device__ __forceinline__ void operator()(const f32x4 (&acc)[2][2][4][2], const Unit& u, int wr, int wc, int fr, int fq, const float (&rsv)[8]) const {
;     ...
;             for (int m = 0; m < 4; ++m) { bf16_t* rowp = O + (size_t)(row0 + ai * HALF + m * 16) * ldc + col0;
;                 const float rs = __builtin_amdgcn_rsqf(rsv[ai * 4 + m] * (1.0f / 1024.0f) + 1e-6f);
;                 const f32x4 g0 = acc[ai][0][m][0] * rs, g1 = acc[ai][0][m][1] * rs, u0 = acc[ai][1][m][0] * rs, u1 = acc[ai][1][m][1] * rs; u32x4 w;
;                 w.x = cvt_pk_bf16(silu_f(g0[0]) * u0[0], silu_f(g0[1]) * u0[1]); w.y = cvt_pk_bf16(silu_f(g0[2]) * u0[2], silu_f(g0[3]) * u0[3]);
;                 w.z = cvt_pk_bf16(silu_f(g1[0]) * u1[0], silu_f(g1[1]) * u1[1]); w.w = cvt_pk_bf16(silu_f(g1[2]) * u1[2], silu_f(g1[3]) * u1[3]);
;                 __builtin_nontemporal_store(w, (u32x4*)rowp); }
; template <class Epi, class Sched, bool ALIGN_EPI = false, bool SP2 = false>
; __device__ __forceinline__ void gemm_phase(PG8_LAS unsigned char* lds, const Gemm g, const Sched& S, const Epi& E) {
;     ...
;         if constexpr (ALIGN_EPI) { if (wr == 0) PG8_BAR; }
;         if constexpr (!Epi::AFTER_DRAIN) { E(acc, cur, wr, wc, fr, fq, rsv); S.done(cur); }
;         if (!has_next) break;
; #pragma unroll
;         for (int a = 0; a < 2; ++a)
; #pragma unroll
;             for (int b = 0; b < 2; ++b)
; #pragma unroll
;                 for (int m = 0; m < 4; ++m)
; #pragma unroll
;                     for (int n = 0; n < 2; ++n) acc[a][b][m][n] = (f32x4){0.f, 0.f, 0.f, 0.f};
;         cur = nxt; cA = nA; cB = nB; ++ui;
;         if constexpr (ALIGN_EPI) { if (wr == 1) PG8_BAR; }
;     }
	v_mul_f32_e32 v22, v22, v26
	v_mul_f32_e32 v23, v23, v27
	v_cvt_pk_bf16_f32 v22, v22, v23
	v_mul_f32_e32 v23, 0xbfb8aa3b, v36
	v_mul_f32_e32 v26, 0xbfb8aa3b, v37
	v_exp_f32_e32 v23, v23
	v_exp_f32_e32 v26, v26
	v_pk_mul_f32 v[32:33], v[40:41], v[32:33] op_sel_hi:[0,1]
	v_lshl_add_u64 v[38:39], v[38:39], 0, v[148:149]
	v_add_f32_e32 v23, 1.0, v23
	v_add_f32_e32 v26, 1.0, v26
	v_rcp_f32_e32 v23, v23
	v_rcp_f32_e32 v26, v26
	v_mul_f32_e32 v23, v36, v23
	v_mul_f32_e32 v26, v37, v26
	v_mul_f32_e32 v23, v23, v28
	v_mul_f32_e32 v26, v26, v29
	v_cvt_pk_bf16_f32 v23, v23, v26
	v_mul_f32_e32 v26, 0xbfb8aa3b, v30
	v_exp_f32_e32 v26, v26
	s_nop 0
	v_add_f32_e32 v26, 1.0, v26
	v_rcp_f32_e32 v26, v26
	s_nop 0
	v_mul_f32_e32 v26, v30, v26
	v_mul_f32_e32 v24, v26, v24
	v_mul_f32_e32 v26, 0xbfb8aa3b, v31
	v_exp_f32_e32 v26, v26
	s_nop 0
	v_add_f32_e32 v26, 1.0, v26
	v_rcp_f32_e32 v26, v26
	s_nop 0
	v_mul_f32_e32 v26, v31, v26
	v_mul_f32_e32 v25, v26, v25
	v_cvt_pk_bf16_f32 v24, v24, v25
	v_mul_f32_e32 v25, 0xbfb8aa3b, v32
	v_exp_f32_e32 v25, v25
	v_mul_f32_e32 v26, 0xbfb8aa3b, v33
	v_exp_f32_e32 v26, v26
	v_add_f32_e32 v25, 1.0, v25
	v_rcp_f32_e32 v25, v25
	v_add_f32_e32 v26, 1.0, v26
	v_rcp_f32_e32 v26, v26
	v_mul_f32_e32 v25, v32, v25
	v_mul_f32_e32 v25, v25, v42
	v_mul_f32_e32 v26, v33, v26
	v_mul_f32_e32 v26, v26, v43
	v_cvt_pk_bf16_f32 v25, v25, v26
	global_store_dwordx4 v[38:39], v[22:25], off nt
	s_nop 1
	v_fmamk_f32 v24, v163, 0x3a800000, v225
	v_rsq_f32_e32 v24, v24
	v_add_u32_e32 v22, 0xb0, v144
	v_mad_i64_i32 v[22:23], s[4:5], v22, s86, v[146:147]
	v_pk_mul_f32 v[18:19], v[24:25], v[18:19] op_sel_hi:[0,1]
	v_pk_mul_f32 v[26:27], v[24:25], v[8:9] op_sel_hi:[0,1]
	v_pk_mul_f32 v[8:9], v[24:25], v[6:7] op_sel_hi:[0,1]
	v_mul_f32_e32 v6, 0xbfb8aa3b, v18
	v_mul_f32_e32 v7, 0xbfb8aa3b, v19
	v_exp_f32_e32 v6, v6
	v_exp_f32_e32 v7, v7
	v_pk_mul_f32 v[10:11], v[24:25], v[10:11] op_sel_hi:[0,1]
	v_pk_mul_f32 v[20:21], v[24:25], v[20:21] op_sel_hi:[0,1]
	v_add_f32_e32 v6, 1.0, v6
	v_add_f32_e32 v7, 1.0, v7
	v_rcp_f32_e32 v6, v6
	v_rcp_f32_e32 v7, v7
	v_pk_mul_f32 v[12:13], v[24:25], v[12:13] op_sel_hi:[0,1]
	v_pk_mul_f32 v[14:15], v[24:25], v[14:15] op_sel_hi:[0,1]
	v_mul_f32_e32 v6, v18, v6
	v_mul_f32_e32 v7, v19, v7
	v_mul_f32_e32 v6, v6, v10
	v_mul_f32_e32 v7, v7, v11
	v_cvt_pk_bf16_f32 v6, v6, v7
	v_mul_f32_e32 v7, 0xbfb8aa3b, v20
	v_mul_f32_e32 v10, 0xbfb8aa3b, v21
	v_exp_f32_e32 v7, v7
	v_exp_f32_e32 v10, v10
	v_pk_mul_f32 v[16:17], v[24:25], v[16:17] op_sel_hi:[0,1]
	v_lshl_add_u64 v[22:23], v[22:23], 0, v[148:149]
	v_add_f32_e32 v7, 1.0, v7
	v_add_f32_e32 v10, 1.0, v10
	v_rcp_f32_e32 v7, v7
	v_rcp_f32_e32 v10, v10
	s_mov_b64 s[4:5], -1
	v_mul_f32_e32 v7, v20, v7
	v_mul_f32_e32 v10, v21, v10
	v_mul_f32_e32 v7, v7, v12
	v_mul_f32_e32 v10, v10, v13
	v_cvt_pk_bf16_f32 v7, v7, v10
	v_mul_f32_e32 v10, 0xbfb8aa3b, v14
	v_exp_f32_e32 v10, v10
	s_nop 0
	v_add_f32_e32 v10, 1.0, v10
	v_rcp_f32_e32 v10, v10
	s_nop 0
	v_mul_f32_e32 v10, v14, v10
	v_mul_f32_e32 v8, v10, v8
	v_mul_f32_e32 v10, 0xbfb8aa3b, v15
	v_exp_f32_e32 v10, v10
	s_nop 0
	v_add_f32_e32 v10, 1.0, v10
	v_rcp_f32_e32 v10, v10
	s_nop 0
	v_mul_f32_e32 v10, v15, v10
	v_mul_f32_e32 v9, v10, v9
	v_cvt_pk_bf16_f32 v8, v8, v9
	v_mul_f32_e32 v9, 0xbfb8aa3b, v16
	v_exp_f32_e32 v9, v9
	v_mul_f32_e32 v10, 0xbfb8aa3b, v17
	v_exp_f32_e32 v10, v10
	v_add_f32_e32 v9, 1.0, v9
	v_rcp_f32_e32 v9, v9
	v_add_f32_e32 v10, 1.0, v10
	v_rcp_f32_e32 v10, v10
	v_mul_f32_e32 v9, v16, v9
	v_mul_f32_e32 v9, v9, v26
	v_mul_f32_e32 v10, v17, v10
	v_mul_f32_e32 v10, v10, v27
	v_cvt_pk_bf16_f32 v9, v9, v10
	global_store_dwordx4 v[22:23], v[6:9], off nt
	s_cbranch_vccnz .LBB0_1099
	s_andn2_b64 vcc, exec, s[0:1]
	s_cbranch_vccnz .LBB0_1098
	s_barrier
	s_branch .LBB0_1098

; __device__ __forceinline__ unsigned pk2(float lo, float hi) { return pg8::cvt_pk_bf16(lo, hi); }
; __device__ __forceinline__ void rms_row(const float* xrow, const float* w, bf16_t* orow, float* of, int lane) {
;     const f32x4* xr = (const f32x4*)xrow + lane; const f32x4* wr = (const f32x4*)w + lane;
;     f32x4 v[4]; float s = 0.f;
; #pragma unroll
;     for (int j = 0; j < 4; ++j) { v[j] = __builtin_nontemporal_load(xr + 64 * j); s += (v[j].x * v[j].x + v[j].y * v[j].y) + (v[j].z * v[j].z + v[j].w * v[j].w); }
;     const float rstd = 1.0f / sqrtf(wave_sum(s) * (1.f / D) + 1e-6f);
; #pragma unroll
;     for (int j = 0; j < 4; ++j) { const f32x4 ww = wr[64 * j]; const f32x4 o = v[j] * rstd * ww;
;         if (of) __builtin_nontemporal_store(o, (f32x4*)of + lane + 64 * j);
;         else { u32x2 p; p.x = pk2(o.x, o.y); p.y = pk2(o.z, o.w); ((u32x2*)orow + lane)[64 * j] = p; } }
; }
; __device__ __forceinline__ void norm_phase(const float* x, const float* w, bf16_t* xn, float* of, int gw, int ngw, int lane) {
;     asm volatile("" : "+v"(lane));
;     for (int m = gw; m < M; m += ngw) rms_row(x + (size_t)m * D, w, xn ? xn + (size_t)m * D : nullptr, of ? of + (size_t)m * D : nullptr, lane);
.LBB0_1370:
	v_readlane_b32 s12, v254, 50
	v_readlane_b32 s4, v254, 52
	v_readlane_b32 s5, v254, 53
	v_readlane_b32 s6, v254, 59
	v_readlane_b32 s10, v252, 22
	v_readlane_b32 s11, v252, 23
	v_lshlrev_b32_e32 v6, 4, v232
	s_mov_b32 s13, 0xf800000
	s_lshl_b32 s7, s6, 12
	s_nop 2
	global_load_dwordx4 v[80:83], v6, s[10:11]
	global_load_dwordx4 v[84:87], v6, s[10:11] offset:1024
	global_load_dwordx4 v[88:91], v6, s[10:11] offset:2048
	global_load_dwordx4 v[92:95], v6, s[10:11] offset:3072
	global_load_dwordx4 v[14:17], v6, s[4:5] nt
	global_load_dwordx4 v[18:21], v6, s[4:5] offset:1024 nt
	global_load_dwordx4 v[22:25], v6, s[4:5] offset:2048 nt
	global_load_dwordx4 v[26:29], v6, s[4:5] offset:3072 nt
.Lfn_loop:
	s_add_u32 s8, s4, s7
	s_addc_u32 s9, s5, 0
	s_add_i32 s12, s12, s6
	s_cmp_lt_i32 s12, 0x8000
	s_cbranch_scc0 .Lfn_lastA
	global_load_dwordx4 v[32:35], v6, s[8:9] nt
	global_load_dwordx4 v[36:39], v6, s[8:9] offset:1024 nt
	global_load_dwordx4 v[40:43], v6, s[8:9] offset:2048 nt
	global_load_dwordx4 v[44:47], v6, s[8:9] offset:3072 nt
	s_waitcnt vmcnt(4)
	v_mul_f32_e32 v48, v15, v15
	v_mul_f32_e32 v49, v17, v17
	v_fmac_f32_e32 v48, v14, v14
	v_fmac_f32_e32 v49, v16, v16
	v_add_f32_e32 v48, v48, v49
	v_mul_f32_e32 v50, v19, v19
	v_mul_f32_e32 v51, v21, v21
	v_fmac_f32_e32 v50, v18, v18
	v_fmac_f32_e32 v51, v20, v20
	v_add_f32_e32 v50, v50, v51
	v_mul_f32_e32 v52, v23, v23
	v_mul_f32_e32 v53, v25, v25
	v_fmac_f32_e32 v52, v22, v22
	v_fmac_f32_e32 v53, v24, v24
	v_add_f32_e32 v52, v52, v53
	v_mul_f32_e32 v54, v27, v27
	v_mul_f32_e32 v55, v29, v29
	v_fmac_f32_e32 v54, v26, v26
	v_fmac_f32_e32 v55, v28, v28
	v_add_f32_e32 v54, v54, v55
	v_add_f32_e32 v48, v48, v50
	v_add_f32_e32 v48, v48, v52
	v_add_f32_e32 v48, v48, v54
	s_nop 1
	v_add_f32_dpp v48, v48, v48 quad_perm:[1,0,3,2] row_mask:0xf bank_mask:0xf
	s_nop 1
	v_add_f32_dpp v48, v48, v48 quad_perm:[2,3,0,1] row_mask:0xf bank_mask:0xf
	s_nop 1
	v_add_f32_dpp v48, v48, v48 row_half_mirror row_mask:0xf bank_mask:0xf
	s_nop 1
	v_add_f32_dpp v48, v48, v48 row_mirror row_mask:0xf bank_mask:0xf
	s_nop 1
	v_add_f32_dpp v48, v48, v48 row_bcast:15 row_mask:0xa bank_mask:0xf
	s_nop 1
	v_add_f32_dpp v48, v48, v48 row_bcast:31 row_mask:0xc bank_mask:0xf
	s_nop 0
	v_readlane_b32 s16, v48, 63
	s_nop 3
	v_mov_b32_e32 v50, s16
	v_fmamk_f32 v50, v50, 0x3a800000, v225
	v_cmp_gt_f32_e32 vcc, s13, v50
	v_mul_f32_e32 v51, 0x4f800000, v50
	s_nop 0
	v_cndmask_b32_e32 v50, v50, v51, vcc
	v_sqrt_f32_e32 v51, v50
	s_nop 0
	v_add_u32_e32 v52, -1, v51
	v_fma_f32 v53, -v52, v51, v50
	v_cmp_ge_f32_e64 s[0:1], 0, v53
	v_add_u32_e32 v53, 1, v51
	s_nop 0
	v_cndmask_b32_e64 v52, v51, v52, s[0:1]
	v_fma_f32 v51, -v53, v51, v50
	v_cmp_lt_f32_e64 s[0:1], 0, v51
	s_nop 1
	v_cndmask_b32_e64 v51, v52, v53, s[0:1]
	v_mul_f32_e32 v52, 0x37800000, v51
	v_cndmask_b32_e32 v51, v51, v52, vcc
	v_mov_b32_e32 v52, 0x260
	v_cmp_class_f32_e32 vcc, v50, v52
	s_nop 1
	v_cndmask_b32_e32 v50, v51, v50, vcc
	v_div_scale_f32 v51, s[0:1], v50, v50, 1.0
	v_rcp_f32_e32 v52, v51
	s_nop 0
	v_fma_f32 v53, -v51, v52, 1.0
	v_fmac_f32_e32 v52, v53, v52
	v_div_scale_f32 v53, vcc, 1.0, v50, 1.0
	v_mul_f32_e32 v54, v53, v52
	v_fma_f32 v55, -v51, v54, v53
	v_fmac_f32_e32 v54, v55, v52
	v_fma_f32 v51, -v51, v54, v53
	v_div_fmas_f32 v51, v51, v52, v54
	v_div_fixup_f32 v56, v51, v50, 1.0
	v_mul_f32_e32 v14, v14, v56
	v_mul_f32_e32 v15, v15, v56
	v_mul_f32_e32 v16, v16, v56
	v_mul_f32_e32 v17, v17, v56
	v_mul_f32_e32 v14, v80, v14
	v_mul_f32_e32 v15, v81, v15
	v_mul_f32_e32 v16, v82, v16
	v_mul_f32_e32 v17, v83, v17
	global_store_dwordx4 v6, v[14:17], s[4:5] nt
	v_mul_f32_e32 v18, v18, v56
	v_mul_f32_e32 v19, v19, v56
	v_mul_f32_e32 v20, v20, v56
	v_mul_f32_e32 v21, v21, v56
	v_mul_f32_e32 v18, v84, v18
	v_mul_f32_e32 v19, v85, v19
	v_mul_f32_e32 v20, v86, v20
	v_mul_f32_e32 v21, v87, v21
	global_store_dwordx4 v6, v[18:21], s[4:5] offset:1024 nt
	v_mul_f32_e32 v22, v22, v56
	v_mul_f32_e32 v23, v23, v56
	v_mul_f32_e32 v24, v24, v56
	v_mul_f32_e32 v25, v25, v56
	v_mul_f32_e32 v22, v88, v22
	v_mul_f32_e32 v23, v89, v23
	v_mul_f32_e32 v24, v90, v24
	v_mul_f32_e32 v25, v91, v25
	global_store_dwordx4 v6, v[22:25], s[4:5] offset:2048 nt
	v_mul_f32_e32 v26, v26, v56
	v_mul_f32_e32 v27, v27, v56
	v_mul_f32_e32 v28, v28, v56
	v_mul_f32_e32 v29, v29, v56
	v_mul_f32_e32 v26, v92, v26
	v_mul_f32_e32 v27, v93, v27
	v_mul_f32_e32 v28, v94, v28
	v_mul_f32_e32 v29, v95, v29
	global_store_dwordx4 v6, v[26:29], s[4:5] offset:3072 nt
	s_mov_b64 s[4:5], s[8:9]
	s_add_u32 s8, s4, s7
	s_addc_u32 s9, s5, 0
	s_add_i32 s12, s12, s6
	s_cmp_lt_i32 s12, 0x8000
	s_cbranch_scc0 .Lfn_lastB
; __device__ __forceinline__ unsigned pk2(float lo, float hi) { return pg8::cvt_pk_bf16(lo, hi); }
; __device__ __forceinline__ void rms_row(const float* xrow, const float* w, bf16_t* orow, float* of, int lane) {
;     const f32x4* xr = (const f32x4*)xrow + lane; const f32x4* wr = (const f32x4*)w + lane;
;     f32x4 v[4]; float s = 0.f;
; #pragma unroll
;     for (int j = 0; j < 4; ++j) { v[j] = __builtin_nontemporal_load(xr + 64 * j); s += (v[j].x * v[j].x + v[j].y * v[j].y) + (v[j].z * v[j].z + v[j].w * v[j].w); }
;     const float rstd = 1.0f / sqrtf(wave_sum(s) * (1.f / D) + 1e-6f);
; #pragma unroll
;     for (int j = 0; j < 4; ++j) { const f32x4 ww = wr[64 * j]; const f32x4 o = v[j] * rstd * ww;
;         if (of) __builtin_nontemporal_store(o, (f32x4*)of + lane + 64 * j);
;         else { u32x2 p; p.x = pk2(o.x, o.y); p.y = pk2(o.z, o.w); ((u32x2*)orow + lane)[64 * j] = p; } }
; }
; __device__ __forceinline__ void norm_phase(const float* x, const float* w, bf16_t* xn, float* of, int gw, int ngw, int lane) {
;     asm volatile("" : "+v"(lane));
;     for (int m = gw; m < M; m += ngw) rms_row(x + (size_t)m * D, w, xn ? xn + (size_t)m * D : nullptr, of ? of + (size_t)m * D : nullptr, lane);
	global_load_dwordx4 v[14:17], v6, s[8:9] nt
	global_load_dwordx4 v[18:21], v6, s[8:9] offset:1024 nt
	global_load_dwordx4 v[22:25], v6, s[8:9] offset:2048 nt
	global_load_dwordx4 v[26:29], v6, s[8:9] offset:3072 nt
	s_waitcnt vmcnt(4)
	v_mul_f32_e32 v48, v33, v33
	v_mul_f32_e32 v49, v35, v35
	v_fmac_f32_e32 v48, v32, v32
	v_fmac_f32_e32 v49, v34, v34
	v_add_f32_e32 v48, v48, v49
	v_mul_f32_e32 v50, v37, v37
	v_mul_f32_e32 v51, v39, v39
	v_fmac_f32_e32 v50, v36, v36
	v_fmac_f32_e32 v51, v38, v38
	v_add_f32_e32 v50, v50, v51
	v_mul_f32_e32 v52, v41, v41
	v_mul_f32_e32 v53, v43, v43
	v_fmac_f32_e32 v52, v40, v40
	v_fmac_f32_e32 v53, v42, v42
	v_add_f32_e32 v52, v52, v53
	v_mul_f32_e32 v54, v45, v45
	v_mul_f32_e32 v55, v47, v47
	v_fmac_f32_e32 v54, v44, v44
	v_fmac_f32_e32 v55, v46, v46
	v_add_f32_e32 v54, v54, v55
	v_add_f32_e32 v48, v48, v50
	v_add_f32_e32 v48, v48, v52
	v_add_f32_e32 v48, v48, v54
	s_nop 1
	v_add_f32_dpp v48, v48, v48 quad_perm:[1,0,3,2] row_mask:0xf bank_mask:0xf
	s_nop 1
	v_add_f32_dpp v48, v48, v48 quad_perm:[2,3,0,1] row_mask:0xf bank_mask:0xf
	s_nop 1
	v_add_f32_dpp v48, v48, v48 row_half_mirror row_mask:0xf bank_mask:0xf
	s_nop 1
	v_add_f32_dpp v48, v48, v48 row_mirror row_mask:0xf bank_mask:0xf
	s_nop 1
	v_add_f32_dpp v48, v48, v48 row_bcast:15 row_mask:0xa bank_mask:0xf
	s_nop 1
	v_add_f32_dpp v48, v48, v48 row_bcast:31 row_mask:0xc bank_mask:0xf
	s_nop 0
	v_readlane_b32 s16, v48, 63
	s_nop 3
	v_mov_b32_e32 v50, s16
	v_fmamk_f32 v50, v50, 0x3a800000, v225
	v_cmp_gt_f32_e32 vcc, s13, v50
	v_mul_f32_e32 v51, 0x4f800000, v50
	s_nop 0
	v_cndmask_b32_e32 v50, v50, v51, vcc
	v_sqrt_f32_e32 v51, v50
	s_nop 0
	v_add_u32_e32 v52, -1, v51
	v_fma_f32 v53, -v52, v51, v50
	v_cmp_ge_f32_e64 s[0:1], 0, v53
	v_add_u32_e32 v53, 1, v51
	s_nop 0
	v_cndmask_b32_e64 v52, v51, v52, s[0:1]
	v_fma_f32 v51, -v53, v51, v50
	v_cmp_lt_f32_e64 s[0:1], 0, v51
	s_nop 1
	v_cndmask_b32_e64 v51, v52, v53, s[0:1]
	v_mul_f32_e32 v52, 0x37800000, v51
	v_cndmask_b32_e32 v51, v51, v52, vcc
	v_mov_b32_e32 v52, 0x260
	v_cmp_class_f32_e32 vcc, v50, v52
	s_nop 1
	v_cndmask_b32_e32 v50, v51, v50, vcc
	v_div_scale_f32 v51, s[0:1], v50, v50, 1.0
	v_rcp_f32_e32 v52, v51
	s_nop 0
	v_fma_f32 v53, -v51, v52, 1.0
	v_fmac_f32_e32 v52, v53, v52
	v_div_scale_f32 v53, vcc, 1.0, v50, 1.0
	v_mul_f32_e32 v54, v53, v52
	v_fma_f32 v55, -v51, v54, v53
	v_fmac_f32_e32 v54, v55, v52
	v_fma_f32 v51, -v51, v54, v53
	v_div_fmas_f32 v51, v51, v52, v54
	v_div_fixup_f32 v56, v51, v50, 1.0
	v_mul_f32_e32 v32, v32, v56
	v_mul_f32_e32 v33, v33, v56
	v_mul_f32_e32 v34, v34, v56
	v_mul_f32_e32 v35, v35, v56
	v_mul_f32_e32 v32, v80, v32
	v_mul_f32_e32 v33, v81, v33
	v_mul_f32_e32 v34, v82, v34
	v_mul_f32_e32 v35, v83, v35
	global_store_dwordx4 v6, v[32:35], s[4:5] nt
	v_mul_f32_e32 v36, v36, v56
	v_mul_f32_e32 v37, v37, v56
	v_mul_f32_e32 v38, v38, v56
	v_mul_f32_e32 v39, v39, v56
	v_mul_f32_e32 v36, v84, v36
	v_mul_f32_e32 v37, v85, v37
	v_mul_f32_e32 v38, v86, v38
	v_mul_f32_e32 v39, v87, v39
	global_store_dwordx4 v6, v[36:39], s[4:5] offset:1024 nt
	v_mul_f32_e32 v40, v40, v56
	v_mul_f32_e32 v41, v41, v56
	v_mul_f32_e32 v42, v42, v56
	v_mul_f32_e32 v43, v43, v56
	v_mul_f32_e32 v40, v88, v40
	v_mul_f32_e32 v41, v89, v41
	v_mul_f32_e32 v42, v90, v42
	v_mul_f32_e32 v43, v91, v43
	global_store_dwordx4 v6, v[40:43], s[4:5] offset:2048 nt
	v_mul_f32_e32 v44, v44, v56
	v_mul_f32_e32 v45, v45, v56
	v_mul_f32_e32 v46, v46, v56
	v_mul_f32_e32 v47, v47, v56
	v_mul_f32_e32 v44, v92, v44
	v_mul_f32_e32 v45, v93, v45
	v_mul_f32_e32 v46, v94, v46
	v_mul_f32_e32 v47, v95, v47
	global_store_dwordx4 v6, v[44:47], s[4:5] offset:3072 nt
	s_mov_b64 s[4:5], s[8:9]
	s_branch .Lfn_loop
.Lfn_lastA:
	s_waitcnt vmcnt(0)
	v_mul_f32_e32 v48, v15, v15
	v_mul_f32_e32 v49, v17, v17
	v_fmac_f32_e32 v48, v14, v14
	v_fmac_f32_e32 v49, v16, v16
	v_add_f32_e32 v48, v48, v49
	v_mul_f32_e32 v50, v19, v19
	v_mul_f32_e32 v51, v21, v21
	v_fmac_f32_e32 v50, v18, v18
	v_fmac_f32_e32 v51, v20, v20
	v_add_f32_e32 v50, v50, v51
	v_mul_f32_e32 v52, v23, v23
	v_mul_f32_e32 v53, v25, v25
	v_fmac_f32_e32 v52, v22, v22
	v_fmac_f32_e32 v53, v24, v24
	v_add_f32_e32 v52, v52, v53
	v_mul_f32_e32 v54, v27, v27
	v_mul_f32_e32 v55, v29, v29
	v_fmac_f32_e32 v54, v26, v26
	v_fmac_f32_e32 v55, v28, v28
	v_add_f32_e32 v54, v54, v55
	v_add_f32_e32 v48, v48, v50
	v_add_f32_e32 v48, v48, v52
	v_add_f32_e32 v48, v48, v54
	s_nop 1
	v_add_f32_dpp v48, v48, v48 quad_perm:[1,0,3,2] row_mask:0xf bank_mask:0xf
	s_nop 1
	v_add_f32_dpp v48, v48, v48 quad_perm:[2,3,0,1] row_mask:0xf bank_mask:0xf
	s_nop 1
	v_add_f32_dpp v48, v48, v48 row_half_mirror row_mask:0xf bank_mask:0xf
	s_nop 1
	v_add_f32_dpp v48, v48, v48 row_mirror row_mask:0xf bank_mask:0xf
	s_nop 1
	v_add_f32_dpp v48, v48, v48 row_bcast:15 row_mask:0xa bank_mask:0xf
	s_nop 1
	v_add_f32_dpp v48, v48, v48 row_bcast:31 row_mask:0xc bank_mask:0xf
	s_nop 0
	v_readlane_b32 s16, v48, 63
	s_nop 3
	v_mov_b32_e32 v50, s16
	v_fmamk_f32 v50, v50, 0x3a800000, v225
	v_cmp_gt_f32_e32 vcc, s13, v50
	v_mul_f32_e32 v51, 0x4f800000, v50
	s_nop 0
	v_cndmask_b32_e32 v50, v50, v51, vcc
	v_sqrt_f32_e32 v51, v50
	s_nop 0
	v_add_u32_e32 v52, -1, v51
	v_fma_f32 v53, -v52, v51, v50
	v_cmp_ge_f32_e64 s[0:1], 0, v53
	v_add_u32_e32 v53, 1, v51
	s_nop 0
	v_cndmask_b32_e64 v52, v51, v52, s[0:1]
	v_fma_f32 v51, -v53, v51, v50
	v_cmp_lt_f32_e64 s[0:1], 0, v51
	s_nop 1
	v_cndmask_b32_e64 v51, v52, v53, s[0:1]
; __device__ __forceinline__ unsigned pk2(float lo, float hi) { return pg8::cvt_pk_bf16(lo, hi); }
; __device__ __forceinline__ void rms_row(const float* xrow, const float* w, bf16_t* orow, float* of, int lane) {
;     const f32x4* xr = (const f32x4*)xrow + lane; const f32x4* wr = (const f32x4*)w + lane;
;     f32x4 v[4]; float s = 0.f;
; #pragma unroll
;     for (int j = 0; j < 4; ++j) { v[j] = __builtin_nontemporal_load(xr + 64 * j); s += (v[j].x * v[j].x + v[j].y * v[j].y) + (v[j].z * v[j].z + v[j].w * v[j].w); }
;     const float rstd = 1.0f / sqrtf(wave_sum(s) * (1.f / D) + 1e-6f);
; #pragma unroll
;     for (int j = 0; j < 4; ++j) { const f32x4 ww = wr[64 * j]; const f32x4 o = v[j] * rstd * ww;
;         if (of) __builtin_nontemporal_store(o, (f32x4*)of + lane + 64 * j);
;         else { u32x2 p; p.x = pk2(o.x, o.y); p.y = pk2(o.z, o.w); ((u32x2*)orow + lane)[64 * j] = p; } }
; }
; __device__ __forceinline__ void norm_phase(const float* x, const float* w, bf16_t* xn, float* of, int gw, int ngw, int lane) {
;     asm volatile("" : "+v"(lane));
;     for (int m = gw; m < M; m += ngw) rms_row(x + (size_t)m * D, w, xn ? xn + (size_t)m * D : nullptr, of ? of + (size_t)m * D : nullptr, lane);
	v_mul_f32_e32 v52, 0x37800000, v51
	v_cndmask_b32_e32 v51, v51, v52, vcc
	v_mov_b32_e32 v52, 0x260
	v_cmp_class_f32_e32 vcc, v50, v52
	s_nop 1
	v_cndmask_b32_e32 v50, v51, v50, vcc
	v_div_scale_f32 v51, s[0:1], v50, v50, 1.0
	v_rcp_f32_e32 v52, v51
	s_nop 0
	v_fma_f32 v53, -v51, v52, 1.0
	v_fmac_f32_e32 v52, v53, v52
	v_div_scale_f32 v53, vcc, 1.0, v50, 1.0
	v_mul_f32_e32 v54, v53, v52
	v_fma_f32 v55, -v51, v54, v53
	v_fmac_f32_e32 v54, v55, v52
	v_fma_f32 v51, -v51, v54, v53
	v_div_fmas_f32 v51, v51, v52, v54
	v_div_fixup_f32 v56, v51, v50, 1.0
	v_mul_f32_e32 v14, v14, v56
	v_mul_f32_e32 v15, v15, v56
	v_mul_f32_e32 v16, v16, v56
	v_mul_f32_e32 v17, v17, v56
	v_mul_f32_e32 v14, v80, v14
	v_mul_f32_e32 v15, v81, v15
	v_mul_f32_e32 v16, v82, v16
	v_mul_f32_e32 v17, v83, v17
	global_store_dwordx4 v6, v[14:17], s[4:5] nt
	v_mul_f32_e32 v18, v18, v56
	v_mul_f32_e32 v19, v19, v56
	v_mul_f32_e32 v20, v20, v56
	v_mul_f32_e32 v21, v21, v56
	v_mul_f32_e32 v18, v84, v18
	v_mul_f32_e32 v19, v85, v19
	v_mul_f32_e32 v20, v86, v20
	v_mul_f32_e32 v21, v87, v21
	global_store_dwordx4 v6, v[18:21], s[4:5] offset:1024 nt
	v_mul_f32_e32 v22, v22, v56
	v_mul_f32_e32 v23, v23, v56
	v_mul_f32_e32 v24, v24, v56
	v_mul_f32_e32 v25, v25, v56
	v_mul_f32_e32 v22, v88, v22
	v_mul_f32_e32 v23, v89, v23
	v_mul_f32_e32 v24, v90, v24
	v_mul_f32_e32 v25, v91, v25
	global_store_dwordx4 v6, v[22:25], s[4:5] offset:2048 nt
	v_mul_f32_e32 v26, v26, v56
	v_mul_f32_e32 v27, v27, v56
	v_mul_f32_e32 v28, v28, v56
	v_mul_f32_e32 v29, v29, v56
	v_mul_f32_e32 v26, v92, v26
	v_mul_f32_e32 v27, v93, v27
	v_mul_f32_e32 v28, v94, v28
	v_mul_f32_e32 v29, v95, v29
	global_store_dwordx4 v6, v[26:29], s[4:5] offset:3072 nt
	s_mov_b64 s[4:5], s[8:9]
	s_branch .Lfn_exit
.Lfn_lastB:
	s_waitcnt vmcnt(0)
	v_mul_f32_e32 v48, v33, v33
	v_mul_f32_e32 v49, v35, v35
	v_fmac_f32_e32 v48, v32, v32
	v_fmac_f32_e32 v49, v34, v34
	v_add_f32_e32 v48, v48, v49
	v_mul_f32_e32 v50, v37, v37
	v_mul_f32_e32 v51, v39, v39
	v_fmac_f32_e32 v50, v36, v36
	v_fmac_f32_e32 v51, v38, v38
	v_add_f32_e32 v50, v50, v51
	v_mul_f32_e32 v52, v41, v41
	v_mul_f32_e32 v53, v43, v43
	v_fmac_f32_e32 v52, v40, v40
	v_fmac_f32_e32 v53, v42, v42
	v_add_f32_e32 v52, v52, v53
	v_mul_f32_e32 v54, v45, v45
	v_mul_f32_e32 v55, v47, v47
	v_fmac_f32_e32 v54, v44, v44
	v_fmac_f32_e32 v55, v46, v46
	v_add_f32_e32 v54, v54, v55
	v_add_f32_e32 v48, v48, v50
	v_add_f32_e32 v48, v48, v52
	v_add_f32_e32 v48, v48, v54
	s_nop 1
	v_add_f32_dpp v48, v48, v48 quad_perm:[1,0,3,2] row_mask:0xf bank_mask:0xf
	s_nop 1
	v_add_f32_dpp v48, v48, v48 quad_perm:[2,3,0,1] row_mask:0xf bank_mask:0xf
	s_nop 1
	v_add_f32_dpp v48, v48, v48 row_half_mirror row_mask:0xf bank_mask:0xf
	s_nop 1
	v_add_f32_dpp v48, v48, v48 row_mirror row_mask:0xf bank_mask:0xf
	s_nop 1
	v_add_f32_dpp v48, v48, v48 row_bcast:15 row_mask:0xa bank_mask:0xf
	s_nop 1
	v_add_f32_dpp v48, v48, v48 row_bcast:31 row_mask:0xc bank_mask:0xf
	s_nop 0
	v_readlane_b32 s16, v48, 63
	s_nop 3
	v_mov_b32_e32 v50, s16
	v_fmamk_f32 v50, v50, 0x3a800000, v225
	v_cmp_gt_f32_e32 vcc, s13, v50
	v_mul_f32_e32 v51, 0x4f800000, v50
	s_nop 0
	v_cndmask_b32_e32 v50, v50, v51, vcc
	v_sqrt_f32_e32 v51, v50
	s_nop 0
	v_add_u32_e32 v52, -1, v51
	v_fma_f32 v53, -v52, v51, v50
	v_cmp_ge_f32_e64 s[0:1], 0, v53
	v_add_u32_e32 v53, 1, v51
	s_nop 0
	v_cndmask_b32_e64 v52, v51, v52, s[0:1]
	v_fma_f32 v51, -v53, v51, v50
	v_cmp_lt_f32_e64 s[0:1], 0, v51
	s_nop 1
	v_cndmask_b32_e64 v51, v52, v53, s[0:1]
	v_mul_f32_e32 v52, 0x37800000, v51
	v_cndmask_b32_e32 v51, v51, v52, vcc
	v_mov_b32_e32 v52, 0x260
	v_cmp_class_f32_e32 vcc, v50, v52
	s_nop 1
	v_cndmask_b32_e32 v50, v51, v50, vcc
	v_div_scale_f32 v51, s[0:1], v50, v50, 1.0
	v_rcp_f32_e32 v52, v51
	s_nop 0
	v_fma_f32 v53, -v51, v52, 1.0
	v_fmac_f32_e32 v52, v53, v52
	v_div_scale_f32 v53, vcc, 1.0, v50, 1.0
	v_mul_f32_e32 v54, v53, v52
	v_fma_f32 v55, -v51, v54, v53
	v_fmac_f32_e32 v54, v55, v52
	v_fma_f32 v51, -v51, v54, v53
	v_div_fmas_f32 v51, v51, v52, v54
	v_div_fixup_f32 v56, v51, v50, 1.0
	v_mul_f32_e32 v32, v32, v56
	v_mul_f32_e32 v33, v33, v56
	v_mul_f32_e32 v34, v34, v56
	v_mul_f32_e32 v35, v35, v56
	v_mul_f32_e32 v32, v80, v32
	v_mul_f32_e32 v33, v81, v33
	v_mul_f32_e32 v34, v82, v34
	v_mul_f32_e32 v35, v83, v35
	global_store_dwordx4 v6, v[32:35], s[4:5] nt
	v_mul_f32_e32 v36, v36, v56
	v_mul_f32_e32 v37, v37, v56
	v_mul_f32_e32 v38, v38, v56
	v_mul_f32_e32 v39, v39, v56
	v_mul_f32_e32 v36, v84, v36
	v_mul_f32_e32 v37, v85, v37
	v_mul_f32_e32 v38, v86, v38
	v_mul_f32_e32 v39, v87, v39
	global_store_dwordx4 v6, v[36:39], s[4:5] offset:1024 nt
	v_mul_f32_e32 v40, v40, v56
	v_mul_f32_e32 v41, v41, v56
	v_mul_f32_e32 v42, v42, v56
	v_mul_f32_e32 v43, v43, v56
	v_mul_f32_e32 v40, v88, v40
	v_mul_f32_e32 v41, v89, v41
	v_mul_f32_e32 v42, v90, v42
	v_mul_f32_e32 v43, v91, v43
	global_store_dwordx4 v6, v[40:43], s[4:5] offset:2048 nt
	v_mul_f32_e32 v44, v44, v56
	v_mul_f32_e32 v45, v45, v56
	v_mul_f32_e32 v46, v46, v56
	v_mul_f32_e32 v47, v47, v56
	v_mul_f32_e32 v44, v92, v44
	v_mul_f32_e32 v45, v93, v45
	v_mul_f32_e32 v46, v94, v46
	v_mul_f32_e32 v47, v95, v47
	global_store_dwordx4 v6, v[44:47], s[4:5] offset:3072 nt
	s_mov_b64 s[4:5], s[8:9]
.Lfn_exit:
	s_getpc_b64 s[98:99]
.Lpost_getpc3:
	s_add_u32 s98, s98, (.LBB0_118-.Lpost_getpc3)&4294967295
	s_addc_u32 s99, s99, (.LBB0_118-.Lpost_getpc3)>>32
	s_setpc_b64 s[98:99]
.LBB0_1388:
	s_endpgm
